# GEMM K-loops: 17 more LDS-DMA stages (offset pairs whose high half is the zero register) use the SGPR-base form
# speedup vs baseline: 1.0076x; 1.0022x over previous
.LBB0_641:
	s_add_u32 s24, s22, 0x100
	s_addc_u32 s25, s23, 0
	s_add_i32 s50, 0, 0x10000
	v_add_u32_e32 v145, s50, v143
	ds_read_b128 v[146:149], v145
	ds_read_b128 v[150:153], v145 offset:1024
	ds_read_b128 v[154:157], v145 offset:2048
	ds_read_b128 v[158:161], v145 offset:3072
	s_cmp_eq_u32 s49, 4
	s_cselect_b32 s29, s19, s25
	s_cselect_b32 s28, s18, s24
	s_cselect_b32 s27, s21, s48
	s_cselect_b32 s26, s20, s5
	v_lshl_add_u64 v[198:199], s[22:23], 0, v[138:139]
	s_add_i32 m0, s38, 0xc000
	ds_read_b128 v[162:165], v144
	ds_read_b128 v[166:169], v144 offset:1024
	ds_read_b128 v[170:173], v144 offset:2048
	ds_read_b128 v[174:177], v144 offset:3072
	ds_read_b128 v[178:181], v144 offset:4096
	ds_read_b128 v[182:185], v144 offset:5120
	ds_read_b128 v[186:189], v144 offset:6144
	ds_read_b128 v[190:193], v144 offset:7168
	global_load_lds_dwordx4 v[198:199], off
	v_lshl_add_u64 v[198:199], s[22:23], 0, v[140:141]
	s_add_i32 m0, s38, 0xe000
	s_nop 0
	global_load_lds_dwordx4 v[198:199], off
	s_waitcnt lgkmcnt(8)
	s_barrier
	s_waitcnt lgkmcnt(0)
	s_setprio 1
	s_waitcnt lgkmcnt(0)
	v_mfma_f32_16x16x32_bf16 v[126:129], v[146:149], v[162:165], v[126:129]
	v_mfma_f32_16x16x32_bf16 v[122:125], v[154:157], v[162:165], v[122:125]
	v_mfma_f32_16x16x32_bf16 v[118:121], v[146:149], v[170:173], v[118:121]
	v_mfma_f32_16x16x32_bf16 v[114:117], v[154:157], v[170:173], v[114:117]
	v_mfma_f32_16x16x32_bf16 v[106:109], v[146:149], v[178:181], v[106:109]
	v_mfma_f32_16x16x32_bf16 v[98:101], v[154:157], v[178:181], v[98:101]
	v_mfma_f32_16x16x32_bf16 v[90:93], v[146:149], v[186:189], v[90:93]
	v_mfma_f32_16x16x32_bf16 v[82:85], v[154:157], v[186:189], v[82:85]
	v_mfma_f32_16x16x32_bf16 v[126:129], v[150:153], v[166:169], v[126:129]
	v_mfma_f32_16x16x32_bf16 v[122:125], v[158:161], v[166:169], v[122:125]
	v_mfma_f32_16x16x32_bf16 v[118:121], v[150:153], v[174:177], v[118:121]
	v_mfma_f32_16x16x32_bf16 v[114:117], v[158:161], v[174:177], v[114:117]
	v_mfma_f32_16x16x32_bf16 v[106:109], v[150:153], v[182:185], v[106:109]
	v_mfma_f32_16x16x32_bf16 v[98:101], v[158:161], v[182:185], v[98:101]
	v_mfma_f32_16x16x32_bf16 v[90:93], v[150:153], v[190:193], v[90:93]
	v_mfma_f32_16x16x32_bf16 v[82:85], v[158:161], v[190:193], v[82:85]
	s_setprio 0
	s_barrier
	s_add_i32 s51, 0, 0x14000
	s_add_i32 s22, s50, s37
	v_add_u32_e32 v145, s51, v143
	v_lshl_add_u64 v[214:215], s[26:27], 0, v[48:49]
	s_mov_b32 m0, s22
	ds_read_b128 v[198:201], v145
	ds_read_b128 v[202:205], v145 offset:1024
	ds_read_b128 v[206:209], v145 offset:2048
	ds_read_b128 v[210:213], v145 offset:3072
	global_load_lds_dwordx4 v[214:215], off
	v_lshl_add_u64 v[216:217], s[26:27], 0, v[130:131]
	s_add_i32 m0, s22, 0x2000
	s_nop 0
	global_load_lds_dwordx4 v[216:217], off
	s_barrier
	s_waitcnt lgkmcnt(0)
	s_setprio 1
	s_waitcnt lgkmcnt(0)
	v_mfma_f32_16x16x32_bf16 v[110:113], v[198:201], v[162:165], v[110:113]
	v_mfma_f32_16x16x32_bf16 v[102:105], v[206:209], v[162:165], v[102:105]
	v_mfma_f32_16x16x32_bf16 v[94:97], v[198:201], v[170:173], v[94:97]
	v_mfma_f32_16x16x32_bf16 v[86:89], v[206:209], v[170:173], v[86:89]
	v_mfma_f32_16x16x32_bf16 v[78:81], v[198:201], v[178:181], v[78:81]
	v_mfma_f32_16x16x32_bf16 v[74:77], v[206:209], v[178:181], v[74:77]
	v_mfma_f32_16x16x32_bf16 v[70:73], v[198:201], v[186:189], v[70:73]
	v_mfma_f32_16x16x32_bf16 v[66:69], v[206:209], v[186:189], v[66:69]
	v_mfma_f32_16x16x32_bf16 v[110:113], v[202:205], v[166:169], v[110:113]
	v_mfma_f32_16x16x32_bf16 v[102:105], v[210:213], v[166:169], v[102:105]
	v_mfma_f32_16x16x32_bf16 v[94:97], v[202:205], v[174:177], v[94:97]
	v_mfma_f32_16x16x32_bf16 v[86:89], v[210:213], v[174:177], v[86:89]
	v_mfma_f32_16x16x32_bf16 v[78:81], v[202:205], v[182:185], v[78:81]
	v_mfma_f32_16x16x32_bf16 v[74:77], v[210:213], v[182:185], v[74:77]
	v_mfma_f32_16x16x32_bf16 v[70:73], v[202:205], v[190:193], v[70:73]
	v_mfma_f32_16x16x32_bf16 v[66:69], v[210:213], v[190:193], v[66:69]
	s_setprio 0
	s_mov_b32 m0, s38
	v_lshl_add_u64 v[218:219], s[28:29], 0, v[134:135]
	s_barrier
	ds_read_b128 v[162:165], v144 offset:16384
	ds_read_b128 v[166:169], v144 offset:17408
	ds_read_b128 v[170:173], v144 offset:18432
	ds_read_b128 v[174:177], v144 offset:19456
	ds_read_b128 v[178:181], v144 offset:20480
	ds_read_b128 v[182:185], v144 offset:21504
	ds_read_b128 v[186:189], v144 offset:22528
	ds_read_b128 v[190:193], v144 offset:23552
	global_load_lds_dwordx4 v[218:219], off
	v_lshl_add_u64 v[220:221], s[28:29], 0, v[132:133]
	s_mov_b32 m0, s39
	s_nop 0
	global_load_lds_dwordx4 v[220:221], off
	s_barrier
	s_waitcnt lgkmcnt(0)
	s_setprio 1
	s_waitcnt lgkmcnt(0)
	v_mfma_f32_16x16x32_bf16 v[62:65], v[146:149], v[162:165], v[62:65]
	v_mfma_f32_16x16x32_bf16 v[58:61], v[154:157], v[162:165], v[58:61]
	v_mfma_f32_16x16x32_bf16 v[54:57], v[146:149], v[170:173], v[54:57]
	v_mfma_f32_16x16x32_bf16 v[50:53], v[154:157], v[170:173], v[50:53]
	v_mfma_f32_16x16x32_bf16 v[36:39], v[146:149], v[178:181], v[36:39]
	v_mfma_f32_16x16x32_bf16 v[32:35], v[154:157], v[178:181], v[32:35]
	v_mfma_f32_16x16x32_bf16 v[20:23], v[146:149], v[186:189], v[20:23]
	v_mfma_f32_16x16x32_bf16 v[16:19], v[154:157], v[186:189], v[16:19]
	v_mfma_f32_16x16x32_bf16 v[62:65], v[150:153], v[166:169], v[62:65]
	v_mfma_f32_16x16x32_bf16 v[58:61], v[158:161], v[166:169], v[58:61]
	v_mfma_f32_16x16x32_bf16 v[54:57], v[150:153], v[174:177], v[54:57]
	v_mfma_f32_16x16x32_bf16 v[50:53], v[158:161], v[174:177], v[50:53]
	v_mfma_f32_16x16x32_bf16 v[36:39], v[150:153], v[182:185], v[36:39]
	v_mfma_f32_16x16x32_bf16 v[32:35], v[158:161], v[182:185], v[32:35]
	v_mfma_f32_16x16x32_bf16 v[20:23], v[150:153], v[190:193], v[20:23]
	v_mfma_f32_16x16x32_bf16 v[16:19], v[158:161], v[190:193], v[16:19]
	s_setprio 0
	s_barrier
	s_add_u32 s22, s26, 0x20000
	s_addc_u32 s23, s27, 0
	s_add_i32 s50, s51, s37
	s_mov_b32 m0, s50
	s_nop 0
	global_load_lds_dwordx4 v48, s[22:23]
	s_add_i32 m0, s50, 0x2000
	s_nop 0
	global_load_lds_dwordx4 v130, s[22:23]
	s_waitcnt vmcnt(6)
	s_barrier
	s_setprio 1
	v_mfma_f32_16x16x32_bf16 v[44:47], v[198:201], v[162:165], v[44:47]
	v_mfma_f32_16x16x32_bf16 v[40:43], v[206:209], v[162:165], v[40:43]
	v_mfma_f32_16x16x32_bf16 v[28:31], v[198:201], v[170:173], v[28:31]
	v_mfma_f32_16x16x32_bf16 v[24:27], v[206:209], v[170:173], v[24:27]
	v_mfma_f32_16x16x32_bf16 v[12:15], v[198:201], v[178:181], v[12:15]
	v_mfma_f32_16x16x32_bf16 v[8:11], v[206:209], v[178:181], v[8:11]
	v_mfma_f32_16x16x32_bf16 v[4:7], v[198:201], v[186:189], v[4:7]
	v_mfma_f32_16x16x32_bf16 v[0:3], v[206:209], v[186:189], v[0:3]
	v_mfma_f32_16x16x32_bf16 v[44:47], v[202:205], v[166:169], v[44:47]
	v_mfma_f32_16x16x32_bf16 v[40:43], v[210:213], v[166:169], v[40:43]
	v_mfma_f32_16x16x32_bf16 v[28:31], v[202:205], v[174:177], v[28:31]
	v_mfma_f32_16x16x32_bf16 v[24:27], v[210:213], v[174:177], v[24:27]
	v_mfma_f32_16x16x32_bf16 v[12:15], v[202:205], v[182:185], v[12:15]
	v_mfma_f32_16x16x32_bf16 v[8:11], v[210:213], v[182:185], v[8:11]
	v_mfma_f32_16x16x32_bf16 v[4:7], v[202:205], v[190:193], v[4:7]
	v_mfma_f32_16x16x32_bf16 v[0:3], v[210:213], v[190:193], v[0:3]
	s_setprio 0
	s_add_i32 s50, 0, 0x18000
	v_add_u32_e32 v145, s50, v143
	s_barrier
	ds_read_b128 v[146:149], v145
	ds_read_b128 v[150:153], v145 offset:1024
	ds_read_b128 v[154:157], v145 offset:2048
	ds_read_b128 v[158:161], v145 offset:3072
	s_add_u32 s22, s28, 0x30000
	s_addc_u32 s23, s29, 0
	s_mov_b32 m0, s40
	ds_read_b128 v[162:165], v144 offset:32768
	ds_read_b128 v[166:169], v144 offset:33792
	ds_read_b128 v[170:173], v144 offset:34816
	ds_read_b128 v[174:177], v144 offset:35840
	ds_read_b128 v[178:181], v144 offset:36864
	ds_read_b128 v[182:185], v144 offset:37888
	ds_read_b128 v[186:189], v144 offset:38912
	ds_read_b128 v[190:193], v144 offset:39936
	global_load_lds_dwordx4 v134, s[22:23]
	s_mov_b32 m0, s41
	s_nop 0
	global_load_lds_dwordx4 v132, s[22:23]
	s_waitcnt lgkmcnt(8)
	s_barrier
	s_waitcnt lgkmcnt(0)
	s_setprio 1
	s_waitcnt lgkmcnt(0)
	v_mfma_f32_16x16x32_bf16 v[126:129], v[146:149], v[162:165], v[126:129]
	v_mfma_f32_16x16x32_bf16 v[122:125], v[154:157], v[162:165], v[122:125]
	v_mfma_f32_16x16x32_bf16 v[118:121], v[146:149], v[170:173], v[118:121]
	v_mfma_f32_16x16x32_bf16 v[114:117], v[154:157], v[170:173], v[114:117]
	v_mfma_f32_16x16x32_bf16 v[106:109], v[146:149], v[178:181], v[106:109]
	v_mfma_f32_16x16x32_bf16 v[98:101], v[154:157], v[178:181], v[98:101]
	v_mfma_f32_16x16x32_bf16 v[90:93], v[146:149], v[186:189], v[90:93]
	v_mfma_f32_16x16x32_bf16 v[82:85], v[154:157], v[186:189], v[82:85]
	v_mfma_f32_16x16x32_bf16 v[126:129], v[150:153], v[166:169], v[126:129]
	v_mfma_f32_16x16x32_bf16 v[122:125], v[158:161], v[166:169], v[122:125]
	v_mfma_f32_16x16x32_bf16 v[118:121], v[150:153], v[174:177], v[118:121]
	v_mfma_f32_16x16x32_bf16 v[114:117], v[158:161], v[174:177], v[114:117]
	v_mfma_f32_16x16x32_bf16 v[106:109], v[150:153], v[182:185], v[106:109]
	v_mfma_f32_16x16x32_bf16 v[98:101], v[158:161], v[182:185], v[98:101]
	v_mfma_f32_16x16x32_bf16 v[90:93], v[150:153], v[190:193], v[90:93]
	v_mfma_f32_16x16x32_bf16 v[82:85], v[158:161], v[190:193], v[82:85]
	s_setprio 0
	s_barrier
	s_add_i32 s28, 0, 0x1c000
	s_add_i32 s22, s50, s37
	v_add_u32_e32 v145, s28, v143
	v_lshl_add_u64 v[214:215], v[214:215], 0, s[66:67]
	s_mov_b32 m0, s22
	ds_read_b128 v[198:201], v145
	ds_read_b128 v[202:205], v145 offset:1024
	ds_read_b128 v[206:209], v145 offset:2048
	ds_read_b128 v[210:213], v145 offset:3072
	global_load_lds_dwordx4 v[214:215], off
	v_lshl_add_u64 v[214:215], v[216:217], 0, s[66:67]
	s_add_i32 m0, s22, 0x2000
	s_nop 0
	global_load_lds_dwordx4 v[214:215], off
	s_barrier
	s_waitcnt lgkmcnt(0)
	s_setprio 1
	s_waitcnt lgkmcnt(0)
	v_mfma_f32_16x16x32_bf16 v[110:113], v[198:201], v[162:165], v[110:113]
	v_mfma_f32_16x16x32_bf16 v[102:105], v[206:209], v[162:165], v[102:105]
	v_mfma_f32_16x16x32_bf16 v[94:97], v[198:201], v[170:173], v[94:97]
	v_mfma_f32_16x16x32_bf16 v[86:89], v[206:209], v[170:173], v[86:89]
	v_mfma_f32_16x16x32_bf16 v[78:81], v[198:201], v[178:181], v[78:81]
	v_mfma_f32_16x16x32_bf16 v[74:77], v[206:209], v[178:181], v[74:77]
	v_mfma_f32_16x16x32_bf16 v[70:73], v[198:201], v[186:189], v[70:73]
	v_mfma_f32_16x16x32_bf16 v[66:69], v[206:209], v[186:189], v[66:69]
	v_mfma_f32_16x16x32_bf16 v[110:113], v[202:205], v[166:169], v[110:113]
	v_mfma_f32_16x16x32_bf16 v[102:105], v[210:213], v[166:169], v[102:105]
	v_mfma_f32_16x16x32_bf16 v[94:97], v[202:205], v[174:177], v[94:97]
	v_mfma_f32_16x16x32_bf16 v[86:89], v[210:213], v[174:177], v[86:89]
	v_mfma_f32_16x16x32_bf16 v[78:81], v[202:205], v[182:185], v[78:81]
	v_mfma_f32_16x16x32_bf16 v[74:77], v[210:213], v[182:185], v[74:77]
	v_mfma_f32_16x16x32_bf16 v[70:73], v[202:205], v[190:193], v[70:73]
	v_mfma_f32_16x16x32_bf16 v[66:69], v[210:213], v[190:193], v[66:69]
	s_setprio 0
	s_mov_b32 m0, s42
	v_lshl_add_u64 v[214:215], v[218:219], 0, s[66:67]
	s_barrier
	ds_read_b128 v[162:165], v144 offset:49152
	ds_read_b128 v[166:169], v144 offset:50176
	ds_read_b128 v[170:173], v144 offset:51200
	ds_read_b128 v[174:177], v144 offset:52224
	ds_read_b128 v[178:181], v144 offset:53248
	ds_read_b128 v[182:185], v144 offset:54272
	ds_read_b128 v[186:189], v144 offset:55296
	ds_read_b128 v[190:193], v144 offset:56320
	global_load_lds_dwordx4 v[214:215], off
	v_lshl_add_u64 v[214:215], v[220:221], 0, s[66:67]
	s_mov_b32 m0, s43
	s_nop 0
	global_load_lds_dwordx4 v[214:215], off
	s_barrier
	s_waitcnt lgkmcnt(0)
	s_setprio 1
	s_waitcnt lgkmcnt(0)
	v_mfma_f32_16x16x32_bf16 v[62:65], v[146:149], v[162:165], v[62:65]
	v_mfma_f32_16x16x32_bf16 v[58:61], v[154:157], v[162:165], v[58:61]
	v_mfma_f32_16x16x32_bf16 v[54:57], v[146:149], v[170:173], v[54:57]
	v_mfma_f32_16x16x32_bf16 v[50:53], v[154:157], v[170:173], v[50:53]
	v_mfma_f32_16x16x32_bf16 v[36:39], v[146:149], v[178:181], v[36:39]
	v_mfma_f32_16x16x32_bf16 v[32:35], v[154:157], v[178:181], v[32:35]
	v_mfma_f32_16x16x32_bf16 v[20:23], v[146:149], v[186:189], v[20:23]
	v_mfma_f32_16x16x32_bf16 v[16:19], v[154:157], v[186:189], v[16:19]
	v_mfma_f32_16x16x32_bf16 v[62:65], v[150:153], v[166:169], v[62:65]
	v_mfma_f32_16x16x32_bf16 v[58:61], v[158:161], v[166:169], v[58:61]
	v_mfma_f32_16x16x32_bf16 v[54:57], v[150:153], v[174:177], v[54:57]
	v_mfma_f32_16x16x32_bf16 v[50:53], v[158:161], v[174:177], v[50:53]
	v_mfma_f32_16x16x32_bf16 v[36:39], v[150:153], v[182:185], v[36:39]
	v_mfma_f32_16x16x32_bf16 v[32:35], v[158:161], v[182:185], v[32:35]
	v_mfma_f32_16x16x32_bf16 v[20:23], v[150:153], v[190:193], v[20:23]
	v_mfma_f32_16x16x32_bf16 v[16:19], v[158:161], v[190:193], v[16:19]
	s_setprio 0
	s_barrier
	s_add_u32 s22, s26, 0x20080
	s_addc_u32 s23, s27, 0
	s_add_i32 s26, s28, s37
	s_mov_b32 m0, s26
	s_nop 0
	global_load_lds_dwordx4 v48, s[22:23]
	s_add_i32 m0, s26, 0x2000
	s_nop 0
	global_load_lds_dwordx4 v130, s[22:23]
	s_waitcnt vmcnt(6)
	s_barrier
	s_setprio 1
	v_mfma_f32_16x16x32_bf16 v[44:47], v[198:201], v[162:165], v[44:47]
	v_mfma_f32_16x16x32_bf16 v[40:43], v[206:209], v[162:165], v[40:43]
	v_mfma_f32_16x16x32_bf16 v[28:31], v[198:201], v[170:173], v[28:31]
	v_mfma_f32_16x16x32_bf16 v[24:27], v[206:209], v[170:173], v[24:27]
	v_mfma_f32_16x16x32_bf16 v[12:15], v[198:201], v[178:181], v[12:15]
	v_mfma_f32_16x16x32_bf16 v[8:11], v[206:209], v[178:181], v[8:11]
	v_mfma_f32_16x16x32_bf16 v[4:7], v[198:201], v[186:189], v[4:7]
	v_mfma_f32_16x16x32_bf16 v[0:3], v[206:209], v[186:189], v[0:3]
	v_mfma_f32_16x16x32_bf16 v[44:47], v[202:205], v[166:169], v[44:47]
	v_mfma_f32_16x16x32_bf16 v[40:43], v[210:213], v[166:169], v[40:43]
	v_mfma_f32_16x16x32_bf16 v[28:31], v[202:205], v[174:177], v[28:31]
	v_mfma_f32_16x16x32_bf16 v[24:27], v[210:213], v[174:177], v[24:27]
	v_mfma_f32_16x16x32_bf16 v[12:15], v[202:205], v[182:185], v[12:15]
	v_mfma_f32_16x16x32_bf16 v[8:11], v[210:213], v[182:185], v[8:11]
	v_mfma_f32_16x16x32_bf16 v[4:7], v[202:205], v[190:193], v[4:7]
	v_mfma_f32_16x16x32_bf16 v[0:3], v[210:213], v[190:193], v[0:3]
	s_setprio 0
	s_add_i32 s49, s49, 2
	s_add_u32 s5, s5, 0x100
	s_addc_u32 s48, s48, 0
	s_cmp_gt_u32 s49, 5
	s_mov_b64 s[22:23], s[24:25]
	s_barrier
	s_cbranch_scc0 .LBB0_641
	v_lshl_add_u32 v146, s47, 8, v142
	v_mov_b32_e32 v145, 0x240000
	v_ashrrev_i32_e32 v147, 31, v146
	v_mad_i64_i32 v[148:149], s[22:23], s46, v145, v[136:137]
	v_lshlrev_b64 v[150:151], 10, v[146:147]
	v_lshl_add_u64 v[150:151], v[148:149], 0, v[150:151]
	global_store_dwordx4 v[150:151], v[126:129], off
	global_store_dwordx4 v[150:151], v[122:125], off offset:64
	global_store_dwordx4 v[150:151], v[110:113], off offset:512
	global_store_dwordx4 v[150:151], v[102:105], off offset:576
	s_mov_b32 s5, 0x20000
	s_mov_b64 s[22:23], 0x20000
	v_or_b32_e32 v102, 16, v146
	v_ashrrev_i32_e32 v103, 31, v102
	v_lshlrev_b64 v[102:103], 10, v[102:103]
	v_lshl_add_u64 v[102:103], v[148:149], 0, v[102:103]
	global_store_dwordx4 v[102:103], v[118:121], off
	global_store_dwordx4 v[102:103], v[114:117], off offset:64
	global_store_dwordx4 v[102:103], v[94:97], off offset:512
	global_store_dwordx4 v[102:103], v[86:89], off offset:576
	s_mov_b32 s46, s4
	s_mov_b32 s47, s45
	v_or_b32_e32 v86, 32, v146
	v_ashrrev_i32_e32 v87, 31, v86
	v_lshlrev_b64 v[86:87], 10, v[86:87]
	v_lshl_add_u64 v[86:87], v[148:149], 0, v[86:87]
	global_store_dwordx4 v[86:87], v[106:109], off
	global_store_dwordx4 v[86:87], v[98:101], off offset:64
	global_store_dwordx4 v[86:87], v[78:81], off offset:512
	global_store_dwordx4 v[86:87], v[74:77], off offset:576
	s_mov_b64 s[24:25], s[20:21]
	s_nop 0
	v_or_b32_e32 v74, 48, v146
	v_ashrrev_i32_e32 v75, 31, v74
	v_lshlrev_b64 v[74:75], 10, v[74:75]
	v_lshl_add_u64 v[74:75], v[148:149], 0, v[74:75]
	global_store_dwordx4 v[74:75], v[90:93], off
	global_store_dwordx4 v[74:75], v[82:85], off offset:64
	global_store_dwordx4 v[74:75], v[70:73], off offset:512
	global_store_dwordx4 v[74:75], v[66:69], off offset:576
	s_nop 1
	v_add_co_u32_e32 v68, vcc, s5, v150
	s_mov_b32 s5, 0x24000
	s_nop 0
	v_addc_co_u32_e32 v69, vcc, 0, v151, vcc
	v_lshl_add_u64 v[66:67], v[150:151], 0, s[22:23]
	global_store_dwordx4 v[68:69], v[62:65], off
	global_store_dwordx4 v[66:67], v[58:61], off offset:64
	global_store_dwordx4 v[66:67], v[44:47], off offset:512
	global_store_dwordx4 v[66:67], v[40:43], off offset:576
	s_mov_b64 s[22:23], 0x24000
	s_nop 0
	v_add_co_u32_e32 v42, vcc, s5, v150
	s_mov_b32 s5, 0x28000
	s_nop 0
	v_addc_co_u32_e32 v43, vcc, 0, v151, vcc
	v_lshl_add_u64 v[40:41], v[150:151], 0, s[22:23]
	global_store_dwordx4 v[42:43], v[54:57], off
	global_store_dwordx4 v[40:41], v[50:53], off offset:64
	global_store_dwordx4 v[40:41], v[28:31], off offset:512
	global_store_dwordx4 v[40:41], v[24:27], off offset:576
	s_mov_b64 s[22:23], 0x28000
	s_nop 0
	v_add_co_u32_e32 v26, vcc, s5, v150
	v_lshl_add_u64 v[24:25], v[150:151], 0, s[22:23]
	s_nop 0
	v_addc_co_u32_e32 v27, vcc, 0, v151, vcc
	global_store_dwordx4 v[26:27], v[36:39], off
	global_store_dwordx4 v[24:25], v[32:35], off offset:64
	global_store_dwordx4 v[24:25], v[12:15], off offset:512
	global_store_dwordx4 v[24:25], v[8:11], off offset:576
	s_mov_b64 s[22:23], 0x2c000
	s_nop 0
	v_add_co_u32_e32 v10, vcc, 0x2c000, v150
	v_lshl_add_u64 v[8:9], v[150:151], 0, s[22:23]
	s_nop 0
	v_addc_co_u32_e32 v11, vcc, 0, v151, vcc
	s_and_b64 vcc, exec, s[0:1]
	s_mov_b64 s[22:23], s[18:19]
	global_store_dwordx4 v[10:11], v[20:23], off
	global_store_dwordx4 v[8:9], v[16:19], off offset:64
	global_store_dwordx4 v[8:9], v[4:7], off offset:512
	global_store_dwordx4 v[8:9], v[0:3], off offset:576
	s_cbranch_vccz .LBB0_638
	s_waitcnt vmcnt(0)
	s_cmpk_gt_u32 s30, 0xff
	s_cbranch_scc1 .LBB0_645
	s_barrier

.LBB0_1056:
	s_add_i32 s56, s28, 2
	s_add_u32 s29, s24, 0xfffc0080
	s_addc_u32 s30, s25, -1
	s_add_i32 s57, 0, 0x10000
	v_add_u32_e32 v142, s57, v216
	ds_read_b128 v[130:133], v142
	ds_read_b128 v[134:137], v142 offset:1024
	ds_read_b128 v[138:141], v142 offset:2048
	ds_read_b128 v[142:145], v142 offset:3072
	s_cmp_eq_u32 s17, s28
	s_cselect_b32 s28, s22, s19
	s_cselect_b32 s31, s21, s30
	s_cselect_b32 s30, s20, s29
	s_cselect_b32 s29, s23, s27
	s_add_i32 m0, s39, 0xc000
	ds_read_b128 v[146:149], v217
	ds_read_b128 v[150:153], v217 offset:1024
	ds_read_b128 v[154:157], v217 offset:2048
	ds_read_b128 v[158:161], v217 offset:3072
	ds_read_b128 v[162:165], v217 offset:4096
	ds_read_b128 v[166:169], v217 offset:5120
	ds_read_b128 v[170:173], v217 offset:6144
	ds_read_b128 v[174:177], v217 offset:7168
	global_load_lds_dwordx4 v204, s[24:25]
	s_add_i32 m0, s39, 0xe000
	s_nop 0
	global_load_lds_dwordx4 v206, s[24:25]
	s_waitcnt lgkmcnt(8)
	s_barrier
	s_waitcnt lgkmcnt(0)
	s_setprio 1
	s_waitcnt lgkmcnt(0)
	v_mfma_f32_16x16x32_bf16 v[126:129], v[130:133], v[146:149], v[126:129]
	v_mfma_f32_16x16x32_bf16 v[122:125], v[138:141], v[146:149], v[122:125]
	v_mfma_f32_16x16x32_bf16 v[118:121], v[130:133], v[154:157], v[118:121]
	v_mfma_f32_16x16x32_bf16 v[114:117], v[138:141], v[154:157], v[114:117]
	v_mfma_f32_16x16x32_bf16 v[102:105], v[130:133], v[162:165], v[102:105]
	v_mfma_f32_16x16x32_bf16 v[98:101], v[138:141], v[162:165], v[98:101]
	v_mfma_f32_16x16x32_bf16 v[86:89], v[130:133], v[170:173], v[86:89]
	v_mfma_f32_16x16x32_bf16 v[82:85], v[138:141], v[170:173], v[82:85]
	v_mfma_f32_16x16x32_bf16 v[126:129], v[134:137], v[150:153], v[126:129]
	v_mfma_f32_16x16x32_bf16 v[122:125], v[142:145], v[150:153], v[122:125]
	v_mfma_f32_16x16x32_bf16 v[118:121], v[134:137], v[158:161], v[118:121]
	v_mfma_f32_16x16x32_bf16 v[114:117], v[142:145], v[158:161], v[114:117]
	v_mfma_f32_16x16x32_bf16 v[102:105], v[134:137], v[166:169], v[102:105]
	v_mfma_f32_16x16x32_bf16 v[98:101], v[142:145], v[166:169], v[98:101]
	v_mfma_f32_16x16x32_bf16 v[86:89], v[134:137], v[174:177], v[86:89]
	v_mfma_f32_16x16x32_bf16 v[82:85], v[142:145], v[174:177], v[82:85]
	s_setprio 0
	s_barrier
	s_add_i32 s60, 0, 0x14000
	s_add_i32 s57, s57, s38
	v_add_u32_e32 v190, s60, v216
	v_lshl_add_u64 v[208:209], s[28:29], 0, v[48:49]
	s_mov_b32 m0, s57
	ds_read_b128 v[178:181], v190
	ds_read_b128 v[182:185], v190 offset:1024
	ds_read_b128 v[186:189], v190 offset:2048
	ds_read_b128 v[190:193], v190 offset:3072
	global_load_lds_dwordx4 v[208:209], off
	v_lshl_add_u64 v[210:211], s[28:29], 0, v[202:203]
	s_add_i32 m0, s57, 0x2000
	s_nop 0
	global_load_lds_dwordx4 v[210:211], off
	s_barrier
	s_waitcnt lgkmcnt(0)
	s_setprio 1
	s_waitcnt lgkmcnt(0)
	v_mfma_f32_16x16x32_bf16 v[110:113], v[178:181], v[146:149], v[110:113]
	v_mfma_f32_16x16x32_bf16 v[106:109], v[186:189], v[146:149], v[106:109]
	v_mfma_f32_16x16x32_bf16 v[94:97], v[178:181], v[154:157], v[94:97]
	v_mfma_f32_16x16x32_bf16 v[90:93], v[186:189], v[154:157], v[90:93]
	v_mfma_f32_16x16x32_bf16 v[78:81], v[178:181], v[162:165], v[78:81]
	v_mfma_f32_16x16x32_bf16 v[74:77], v[186:189], v[162:165], v[74:77]
	v_mfma_f32_16x16x32_bf16 v[70:73], v[178:181], v[170:173], v[70:73]
	v_mfma_f32_16x16x32_bf16 v[66:69], v[186:189], v[170:173], v[66:69]
	v_mfma_f32_16x16x32_bf16 v[110:113], v[182:185], v[150:153], v[110:113]
	v_mfma_f32_16x16x32_bf16 v[106:109], v[190:193], v[150:153], v[106:109]
	v_mfma_f32_16x16x32_bf16 v[94:97], v[182:185], v[158:161], v[94:97]
	v_mfma_f32_16x16x32_bf16 v[90:93], v[190:193], v[158:161], v[90:93]
	v_mfma_f32_16x16x32_bf16 v[78:81], v[182:185], v[166:169], v[78:81]
	v_mfma_f32_16x16x32_bf16 v[74:77], v[190:193], v[166:169], v[74:77]
	v_mfma_f32_16x16x32_bf16 v[70:73], v[182:185], v[174:177], v[70:73]
	v_mfma_f32_16x16x32_bf16 v[66:69], v[190:193], v[174:177], v[66:69]
	s_setprio 0
	s_mov_b32 m0, s39
	v_lshl_add_u64 v[212:213], s[30:31], 0, v[198:199]
	s_barrier
	ds_read_b128 v[146:149], v217 offset:16384
	ds_read_b128 v[150:153], v217 offset:17408
	ds_read_b128 v[154:157], v217 offset:18432
	ds_read_b128 v[158:161], v217 offset:19456
	ds_read_b128 v[162:165], v217 offset:20480
	ds_read_b128 v[166:169], v217 offset:21504
	ds_read_b128 v[170:173], v217 offset:22528
	ds_read_b128 v[174:177], v217 offset:23552
	global_load_lds_dwordx4 v[212:213], off
	v_lshl_add_u64 v[218:219], s[30:31], 0, v[200:201]
	s_mov_b32 m0, s40
	s_nop 0
	global_load_lds_dwordx4 v[218:219], off
	s_barrier
	s_waitcnt lgkmcnt(0)
	s_setprio 1
	s_waitcnt lgkmcnt(0)
	v_mfma_f32_16x16x32_bf16 v[62:65], v[130:133], v[146:149], v[62:65]
	v_mfma_f32_16x16x32_bf16 v[58:61], v[138:141], v[146:149], v[58:61]
	v_mfma_f32_16x16x32_bf16 v[54:57], v[130:133], v[154:157], v[54:57]
	v_mfma_f32_16x16x32_bf16 v[50:53], v[138:141], v[154:157], v[50:53]
	v_mfma_f32_16x16x32_bf16 v[36:39], v[130:133], v[162:165], v[36:39]
	v_mfma_f32_16x16x32_bf16 v[32:35], v[138:141], v[162:165], v[32:35]
	v_mfma_f32_16x16x32_bf16 v[20:23], v[130:133], v[170:173], v[20:23]
	v_mfma_f32_16x16x32_bf16 v[16:19], v[138:141], v[170:173], v[16:19]
	v_mfma_f32_16x16x32_bf16 v[62:65], v[134:137], v[150:153], v[62:65]
	v_mfma_f32_16x16x32_bf16 v[58:61], v[142:145], v[150:153], v[58:61]
	v_mfma_f32_16x16x32_bf16 v[54:57], v[134:137], v[158:161], v[54:57]
	v_mfma_f32_16x16x32_bf16 v[50:53], v[142:145], v[158:161], v[50:53]
	v_mfma_f32_16x16x32_bf16 v[36:39], v[134:137], v[166:169], v[36:39]
	v_mfma_f32_16x16x32_bf16 v[32:35], v[142:145], v[166:169], v[32:35]
	v_mfma_f32_16x16x32_bf16 v[20:23], v[134:137], v[174:177], v[20:23]
	v_mfma_f32_16x16x32_bf16 v[16:19], v[142:145], v[174:177], v[16:19]
	s_setprio 0
	s_barrier
	s_add_u32 s58, s28, 0x40000
	s_addc_u32 s59, s29, 0
	s_add_i32 s57, s60, s38
	s_mov_b32 m0, s57
	s_nop 0
	global_load_lds_dwordx4 v48, s[58:59]
	s_add_i32 m0, s57, 0x2000
	s_nop 0
	global_load_lds_dwordx4 v202, s[58:59]
	s_waitcnt vmcnt(6)
	s_barrier
	s_setprio 1
	v_mfma_f32_16x16x32_bf16 v[44:47], v[178:181], v[146:149], v[44:47]
	v_mfma_f32_16x16x32_bf16 v[40:43], v[186:189], v[146:149], v[40:43]
	v_mfma_f32_16x16x32_bf16 v[28:31], v[178:181], v[154:157], v[28:31]
	v_mfma_f32_16x16x32_bf16 v[24:27], v[186:189], v[154:157], v[24:27]
	v_mfma_f32_16x16x32_bf16 v[12:15], v[178:181], v[162:165], v[12:15]
	v_mfma_f32_16x16x32_bf16 v[8:11], v[186:189], v[162:165], v[8:11]
	v_mfma_f32_16x16x32_bf16 v[4:7], v[178:181], v[170:173], v[4:7]
	v_mfma_f32_16x16x32_bf16 v[0:3], v[186:189], v[170:173], v[0:3]
	v_mfma_f32_16x16x32_bf16 v[44:47], v[182:185], v[150:153], v[44:47]
	v_mfma_f32_16x16x32_bf16 v[40:43], v[190:193], v[150:153], v[40:43]
	v_mfma_f32_16x16x32_bf16 v[28:31], v[182:185], v[158:161], v[28:31]
	v_mfma_f32_16x16x32_bf16 v[24:27], v[190:193], v[158:161], v[24:27]
	v_mfma_f32_16x16x32_bf16 v[12:15], v[182:185], v[166:169], v[12:15]
	v_mfma_f32_16x16x32_bf16 v[8:11], v[190:193], v[166:169], v[8:11]
	v_mfma_f32_16x16x32_bf16 v[4:7], v[182:185], v[174:177], v[4:7]
	v_mfma_f32_16x16x32_bf16 v[0:3], v[190:193], v[174:177], v[0:3]
	s_setprio 0
	s_add_i32 s57, 0, 0x18000
	v_add_u32_e32 v142, s57, v216
	s_barrier
	ds_read_b128 v[130:133], v142
	ds_read_b128 v[134:137], v142 offset:1024
	ds_read_b128 v[138:141], v142 offset:2048
	ds_read_b128 v[142:145], v142 offset:3072
	s_add_u32 s30, s30, 0x40000
	s_addc_u32 s31, s31, 0
	s_mov_b32 m0, s41
	ds_read_b128 v[146:149], v217 offset:32768
	ds_read_b128 v[150:153], v217 offset:33792
	ds_read_b128 v[154:157], v217 offset:34816
	ds_read_b128 v[158:161], v217 offset:35840
	ds_read_b128 v[162:165], v217 offset:36864
	ds_read_b128 v[166:169], v217 offset:37888
	ds_read_b128 v[170:173], v217 offset:38912
	ds_read_b128 v[174:177], v217 offset:39936
	global_load_lds_dwordx4 v198, s[30:31]
	s_mov_b32 m0, s42
	s_nop 0
	global_load_lds_dwordx4 v200, s[30:31]
	s_waitcnt lgkmcnt(8)
	s_barrier
	s_waitcnt lgkmcnt(0)
	s_setprio 1
	s_waitcnt lgkmcnt(0)
	v_mfma_f32_16x16x32_bf16 v[126:129], v[130:133], v[146:149], v[126:129]
	v_mfma_f32_16x16x32_bf16 v[122:125], v[138:141], v[146:149], v[122:125]
	v_mfma_f32_16x16x32_bf16 v[118:121], v[130:133], v[154:157], v[118:121]
	v_mfma_f32_16x16x32_bf16 v[114:117], v[138:141], v[154:157], v[114:117]
	v_mfma_f32_16x16x32_bf16 v[102:105], v[130:133], v[162:165], v[102:105]
	v_mfma_f32_16x16x32_bf16 v[98:101], v[138:141], v[162:165], v[98:101]
	v_mfma_f32_16x16x32_bf16 v[86:89], v[130:133], v[170:173], v[86:89]
	v_mfma_f32_16x16x32_bf16 v[82:85], v[138:141], v[170:173], v[82:85]
	v_mfma_f32_16x16x32_bf16 v[126:129], v[134:137], v[150:153], v[126:129]
	v_mfma_f32_16x16x32_bf16 v[122:125], v[142:145], v[150:153], v[122:125]
	v_mfma_f32_16x16x32_bf16 v[118:121], v[134:137], v[158:161], v[118:121]
	v_mfma_f32_16x16x32_bf16 v[114:117], v[142:145], v[158:161], v[114:117]
	v_mfma_f32_16x16x32_bf16 v[102:105], v[134:137], v[166:169], v[102:105]
	v_mfma_f32_16x16x32_bf16 v[98:101], v[142:145], v[166:169], v[98:101]
	v_mfma_f32_16x16x32_bf16 v[86:89], v[134:137], v[174:177], v[86:89]
	v_mfma_f32_16x16x32_bf16 v[82:85], v[142:145], v[174:177], v[82:85]
	s_setprio 0
	s_barrier
	s_add_i32 s30, 0, 0x1c000
	s_add_i32 s31, s57, s38
	v_add_u32_e32 v190, s30, v216
	v_lshl_add_u64 v[208:209], v[208:209], 0, s[66:67]
	s_mov_b32 m0, s31
	ds_read_b128 v[178:181], v190
	ds_read_b128 v[182:185], v190 offset:1024
	ds_read_b128 v[186:189], v190 offset:2048
	ds_read_b128 v[190:193], v190 offset:3072
	global_load_lds_dwordx4 v[208:209], off
	v_lshl_add_u64 v[208:209], v[210:211], 0, s[66:67]
	s_add_i32 m0, s31, 0x2000
	s_nop 0
	global_load_lds_dwordx4 v[208:209], off
	s_barrier
	s_waitcnt lgkmcnt(0)
	s_setprio 1
	s_waitcnt lgkmcnt(0)
	v_mfma_f32_16x16x32_bf16 v[110:113], v[178:181], v[146:149], v[110:113]
	v_mfma_f32_16x16x32_bf16 v[106:109], v[186:189], v[146:149], v[106:109]
	v_mfma_f32_16x16x32_bf16 v[94:97], v[178:181], v[154:157], v[94:97]
	v_mfma_f32_16x16x32_bf16 v[90:93], v[186:189], v[154:157], v[90:93]
	v_mfma_f32_16x16x32_bf16 v[78:81], v[178:181], v[162:165], v[78:81]
	v_mfma_f32_16x16x32_bf16 v[74:77], v[186:189], v[162:165], v[74:77]
	v_mfma_f32_16x16x32_bf16 v[70:73], v[178:181], v[170:173], v[70:73]
	v_mfma_f32_16x16x32_bf16 v[66:69], v[186:189], v[170:173], v[66:69]
	v_mfma_f32_16x16x32_bf16 v[110:113], v[182:185], v[150:153], v[110:113]
	v_mfma_f32_16x16x32_bf16 v[106:109], v[190:193], v[150:153], v[106:109]
	v_mfma_f32_16x16x32_bf16 v[94:97], v[182:185], v[158:161], v[94:97]
	v_mfma_f32_16x16x32_bf16 v[90:93], v[190:193], v[158:161], v[90:93]
	v_mfma_f32_16x16x32_bf16 v[78:81], v[182:185], v[166:169], v[78:81]
	v_mfma_f32_16x16x32_bf16 v[74:77], v[190:193], v[166:169], v[74:77]
	v_mfma_f32_16x16x32_bf16 v[70:73], v[182:185], v[174:177], v[70:73]
	v_mfma_f32_16x16x32_bf16 v[66:69], v[190:193], v[174:177], v[66:69]
	s_setprio 0
	s_mov_b32 m0, s49
	v_lshl_add_u64 v[208:209], v[212:213], 0, s[66:67]
	s_barrier
	ds_read_b128 v[146:149], v217 offset:49152
	ds_read_b128 v[150:153], v217 offset:50176
	ds_read_b128 v[154:157], v217 offset:51200
	ds_read_b128 v[158:161], v217 offset:52224
	ds_read_b128 v[162:165], v217 offset:53248
	ds_read_b128 v[166:169], v217 offset:54272
	ds_read_b128 v[170:173], v217 offset:55296
	ds_read_b128 v[174:177], v217 offset:56320
	global_load_lds_dwordx4 v[208:209], off
	v_lshl_add_u64 v[208:209], v[218:219], 0, s[66:67]
	s_mov_b32 m0, s50
	s_nop 0
	global_load_lds_dwordx4 v[208:209], off
	s_barrier
	s_waitcnt lgkmcnt(0)
	s_setprio 1
	s_waitcnt lgkmcnt(0)
	v_mfma_f32_16x16x32_bf16 v[62:65], v[130:133], v[146:149], v[62:65]
	v_mfma_f32_16x16x32_bf16 v[58:61], v[138:141], v[146:149], v[58:61]
	v_mfma_f32_16x16x32_bf16 v[54:57], v[130:133], v[154:157], v[54:57]
	v_mfma_f32_16x16x32_bf16 v[50:53], v[138:141], v[154:157], v[50:53]
	v_mfma_f32_16x16x32_bf16 v[36:39], v[130:133], v[162:165], v[36:39]
	v_mfma_f32_16x16x32_bf16 v[32:35], v[138:141], v[162:165], v[32:35]
	v_mfma_f32_16x16x32_bf16 v[20:23], v[130:133], v[170:173], v[20:23]
	v_mfma_f32_16x16x32_bf16 v[16:19], v[138:141], v[170:173], v[16:19]
	v_mfma_f32_16x16x32_bf16 v[62:65], v[134:137], v[150:153], v[62:65]
	v_mfma_f32_16x16x32_bf16 v[58:61], v[142:145], v[150:153], v[58:61]
	v_mfma_f32_16x16x32_bf16 v[54:57], v[134:137], v[158:161], v[54:57]
	v_mfma_f32_16x16x32_bf16 v[50:53], v[142:145], v[158:161], v[50:53]
	v_mfma_f32_16x16x32_bf16 v[36:39], v[134:137], v[166:169], v[36:39]
	v_mfma_f32_16x16x32_bf16 v[32:35], v[142:145], v[166:169], v[32:35]
	v_mfma_f32_16x16x32_bf16 v[20:23], v[134:137], v[174:177], v[20:23]
	v_mfma_f32_16x16x32_bf16 v[16:19], v[142:145], v[174:177], v[16:19]
	s_setprio 0
	s_barrier
	s_add_u32 s28, s28, 0x40080
	s_addc_u32 s29, s29, 0
	s_add_i32 s30, s30, s38
	s_mov_b32 m0, s30
	s_nop 0
	global_load_lds_dwordx4 v48, s[28:29]
	s_add_i32 m0, s30, 0x2000
	s_nop 0
	global_load_lds_dwordx4 v202, s[28:29]
	s_waitcnt vmcnt(6)
	s_barrier
	s_setprio 1
	v_mfma_f32_16x16x32_bf16 v[44:47], v[178:181], v[146:149], v[44:47]
	v_mfma_f32_16x16x32_bf16 v[40:43], v[186:189], v[146:149], v[40:43]
	v_mfma_f32_16x16x32_bf16 v[28:31], v[178:181], v[154:157], v[28:31]
	v_mfma_f32_16x16x32_bf16 v[24:27], v[186:189], v[154:157], v[24:27]
	v_mfma_f32_16x16x32_bf16 v[12:15], v[178:181], v[162:165], v[12:15]
	v_mfma_f32_16x16x32_bf16 v[8:11], v[186:189], v[162:165], v[8:11]
	v_mfma_f32_16x16x32_bf16 v[4:7], v[178:181], v[170:173], v[4:7]
	v_mfma_f32_16x16x32_bf16 v[0:3], v[186:189], v[170:173], v[0:3]
	v_mfma_f32_16x16x32_bf16 v[44:47], v[182:185], v[150:153], v[44:47]
	v_mfma_f32_16x16x32_bf16 v[40:43], v[190:193], v[150:153], v[40:43]
	v_mfma_f32_16x16x32_bf16 v[28:31], v[182:185], v[158:161], v[28:31]
	v_mfma_f32_16x16x32_bf16 v[24:27], v[190:193], v[158:161], v[24:27]
	v_mfma_f32_16x16x32_bf16 v[12:15], v[182:185], v[166:169], v[12:15]
	v_mfma_f32_16x16x32_bf16 v[8:11], v[190:193], v[166:169], v[8:11]
	v_mfma_f32_16x16x32_bf16 v[4:7], v[182:185], v[174:177], v[4:7]
	v_mfma_f32_16x16x32_bf16 v[0:3], v[190:193], v[174:177], v[0:3]
	s_setprio 0
	s_add_u32 s24, s24, 0x100
	s_addc_u32 s25, s25, 0
	s_add_u32 s19, s19, 0x100
	s_addc_u32 s27, s27, 0
	s_cmp_ge_i32 s56, s1
	s_mov_b32 s28, s56
	s_barrier
	s_cbranch_scc0 .LBB0_1056
	v_mov_b32_e32 v130, v214
	v_mov_b32_e32 v131, v215
	s_bitcmp1_b32 s55, 0
	v_add_u32_e32 v134, s47, v130
	v_lshlrev_b32_e32 v130, 8, v134
	v_lshl_add_u32 v132, v131, 3, s48
	v_ashrrev_i32_e32 v131, 31, v130
	v_lshl_add_u64 v[130:131], v[130:131], 1, s[12:13]
	v_ashrrev_i32_e32 v133, 31, v132
	s_cselect_b64 s[28:29], -1, 0
	v_lshlrev_b32_e32 v208, 9, v215
	v_lshl_add_u32 v208, v214, 4, v208
	v_lshl_add_u32 v208, s47, 9, v208
	v_lshl_add_u32 v208, s48, 6, v208
	v_mov_b32_e32 v209, 0
	v_lshl_add_u64 v[208:209], v[208:209], 0, s[12:13]
	s_mov_b64 s[24:25], -1
	s_and_b64 vcc, exec, s[28:29]
	s_mov_b32 s57, s81
	s_cbranch_vccz .LBB0_1093
	s_mov_b64 s[24:25], 0x20000
	v_lshl_add_u64 v[130:131], v[208:209], 0, s[24:25]
	s_and_b32 s1, s55, -2
	s_mov_b64 s[24:25], 0x100
	s_cmp_lg_u32 s1, 4
	v_mov_b64_e32 v[210:211], v[130:131]
	s_cbranch_scc1 .LBB0_1060
	v_lshl_add_u32 v134, s26, 8, v134
	v_ashrrev_i32_e32 v135, 31, v134
	v_lshlrev_b64 v[134:135], 11, v[134:135]
	s_lshl_b32 s0, s0, 8
	v_lshl_add_u64 v[134:135], s[14:15], 0, v[134:135]
	s_ashr_i32 s1, s0, 31
	v_lshl_add_u64 v[134:135], s[0:1], 1, v[134:135]
	v_lshl_add_u64 v[210:211], v[132:133], 1, v[134:135]
	s_mov_b64 s[24:25], 0x400

.LBB0_1202:
	s_add_u32 s28, s26, 0xfffc0080
	s_addc_u32 s29, s27, -1
	s_add_i32 s49, 0, 0x10000
	v_add_u32_e32 v142, s49, v170
	ds_read_b128 v[130:133], v142
	ds_read_b128 v[134:137], v142 offset:1024
	ds_read_b128 v[138:141], v142 offset:2048
	ds_read_b128 v[142:145], v142 offset:3072
	s_cmp_eq_u32 s25, 12
	s_cselect_b32 s31, s19, s29
	s_cselect_b32 s30, s18, s28
	s_cselect_b32 s29, s21, s17
	s_cselect_b32 s28, s20, s15
	v_lshl_add_u64 v[190:191], s[26:27], 0, v[150:151]
	s_add_i32 m0, s23, 0xc000
	ds_read_b128 v[154:157], v172
	ds_read_b128 v[158:161], v172 offset:1024
	ds_read_b128 v[162:165], v172 offset:2048
	ds_read_b128 v[166:169], v172 offset:3072
	ds_read_b128 v[174:177], v172 offset:4096
	ds_read_b128 v[178:181], v172 offset:5120
	ds_read_b128 v[182:185], v172 offset:6144
	ds_read_b128 v[186:189], v172 offset:7168
	global_load_lds_dwordx4 v[190:191], off
	v_lshl_add_u64 v[190:191], s[26:27], 0, v[152:153]
	s_add_i32 m0, s23, 0xe000
	s_nop 0
	global_load_lds_dwordx4 v[190:191], off
	s_waitcnt lgkmcnt(8)
	s_barrier
	s_waitcnt lgkmcnt(0)
	s_setprio 1
	s_waitcnt lgkmcnt(0)
	v_mfma_f32_16x16x32_bf16 v[126:129], v[130:133], v[154:157], v[126:129]
	v_mfma_f32_16x16x32_bf16 v[122:125], v[138:141], v[154:157], v[122:125]
	v_mfma_f32_16x16x32_bf16 v[114:117], v[130:133], v[162:165], v[114:117]
	v_mfma_f32_16x16x32_bf16 v[106:109], v[138:141], v[162:165], v[106:109]
	v_mfma_f32_16x16x32_bf16 v[94:97], v[130:133], v[174:177], v[94:97]
	v_mfma_f32_16x16x32_bf16 v[90:93], v[138:141], v[174:177], v[90:93]
	v_mfma_f32_16x16x32_bf16 v[82:85], v[130:133], v[182:185], v[82:85]
	v_mfma_f32_16x16x32_bf16 v[74:77], v[138:141], v[182:185], v[74:77]
	v_mfma_f32_16x16x32_bf16 v[126:129], v[134:137], v[158:161], v[126:129]
	v_mfma_f32_16x16x32_bf16 v[122:125], v[142:145], v[158:161], v[122:125]
	v_mfma_f32_16x16x32_bf16 v[114:117], v[134:137], v[166:169], v[114:117]
	v_mfma_f32_16x16x32_bf16 v[106:109], v[142:145], v[166:169], v[106:109]
	v_mfma_f32_16x16x32_bf16 v[94:97], v[134:137], v[178:181], v[94:97]
	v_mfma_f32_16x16x32_bf16 v[90:93], v[142:145], v[178:181], v[90:93]
	v_mfma_f32_16x16x32_bf16 v[82:85], v[134:137], v[186:189], v[82:85]
	v_mfma_f32_16x16x32_bf16 v[74:77], v[142:145], v[186:189], v[74:77]
	s_setprio 0
	s_barrier
	s_add_i32 s52, 0, 0x14000
	s_add_i32 s49, s49, s35
	v_add_u32_e32 v173, s52, v170
	v_lshl_add_u64 v[210:211], s[28:29], 0, v[48:49]
	s_mov_b32 m0, s49
	ds_read_b128 v[190:193], v173
	ds_read_b128 v[198:201], v173 offset:1024
	ds_read_b128 v[202:205], v173 offset:2048
	ds_read_b128 v[206:209], v173 offset:3072
	global_load_lds_dwordx4 v[210:211], off
	v_lshl_add_u64 v[212:213], s[28:29], 0, v[146:147]
	s_add_i32 m0, s49, 0x2000
	s_nop 0
	global_load_lds_dwordx4 v[212:213], off
	s_barrier
	s_waitcnt lgkmcnt(0)
	s_setprio 1
	s_waitcnt lgkmcnt(0)
	v_mfma_f32_16x16x32_bf16 v[118:121], v[190:193], v[154:157], v[118:121]
	v_mfma_f32_16x16x32_bf16 v[110:113], v[202:205], v[154:157], v[110:113]
	v_mfma_f32_16x16x32_bf16 v[102:105], v[190:193], v[162:165], v[102:105]
	v_mfma_f32_16x16x32_bf16 v[98:101], v[202:205], v[162:165], v[98:101]
	v_mfma_f32_16x16x32_bf16 v[86:89], v[190:193], v[174:177], v[86:89]
	v_mfma_f32_16x16x32_bf16 v[78:81], v[202:205], v[174:177], v[78:81]
	v_mfma_f32_16x16x32_bf16 v[70:73], v[190:193], v[182:185], v[70:73]
	v_mfma_f32_16x16x32_bf16 v[66:69], v[202:205], v[182:185], v[66:69]
	v_mfma_f32_16x16x32_bf16 v[118:121], v[198:201], v[158:161], v[118:121]
	v_mfma_f32_16x16x32_bf16 v[110:113], v[206:209], v[158:161], v[110:113]
	v_mfma_f32_16x16x32_bf16 v[102:105], v[198:201], v[166:169], v[102:105]
	v_mfma_f32_16x16x32_bf16 v[98:101], v[206:209], v[166:169], v[98:101]
	v_mfma_f32_16x16x32_bf16 v[86:89], v[198:201], v[178:181], v[86:89]
	v_mfma_f32_16x16x32_bf16 v[78:81], v[206:209], v[178:181], v[78:81]
	v_mfma_f32_16x16x32_bf16 v[70:73], v[198:201], v[186:189], v[70:73]
	v_mfma_f32_16x16x32_bf16 v[66:69], v[206:209], v[186:189], v[66:69]
	s_setprio 0
	s_mov_b32 m0, s23
	v_lshl_add_u64 v[214:215], s[30:31], 0, v[48:49]
	s_barrier
	ds_read_b128 v[154:157], v172 offset:16384
	ds_read_b128 v[158:161], v172 offset:17408
	ds_read_b128 v[162:165], v172 offset:18432
	ds_read_b128 v[166:169], v172 offset:19456
	ds_read_b128 v[174:177], v172 offset:20480
	ds_read_b128 v[178:181], v172 offset:21504
	ds_read_b128 v[182:185], v172 offset:22528
	ds_read_b128 v[186:189], v172 offset:23552
	global_load_lds_dwordx4 v[214:215], off
	v_lshl_add_u64 v[216:217], s[30:31], 0, v[146:147]
	s_mov_b32 m0, s41
	s_nop 0
	global_load_lds_dwordx4 v[216:217], off
	s_barrier
	s_waitcnt lgkmcnt(0)
	s_setprio 1
	s_waitcnt lgkmcnt(0)
	v_mfma_f32_16x16x32_bf16 v[62:65], v[130:133], v[154:157], v[62:65]
	v_mfma_f32_16x16x32_bf16 v[58:61], v[138:141], v[154:157], v[58:61]
	v_mfma_f32_16x16x32_bf16 v[50:53], v[130:133], v[162:165], v[50:53]
	v_mfma_f32_16x16x32_bf16 v[40:43], v[138:141], v[162:165], v[40:43]
	v_mfma_f32_16x16x32_bf16 v[32:35], v[130:133], v[174:177], v[32:35]
	v_mfma_f32_16x16x32_bf16 v[24:27], v[138:141], v[174:177], v[24:27]
	v_mfma_f32_16x16x32_bf16 v[16:19], v[130:133], v[182:185], v[16:19]
	v_mfma_f32_16x16x32_bf16 v[8:11], v[138:141], v[182:185], v[8:11]
	v_mfma_f32_16x16x32_bf16 v[62:65], v[134:137], v[158:161], v[62:65]
	v_mfma_f32_16x16x32_bf16 v[58:61], v[142:145], v[158:161], v[58:61]
	v_mfma_f32_16x16x32_bf16 v[50:53], v[134:137], v[166:169], v[50:53]
	v_mfma_f32_16x16x32_bf16 v[40:43], v[142:145], v[166:169], v[40:43]
	v_mfma_f32_16x16x32_bf16 v[32:35], v[134:137], v[178:181], v[32:35]
	v_mfma_f32_16x16x32_bf16 v[24:27], v[142:145], v[178:181], v[24:27]
	v_mfma_f32_16x16x32_bf16 v[16:19], v[134:137], v[186:189], v[16:19]
	v_mfma_f32_16x16x32_bf16 v[8:11], v[142:145], v[186:189], v[8:11]
	s_setprio 0
	s_barrier
	s_add_u32 s50, s28, 0x40000
	s_addc_u32 s51, s29, 0
	s_add_i32 s49, s52, s35
	s_mov_b32 m0, s49
	s_nop 0
	global_load_lds_dwordx4 v48, s[50:51]
	v_lshl_add_u64 v[130:131], s[50:51], 0, v[146:147]
	s_add_i32 m0, s49, 0x2000
	s_nop 0
	global_load_lds_dwordx4 v[130:131], off
	s_waitcnt vmcnt(6)
	s_barrier
	s_setprio 1
	v_mfma_f32_16x16x32_bf16 v[54:57], v[190:193], v[154:157], v[54:57]
	v_mfma_f32_16x16x32_bf16 v[44:47], v[202:205], v[154:157], v[44:47]
	v_mfma_f32_16x16x32_bf16 v[36:39], v[190:193], v[162:165], v[36:39]
	v_mfma_f32_16x16x32_bf16 v[28:31], v[202:205], v[162:165], v[28:31]
	v_mfma_f32_16x16x32_bf16 v[20:23], v[190:193], v[174:177], v[20:23]
	v_mfma_f32_16x16x32_bf16 v[12:15], v[202:205], v[174:177], v[12:15]
	v_mfma_f32_16x16x32_bf16 v[4:7], v[190:193], v[182:185], v[4:7]
	v_mfma_f32_16x16x32_bf16 v[0:3], v[202:205], v[182:185], v[0:3]
	v_mfma_f32_16x16x32_bf16 v[54:57], v[198:201], v[158:161], v[54:57]
	v_mfma_f32_16x16x32_bf16 v[44:47], v[206:209], v[158:161], v[44:47]
	v_mfma_f32_16x16x32_bf16 v[36:39], v[198:201], v[166:169], v[36:39]
	v_mfma_f32_16x16x32_bf16 v[28:31], v[206:209], v[166:169], v[28:31]
	v_mfma_f32_16x16x32_bf16 v[20:23], v[198:201], v[178:181], v[20:23]
	v_mfma_f32_16x16x32_bf16 v[12:15], v[206:209], v[178:181], v[12:15]
	v_mfma_f32_16x16x32_bf16 v[4:7], v[198:201], v[186:189], v[4:7]
	v_mfma_f32_16x16x32_bf16 v[0:3], v[206:209], v[186:189], v[0:3]
	s_setprio 0
	s_add_i32 s49, 0, 0x18000
	v_add_u32_e32 v142, s49, v170
	s_barrier
	ds_read_b128 v[130:133], v142
	ds_read_b128 v[134:137], v142 offset:1024
	ds_read_b128 v[138:141], v142 offset:2048
	ds_read_b128 v[142:145], v142 offset:3072
	s_add_u32 s30, s30, 0x40000
	s_addc_u32 s31, s31, 0
	s_mov_b32 m0, s42
	ds_read_b128 v[154:157], v172 offset:32768
	ds_read_b128 v[158:161], v172 offset:33792
	ds_read_b128 v[162:165], v172 offset:34816
	ds_read_b128 v[166:169], v172 offset:35840
	ds_read_b128 v[174:177], v172 offset:36864
	ds_read_b128 v[178:181], v172 offset:37888
	ds_read_b128 v[182:185], v172 offset:38912
	ds_read_b128 v[186:189], v172 offset:39936
	global_load_lds_dwordx4 v48, s[30:31]
	v_lshl_add_u64 v[190:191], s[30:31], 0, v[146:147]
	s_mov_b32 m0, s43
	s_nop 0
	global_load_lds_dwordx4 v[190:191], off
	s_waitcnt lgkmcnt(8)
	s_barrier
	s_waitcnt lgkmcnt(0)
	s_setprio 1
	s_waitcnt lgkmcnt(0)
	v_mfma_f32_16x16x32_bf16 v[126:129], v[130:133], v[154:157], v[126:129]
	v_mfma_f32_16x16x32_bf16 v[122:125], v[138:141], v[154:157], v[122:125]
	v_mfma_f32_16x16x32_bf16 v[114:117], v[130:133], v[162:165], v[114:117]
	v_mfma_f32_16x16x32_bf16 v[106:109], v[138:141], v[162:165], v[106:109]
	v_mfma_f32_16x16x32_bf16 v[94:97], v[130:133], v[174:177], v[94:97]
	v_mfma_f32_16x16x32_bf16 v[90:93], v[138:141], v[174:177], v[90:93]
	v_mfma_f32_16x16x32_bf16 v[82:85], v[130:133], v[182:185], v[82:85]
	v_mfma_f32_16x16x32_bf16 v[74:77], v[138:141], v[182:185], v[74:77]
	v_mfma_f32_16x16x32_bf16 v[126:129], v[134:137], v[158:161], v[126:129]
	v_mfma_f32_16x16x32_bf16 v[122:125], v[142:145], v[158:161], v[122:125]
	v_mfma_f32_16x16x32_bf16 v[114:117], v[134:137], v[166:169], v[114:117]
	v_mfma_f32_16x16x32_bf16 v[106:109], v[142:145], v[166:169], v[106:109]
	v_mfma_f32_16x16x32_bf16 v[94:97], v[134:137], v[178:181], v[94:97]
	v_mfma_f32_16x16x32_bf16 v[90:93], v[142:145], v[178:181], v[90:93]
	v_mfma_f32_16x16x32_bf16 v[82:85], v[134:137], v[186:189], v[82:85]
	v_mfma_f32_16x16x32_bf16 v[74:77], v[142:145], v[186:189], v[74:77]
	s_setprio 0
	s_barrier
	s_add_i32 s30, 0, 0x1c000
	s_add_i32 s31, s49, s35
	v_add_u32_e32 v173, s30, v170
	v_lshl_add_u64 v[210:211], v[210:211], 0, s[66:67]
	s_mov_b32 m0, s31
	ds_read_b128 v[190:193], v173
	ds_read_b128 v[198:201], v173 offset:1024
	ds_read_b128 v[202:205], v173 offset:2048
	ds_read_b128 v[206:209], v173 offset:3072
	global_load_lds_dwordx4 v[210:211], off
	v_lshl_add_u64 v[210:211], v[212:213], 0, s[66:67]
	s_add_i32 m0, s31, 0x2000
	s_nop 0
	global_load_lds_dwordx4 v[210:211], off
	s_barrier
	s_waitcnt lgkmcnt(0)
	s_setprio 1
	s_waitcnt lgkmcnt(0)
	v_mfma_f32_16x16x32_bf16 v[118:121], v[190:193], v[154:157], v[118:121]
	v_mfma_f32_16x16x32_bf16 v[110:113], v[202:205], v[154:157], v[110:113]
	v_mfma_f32_16x16x32_bf16 v[102:105], v[190:193], v[162:165], v[102:105]
	v_mfma_f32_16x16x32_bf16 v[98:101], v[202:205], v[162:165], v[98:101]
	v_mfma_f32_16x16x32_bf16 v[86:89], v[190:193], v[174:177], v[86:89]
	v_mfma_f32_16x16x32_bf16 v[78:81], v[202:205], v[174:177], v[78:81]
	v_mfma_f32_16x16x32_bf16 v[70:73], v[190:193], v[182:185], v[70:73]
	v_mfma_f32_16x16x32_bf16 v[66:69], v[202:205], v[182:185], v[66:69]
	v_mfma_f32_16x16x32_bf16 v[118:121], v[198:201], v[158:161], v[118:121]
	v_mfma_f32_16x16x32_bf16 v[110:113], v[206:209], v[158:161], v[110:113]
	v_mfma_f32_16x16x32_bf16 v[102:105], v[198:201], v[166:169], v[102:105]
	v_mfma_f32_16x16x32_bf16 v[98:101], v[206:209], v[166:169], v[98:101]
	v_mfma_f32_16x16x32_bf16 v[86:89], v[198:201], v[178:181], v[86:89]
	v_mfma_f32_16x16x32_bf16 v[78:81], v[206:209], v[178:181], v[78:81]
	v_mfma_f32_16x16x32_bf16 v[70:73], v[198:201], v[186:189], v[70:73]
	v_mfma_f32_16x16x32_bf16 v[66:69], v[206:209], v[186:189], v[66:69]
	s_setprio 0
	s_mov_b32 m0, s46
	v_lshl_add_u64 v[210:211], v[214:215], 0, s[66:67]
	s_barrier
	ds_read_b128 v[154:157], v172 offset:49152
	ds_read_b128 v[158:161], v172 offset:50176
	ds_read_b128 v[162:165], v172 offset:51200
	ds_read_b128 v[166:169], v172 offset:52224
	ds_read_b128 v[174:177], v172 offset:53248
	ds_read_b128 v[178:181], v172 offset:54272
	ds_read_b128 v[182:185], v172 offset:55296
	ds_read_b128 v[186:189], v172 offset:56320
	global_load_lds_dwordx4 v[210:211], off
	v_lshl_add_u64 v[210:211], v[216:217], 0, s[66:67]
	s_mov_b32 m0, s47
	s_nop 0
	global_load_lds_dwordx4 v[210:211], off
	s_barrier
	s_waitcnt lgkmcnt(0)
	s_setprio 1
	s_waitcnt lgkmcnt(0)
	v_mfma_f32_16x16x32_bf16 v[62:65], v[130:133], v[154:157], v[62:65]
	v_mfma_f32_16x16x32_bf16 v[58:61], v[138:141], v[154:157], v[58:61]
	v_mfma_f32_16x16x32_bf16 v[50:53], v[130:133], v[162:165], v[50:53]
	v_mfma_f32_16x16x32_bf16 v[40:43], v[138:141], v[162:165], v[40:43]
	v_mfma_f32_16x16x32_bf16 v[32:35], v[130:133], v[174:177], v[32:35]
	v_mfma_f32_16x16x32_bf16 v[24:27], v[138:141], v[174:177], v[24:27]
	v_mfma_f32_16x16x32_bf16 v[16:19], v[130:133], v[182:185], v[16:19]
	v_mfma_f32_16x16x32_bf16 v[8:11], v[138:141], v[182:185], v[8:11]
	v_mfma_f32_16x16x32_bf16 v[62:65], v[134:137], v[158:161], v[62:65]
	v_mfma_f32_16x16x32_bf16 v[58:61], v[142:145], v[158:161], v[58:61]
	v_mfma_f32_16x16x32_bf16 v[50:53], v[134:137], v[166:169], v[50:53]
	v_mfma_f32_16x16x32_bf16 v[40:43], v[142:145], v[166:169], v[40:43]
	v_mfma_f32_16x16x32_bf16 v[32:35], v[134:137], v[178:181], v[32:35]
	v_mfma_f32_16x16x32_bf16 v[24:27], v[142:145], v[178:181], v[24:27]
	v_mfma_f32_16x16x32_bf16 v[16:19], v[134:137], v[186:189], v[16:19]
	v_mfma_f32_16x16x32_bf16 v[8:11], v[142:145], v[186:189], v[8:11]
	s_setprio 0
	s_barrier
	s_add_u32 s28, s28, 0x40080
	s_addc_u32 s29, s29, 0
	s_add_i32 s30, s30, s35
	s_mov_b32 m0, s30
	s_nop 0
	global_load_lds_dwordx4 v48, s[28:29]
	v_lshl_add_u64 v[130:131], s[28:29], 0, v[146:147]
	s_add_i32 m0, s30, 0x2000
	s_nop 0
	global_load_lds_dwordx4 v[130:131], off
	s_waitcnt vmcnt(6)
	s_barrier
	s_setprio 1
	v_mfma_f32_16x16x32_bf16 v[54:57], v[190:193], v[154:157], v[54:57]
	v_mfma_f32_16x16x32_bf16 v[44:47], v[202:205], v[154:157], v[44:47]
	v_mfma_f32_16x16x32_bf16 v[36:39], v[190:193], v[162:165], v[36:39]
	v_mfma_f32_16x16x32_bf16 v[28:31], v[202:205], v[162:165], v[28:31]
	v_mfma_f32_16x16x32_bf16 v[20:23], v[190:193], v[174:177], v[20:23]
	v_mfma_f32_16x16x32_bf16 v[12:15], v[202:205], v[174:177], v[12:15]
	v_mfma_f32_16x16x32_bf16 v[4:7], v[190:193], v[182:185], v[4:7]
	v_mfma_f32_16x16x32_bf16 v[0:3], v[202:205], v[182:185], v[0:3]
	v_mfma_f32_16x16x32_bf16 v[54:57], v[198:201], v[158:161], v[54:57]
	v_mfma_f32_16x16x32_bf16 v[44:47], v[206:209], v[158:161], v[44:47]
	v_mfma_f32_16x16x32_bf16 v[36:39], v[198:201], v[166:169], v[36:39]
	v_mfma_f32_16x16x32_bf16 v[28:31], v[206:209], v[166:169], v[28:31]
	v_mfma_f32_16x16x32_bf16 v[20:23], v[198:201], v[178:181], v[20:23]
	v_mfma_f32_16x16x32_bf16 v[12:15], v[206:209], v[178:181], v[12:15]
	v_mfma_f32_16x16x32_bf16 v[4:7], v[198:201], v[186:189], v[4:7]
	v_mfma_f32_16x16x32_bf16 v[0:3], v[206:209], v[186:189], v[0:3]
	s_setprio 0
	s_add_i32 s25, s25, 2
	s_add_u32 s26, s26, 0x100
	s_addc_u32 s27, s27, 0
	s_add_u32 s15, s15, 0x100
	s_addc_u32 s17, s17, 0
	s_cmp_gt_u32 s25, 13
	s_barrier
	s_cbranch_scc0 .LBB0_1202
	s_mul_hi_i32 s15, s24, 0x38e38e39
	s_lshr_b32 s17, s15, 31
	s_ashr_i32 s15, s15, 1
	s_add_i32 s15, s15, s17
	s_mul_i32 s17, s15, -9
	s_sub_i32 s25, 0, s24
	s_cmp_eq_u32 s17, s25
	s_mov_b64 s[26:27], 0x30000
	s_cbranch_scc1 .LBB0_1198
	s_mul_hi_i32 s27, s15, 0x1800
	s_mul_i32 s26, s15, 0x1800
	s_branch .LBB0_1198

.LBB0_1219:
	s_add_u32 s26, s24, 0xfffc0080
	s_addc_u32 s27, s25, -1
	s_add_i32 s31, 0, 0x10000
	v_add_u32_e32 v142, s31, v208
	ds_read_b128 v[130:133], v142
	ds_read_b128 v[134:137], v142 offset:1024
	ds_read_b128 v[138:141], v142 offset:2048
	ds_read_b128 v[142:145], v142 offset:3072
	s_cmp_eq_u32 s30, 12
	s_cselect_b32 s29, s19, s27
	s_cselect_b32 s28, s18, s26
	s_cselect_b32 s27, s21, s17
	s_cselect_b32 s26, s20, s15
	s_add_i32 m0, s41, 0xc000
	ds_read_b128 v[146:149], v210
	ds_read_b128 v[150:153], v210 offset:1024
	ds_read_b128 v[154:157], v210 offset:2048
	ds_read_b128 v[158:161], v210 offset:3072
	ds_read_b128 v[162:165], v210 offset:4096
	ds_read_b128 v[166:169], v210 offset:5120
	ds_read_b128 v[170:173], v210 offset:6144
	ds_read_b128 v[174:177], v210 offset:7168
	global_load_lds_dwordx4 v200, s[24:25]
	s_add_i32 m0, s41, 0xe000
	s_nop 0
	global_load_lds_dwordx4 v202, s[24:25]
	s_waitcnt lgkmcnt(8)
	s_barrier
	s_waitcnt lgkmcnt(0)
	s_setprio 1
	s_waitcnt lgkmcnt(0)
	v_mfma_f32_16x16x32_bf16 v[126:129], v[130:133], v[146:149], v[126:129]
	v_mfma_f32_16x16x32_bf16 v[122:125], v[138:141], v[146:149], v[122:125]
	v_mfma_f32_16x16x32_bf16 v[118:121], v[130:133], v[154:157], v[118:121]
	v_mfma_f32_16x16x32_bf16 v[106:109], v[138:141], v[154:157], v[106:109]
	v_mfma_f32_16x16x32_bf16 v[94:97], v[130:133], v[162:165], v[94:97]
	v_mfma_f32_16x16x32_bf16 v[90:93], v[138:141], v[162:165], v[90:93]
	v_mfma_f32_16x16x32_bf16 v[86:89], v[130:133], v[170:173], v[86:89]
	v_mfma_f32_16x16x32_bf16 v[74:77], v[138:141], v[170:173], v[74:77]
	v_mfma_f32_16x16x32_bf16 v[126:129], v[134:137], v[150:153], v[126:129]
	v_mfma_f32_16x16x32_bf16 v[122:125], v[142:145], v[150:153], v[122:125]
	v_mfma_f32_16x16x32_bf16 v[118:121], v[134:137], v[158:161], v[118:121]
	v_mfma_f32_16x16x32_bf16 v[106:109], v[142:145], v[158:161], v[106:109]
	v_mfma_f32_16x16x32_bf16 v[94:97], v[134:137], v[166:169], v[94:97]
	v_mfma_f32_16x16x32_bf16 v[90:93], v[142:145], v[166:169], v[90:93]
	v_mfma_f32_16x16x32_bf16 v[86:89], v[134:137], v[174:177], v[86:89]
	v_mfma_f32_16x16x32_bf16 v[74:77], v[142:145], v[174:177], v[74:77]
	s_setprio 0
	s_barrier
	s_add_i32 s50, 0, 0x14000
	s_add_i32 s31, s31, s40
	v_add_u32_e32 v204, s50, v208
	v_lshl_add_u64 v[212:213], s[26:27], 0, v[48:49]
	s_mov_b32 m0, s31
	ds_read_b128 v[178:181], v204
	ds_read_b128 v[182:185], v204 offset:1024
	ds_read_b128 v[186:189], v204 offset:2048
	ds_read_b128 v[204:207], v204 offset:3072
	global_load_lds_dwordx4 v[212:213], off
	v_lshl_add_u64 v[214:215], s[26:27], 0, v[190:191]
	s_add_i32 m0, s31, 0x2000
	s_nop 0
	global_load_lds_dwordx4 v[214:215], off
	s_barrier
	s_waitcnt lgkmcnt(0)
	s_setprio 1
	s_waitcnt lgkmcnt(0)
	v_mfma_f32_16x16x32_bf16 v[114:117], v[178:181], v[146:149], v[114:117]
	v_mfma_f32_16x16x32_bf16 v[110:113], v[186:189], v[146:149], v[110:113]
	v_mfma_f32_16x16x32_bf16 v[102:105], v[178:181], v[154:157], v[102:105]
	v_mfma_f32_16x16x32_bf16 v[98:101], v[186:189], v[154:157], v[98:101]
	v_mfma_f32_16x16x32_bf16 v[82:85], v[178:181], v[162:165], v[82:85]
	v_mfma_f32_16x16x32_bf16 v[78:81], v[186:189], v[162:165], v[78:81]
	v_mfma_f32_16x16x32_bf16 v[70:73], v[178:181], v[170:173], v[70:73]
	v_mfma_f32_16x16x32_bf16 v[66:69], v[186:189], v[170:173], v[66:69]
	v_mfma_f32_16x16x32_bf16 v[114:117], v[182:185], v[150:153], v[114:117]
	v_mfma_f32_16x16x32_bf16 v[110:113], v[204:207], v[150:153], v[110:113]
	v_mfma_f32_16x16x32_bf16 v[102:105], v[182:185], v[158:161], v[102:105]
	v_mfma_f32_16x16x32_bf16 v[98:101], v[204:207], v[158:161], v[98:101]
	v_mfma_f32_16x16x32_bf16 v[82:85], v[182:185], v[166:169], v[82:85]
	v_mfma_f32_16x16x32_bf16 v[78:81], v[204:207], v[166:169], v[78:81]
	v_mfma_f32_16x16x32_bf16 v[70:73], v[182:185], v[174:177], v[70:73]
	v_mfma_f32_16x16x32_bf16 v[66:69], v[204:207], v[174:177], v[66:69]
	s_setprio 0
	s_mov_b32 m0, s41
	v_lshl_add_u64 v[216:217], s[28:29], 0, v[48:49]
	s_barrier
	ds_read_b128 v[146:149], v210 offset:16384
	ds_read_b128 v[150:153], v210 offset:17408
	ds_read_b128 v[154:157], v210 offset:18432
	ds_read_b128 v[158:161], v210 offset:19456
	ds_read_b128 v[162:165], v210 offset:20480
	ds_read_b128 v[166:169], v210 offset:21504
	ds_read_b128 v[170:173], v210 offset:22528
	ds_read_b128 v[174:177], v210 offset:23552
	global_load_lds_dwordx4 v[216:217], off
	v_lshl_add_u64 v[218:219], s[28:29], 0, v[190:191]
	s_mov_b32 m0, s42
	s_nop 0
	global_load_lds_dwordx4 v[218:219], off
	s_barrier
	s_waitcnt lgkmcnt(0)
	s_setprio 1
	s_waitcnt lgkmcnt(0)
	v_mfma_f32_16x16x32_bf16 v[62:65], v[130:133], v[146:149], v[62:65]
	v_mfma_f32_16x16x32_bf16 v[58:61], v[138:141], v[146:149], v[58:61]
	v_mfma_f32_16x16x32_bf16 v[54:57], v[130:133], v[154:157], v[54:57]
	v_mfma_f32_16x16x32_bf16 v[40:43], v[138:141], v[154:157], v[40:43]
	v_mfma_f32_16x16x32_bf16 v[36:39], v[130:133], v[162:165], v[36:39]
	v_mfma_f32_16x16x32_bf16 v[24:27], v[138:141], v[162:165], v[24:27]
	v_mfma_f32_16x16x32_bf16 v[20:23], v[130:133], v[170:173], v[20:23]
	v_mfma_f32_16x16x32_bf16 v[8:11], v[138:141], v[170:173], v[8:11]
	v_mfma_f32_16x16x32_bf16 v[62:65], v[134:137], v[150:153], v[62:65]
	v_mfma_f32_16x16x32_bf16 v[58:61], v[142:145], v[150:153], v[58:61]
	v_mfma_f32_16x16x32_bf16 v[54:57], v[134:137], v[158:161], v[54:57]
	v_mfma_f32_16x16x32_bf16 v[40:43], v[142:145], v[158:161], v[40:43]
	v_mfma_f32_16x16x32_bf16 v[36:39], v[134:137], v[166:169], v[36:39]
	v_mfma_f32_16x16x32_bf16 v[24:27], v[142:145], v[166:169], v[24:27]
	v_mfma_f32_16x16x32_bf16 v[20:23], v[134:137], v[174:177], v[20:23]
	v_mfma_f32_16x16x32_bf16 v[8:11], v[142:145], v[174:177], v[8:11]
	s_setprio 0
	s_barrier
	s_add_u32 s34, s26, 0x40000
	s_addc_u32 s35, s27, 0
	s_add_i32 s31, s50, s40
	s_mov_b32 m0, s31
	s_nop 0
	global_load_lds_dwordx4 v48, s[34:35]
	s_add_i32 m0, s31, 0x2000
	s_nop 0
	global_load_lds_dwordx4 v190, s[34:35]
	s_waitcnt vmcnt(6)
	s_barrier
	s_setprio 1
	v_mfma_f32_16x16x32_bf16 v[50:53], v[178:181], v[146:149], v[50:53]
	v_mfma_f32_16x16x32_bf16 v[44:47], v[186:189], v[146:149], v[44:47]
	v_mfma_f32_16x16x32_bf16 v[32:35], v[178:181], v[154:157], v[32:35]
	v_mfma_f32_16x16x32_bf16 v[28:31], v[186:189], v[154:157], v[28:31]
	v_mfma_f32_16x16x32_bf16 v[16:19], v[178:181], v[162:165], v[16:19]
	v_mfma_f32_16x16x32_bf16 v[12:15], v[186:189], v[162:165], v[12:15]
	v_mfma_f32_16x16x32_bf16 v[4:7], v[178:181], v[170:173], v[4:7]
	v_mfma_f32_16x16x32_bf16 v[0:3], v[186:189], v[170:173], v[0:3]
	v_mfma_f32_16x16x32_bf16 v[50:53], v[182:185], v[150:153], v[50:53]
	v_mfma_f32_16x16x32_bf16 v[44:47], v[204:207], v[150:153], v[44:47]
	v_mfma_f32_16x16x32_bf16 v[32:35], v[182:185], v[158:161], v[32:35]
	v_mfma_f32_16x16x32_bf16 v[28:31], v[204:207], v[158:161], v[28:31]
	v_mfma_f32_16x16x32_bf16 v[16:19], v[182:185], v[166:169], v[16:19]
	v_mfma_f32_16x16x32_bf16 v[12:15], v[204:207], v[166:169], v[12:15]
	v_mfma_f32_16x16x32_bf16 v[4:7], v[182:185], v[174:177], v[4:7]
	v_mfma_f32_16x16x32_bf16 v[0:3], v[204:207], v[174:177], v[0:3]
	s_setprio 0
	s_add_i32 s31, 0, 0x18000
	v_add_u32_e32 v142, s31, v208
	s_barrier
	ds_read_b128 v[130:133], v142
	ds_read_b128 v[134:137], v142 offset:1024
	ds_read_b128 v[138:141], v142 offset:2048
	ds_read_b128 v[142:145], v142 offset:3072
	s_add_u32 s28, s28, 0x40000
	s_addc_u32 s29, s29, 0
	s_mov_b32 m0, s43
	ds_read_b128 v[146:149], v210 offset:32768
	ds_read_b128 v[150:153], v210 offset:33792
	ds_read_b128 v[154:157], v210 offset:34816
	ds_read_b128 v[158:161], v210 offset:35840
	ds_read_b128 v[162:165], v210 offset:36864
	ds_read_b128 v[166:169], v210 offset:37888
	ds_read_b128 v[170:173], v210 offset:38912
	ds_read_b128 v[174:177], v210 offset:39936
	global_load_lds_dwordx4 v48, s[28:29]
	s_mov_b32 m0, s44
	s_nop 0
	global_load_lds_dwordx4 v190, s[28:29]
	s_waitcnt lgkmcnt(8)
	s_barrier
	s_waitcnt lgkmcnt(0)
	s_setprio 1
	s_waitcnt lgkmcnt(0)
	v_mfma_f32_16x16x32_bf16 v[126:129], v[130:133], v[146:149], v[126:129]
	v_mfma_f32_16x16x32_bf16 v[122:125], v[138:141], v[146:149], v[122:125]
	v_mfma_f32_16x16x32_bf16 v[118:121], v[130:133], v[154:157], v[118:121]
	v_mfma_f32_16x16x32_bf16 v[106:109], v[138:141], v[154:157], v[106:109]
	v_mfma_f32_16x16x32_bf16 v[94:97], v[130:133], v[162:165], v[94:97]
	v_mfma_f32_16x16x32_bf16 v[90:93], v[138:141], v[162:165], v[90:93]
	v_mfma_f32_16x16x32_bf16 v[86:89], v[130:133], v[170:173], v[86:89]
	v_mfma_f32_16x16x32_bf16 v[74:77], v[138:141], v[170:173], v[74:77]
	v_mfma_f32_16x16x32_bf16 v[126:129], v[134:137], v[150:153], v[126:129]
	v_mfma_f32_16x16x32_bf16 v[122:125], v[142:145], v[150:153], v[122:125]
	v_mfma_f32_16x16x32_bf16 v[118:121], v[134:137], v[158:161], v[118:121]
	v_mfma_f32_16x16x32_bf16 v[106:109], v[142:145], v[158:161], v[106:109]
	v_mfma_f32_16x16x32_bf16 v[94:97], v[134:137], v[166:169], v[94:97]
	v_mfma_f32_16x16x32_bf16 v[90:93], v[142:145], v[166:169], v[90:93]
	v_mfma_f32_16x16x32_bf16 v[86:89], v[134:137], v[174:177], v[86:89]
	v_mfma_f32_16x16x32_bf16 v[74:77], v[142:145], v[174:177], v[74:77]
	s_setprio 0
	s_barrier
	s_add_i32 s28, 0, 0x1c000
	s_add_i32 s29, s31, s40
	v_add_u32_e32 v204, s28, v208
	v_lshl_add_u64 v[212:213], v[212:213], 0, s[66:67]
	s_mov_b32 m0, s29
	ds_read_b128 v[178:181], v204
	ds_read_b128 v[182:185], v204 offset:1024
	ds_read_b128 v[186:189], v204 offset:2048
	ds_read_b128 v[204:207], v204 offset:3072
	global_load_lds_dwordx4 v[212:213], off
	v_lshl_add_u64 v[212:213], v[214:215], 0, s[66:67]
	s_add_i32 m0, s29, 0x2000
	s_nop 0
	global_load_lds_dwordx4 v[212:213], off
	s_barrier
	s_waitcnt lgkmcnt(0)
	s_setprio 1
	s_waitcnt lgkmcnt(0)
	v_mfma_f32_16x16x32_bf16 v[114:117], v[178:181], v[146:149], v[114:117]
	v_mfma_f32_16x16x32_bf16 v[110:113], v[186:189], v[146:149], v[110:113]
	v_mfma_f32_16x16x32_bf16 v[102:105], v[178:181], v[154:157], v[102:105]
	v_mfma_f32_16x16x32_bf16 v[98:101], v[186:189], v[154:157], v[98:101]
	v_mfma_f32_16x16x32_bf16 v[82:85], v[178:181], v[162:165], v[82:85]
	v_mfma_f32_16x16x32_bf16 v[78:81], v[186:189], v[162:165], v[78:81]
	v_mfma_f32_16x16x32_bf16 v[70:73], v[178:181], v[170:173], v[70:73]
	v_mfma_f32_16x16x32_bf16 v[66:69], v[186:189], v[170:173], v[66:69]
	v_mfma_f32_16x16x32_bf16 v[114:117], v[182:185], v[150:153], v[114:117]
	v_mfma_f32_16x16x32_bf16 v[110:113], v[204:207], v[150:153], v[110:113]
	v_mfma_f32_16x16x32_bf16 v[102:105], v[182:185], v[158:161], v[102:105]
	v_mfma_f32_16x16x32_bf16 v[98:101], v[204:207], v[158:161], v[98:101]
	v_mfma_f32_16x16x32_bf16 v[82:85], v[182:185], v[166:169], v[82:85]
	v_mfma_f32_16x16x32_bf16 v[78:81], v[204:207], v[166:169], v[78:81]
	v_mfma_f32_16x16x32_bf16 v[70:73], v[182:185], v[174:177], v[70:73]
	v_mfma_f32_16x16x32_bf16 v[66:69], v[204:207], v[174:177], v[66:69]
	s_setprio 0
	s_mov_b32 m0, s47
	v_lshl_add_u64 v[212:213], v[216:217], 0, s[66:67]
	s_barrier
	ds_read_b128 v[146:149], v210 offset:49152
	ds_read_b128 v[150:153], v210 offset:50176
	ds_read_b128 v[154:157], v210 offset:51200
	ds_read_b128 v[158:161], v210 offset:52224
	ds_read_b128 v[162:165], v210 offset:53248
	ds_read_b128 v[166:169], v210 offset:54272
	ds_read_b128 v[170:173], v210 offset:55296
	ds_read_b128 v[174:177], v210 offset:56320
	global_load_lds_dwordx4 v[212:213], off
	v_lshl_add_u64 v[212:213], v[218:219], 0, s[66:67]
	s_mov_b32 m0, s48
	s_nop 0
	global_load_lds_dwordx4 v[212:213], off
	s_barrier
	s_waitcnt lgkmcnt(0)
	s_setprio 1
	s_waitcnt lgkmcnt(0)
	v_mfma_f32_16x16x32_bf16 v[62:65], v[130:133], v[146:149], v[62:65]
	v_mfma_f32_16x16x32_bf16 v[58:61], v[138:141], v[146:149], v[58:61]
	v_mfma_f32_16x16x32_bf16 v[54:57], v[130:133], v[154:157], v[54:57]
	v_mfma_f32_16x16x32_bf16 v[40:43], v[138:141], v[154:157], v[40:43]
	v_mfma_f32_16x16x32_bf16 v[36:39], v[130:133], v[162:165], v[36:39]
	v_mfma_f32_16x16x32_bf16 v[24:27], v[138:141], v[162:165], v[24:27]
	v_mfma_f32_16x16x32_bf16 v[20:23], v[130:133], v[170:173], v[20:23]
	v_mfma_f32_16x16x32_bf16 v[8:11], v[138:141], v[170:173], v[8:11]
	v_mfma_f32_16x16x32_bf16 v[62:65], v[134:137], v[150:153], v[62:65]
	v_mfma_f32_16x16x32_bf16 v[58:61], v[142:145], v[150:153], v[58:61]
	v_mfma_f32_16x16x32_bf16 v[54:57], v[134:137], v[158:161], v[54:57]
	v_mfma_f32_16x16x32_bf16 v[40:43], v[142:145], v[158:161], v[40:43]
	v_mfma_f32_16x16x32_bf16 v[36:39], v[134:137], v[166:169], v[36:39]
	v_mfma_f32_16x16x32_bf16 v[24:27], v[142:145], v[166:169], v[24:27]
	v_mfma_f32_16x16x32_bf16 v[20:23], v[134:137], v[174:177], v[20:23]
	v_mfma_f32_16x16x32_bf16 v[8:11], v[142:145], v[174:177], v[8:11]
	s_setprio 0
	s_barrier
	s_add_u32 s26, s26, 0x40080
	s_addc_u32 s27, s27, 0
	s_add_i32 s28, s28, s40
	s_mov_b32 m0, s28
	s_nop 0
	global_load_lds_dwordx4 v48, s[26:27]
	s_add_i32 m0, s28, 0x2000
	s_nop 0
	global_load_lds_dwordx4 v190, s[26:27]
	s_waitcnt vmcnt(6)
	s_barrier
	s_setprio 1
	v_mfma_f32_16x16x32_bf16 v[50:53], v[178:181], v[146:149], v[50:53]
	v_mfma_f32_16x16x32_bf16 v[44:47], v[186:189], v[146:149], v[44:47]
	v_mfma_f32_16x16x32_bf16 v[32:35], v[178:181], v[154:157], v[32:35]
	v_mfma_f32_16x16x32_bf16 v[28:31], v[186:189], v[154:157], v[28:31]
	v_mfma_f32_16x16x32_bf16 v[16:19], v[178:181], v[162:165], v[16:19]
	v_mfma_f32_16x16x32_bf16 v[12:15], v[186:189], v[162:165], v[12:15]
	v_mfma_f32_16x16x32_bf16 v[4:7], v[178:181], v[170:173], v[4:7]
	v_mfma_f32_16x16x32_bf16 v[0:3], v[186:189], v[170:173], v[0:3]
	v_mfma_f32_16x16x32_bf16 v[50:53], v[182:185], v[150:153], v[50:53]
	v_mfma_f32_16x16x32_bf16 v[44:47], v[204:207], v[150:153], v[44:47]
	v_mfma_f32_16x16x32_bf16 v[32:35], v[182:185], v[158:161], v[32:35]
	v_mfma_f32_16x16x32_bf16 v[28:31], v[204:207], v[158:161], v[28:31]
	v_mfma_f32_16x16x32_bf16 v[16:19], v[182:185], v[166:169], v[16:19]
	v_mfma_f32_16x16x32_bf16 v[12:15], v[204:207], v[166:169], v[12:15]
	v_mfma_f32_16x16x32_bf16 v[4:7], v[182:185], v[174:177], v[4:7]
	v_mfma_f32_16x16x32_bf16 v[0:3], v[204:207], v[174:177], v[0:3]
	s_setprio 0
	s_add_i32 s30, s30, 2
	s_add_u32 s24, s24, 0x100
	s_addc_u32 s25, s25, 0
	s_add_u32 s15, s15, 0x100
	s_addc_u32 s17, s17, 0
	s_cmp_gt_u32 s30, 13
	s_barrier
	s_cbranch_scc0 .LBB0_1219
	s_mul_hi_i32 s15, s22, 0x38e38e39
	s_lshr_b32 s17, s15, 31
	s_ashr_i32 s15, s15, 1
	s_add_i32 s24, s15, s17
	s_mul_i32 s15, s24, -9
	s_add_i32 s28, s15, s22
	s_cmp_eq_u32 s28, 0
	s_cselect_b64 s[26:27], -1, 0
	s_ashr_i32 s25, s24, 31
	s_cmp_lg_u32 s28, 0
	s_cbranch_scc0 .LBB0_1222
	s_ashr_i32 s29, s28, 31
	s_lshl_b64 s[28:29], s[28:29], 18
	s_lshl_b64 s[30:31], s[24:25], 21
	s_add_u32 s15, s28, s30
	s_addc_u32 s17, s29, s31
	s_add_u32 s28, s15, 0xfffc0000
	s_addc_u32 s29, s17, -1
	s_mov_b64 s[30:31], s[6:7]
	s_cbranch_execnz .LBB0_1215
	s_branch .LBB0_1214

.LBB0_1356:
	s_add_u32 s28, s26, 0xfffc0080
	s_addc_u32 s29, s27, -1
	s_add_i32 s46, 0, 0x10000
	v_add_u32_e32 v140, s46, v143
	ds_read_b128 v[146:149], v140
	ds_read_b128 v[150:153], v140 offset:1024
	ds_read_b128 v[154:157], v140 offset:2048
	ds_read_b128 v[158:161], v140 offset:3072
	s_cmp_eq_u32 s45, 12
	s_cselect_b32 s31, s19, s29
	s_cselect_b32 s30, s18, s28
	s_cselect_b32 s29, s21, s17
	s_cselect_b32 s28, s20, s15
	s_add_i32 m0, s23, 0xc000
	ds_read_b128 v[162:165], v145
	ds_read_b128 v[166:169], v145 offset:1024
	ds_read_b128 v[170:173], v145 offset:2048
	ds_read_b128 v[174:177], v145 offset:3072
	ds_read_b128 v[178:181], v145 offset:4096
	ds_read_b128 v[182:185], v145 offset:5120
	ds_read_b128 v[186:189], v145 offset:6144
	ds_read_b128 v[190:193], v145 offset:7168
	global_load_lds_dwordx4 v136, s[26:27]
	s_add_i32 m0, s23, 0xe000
	s_nop 0
	global_load_lds_dwordx4 v138, s[26:27]
	s_waitcnt lgkmcnt(8)
	s_barrier
	s_waitcnt lgkmcnt(0)
	s_setprio 1
	s_waitcnt lgkmcnt(0)
	v_mfma_f32_16x16x32_bf16 v[126:129], v[146:149], v[162:165], v[126:129]
	v_mfma_f32_16x16x32_bf16 v[118:121], v[154:157], v[162:165], v[118:121]
	v_mfma_f32_16x16x32_bf16 v[110:113], v[146:149], v[170:173], v[110:113]
	v_mfma_f32_16x16x32_bf16 v[102:105], v[154:157], v[170:173], v[102:105]
	v_mfma_f32_16x16x32_bf16 v[94:97], v[146:149], v[178:181], v[94:97]
	v_mfma_f32_16x16x32_bf16 v[86:89], v[154:157], v[178:181], v[86:89]
	v_mfma_f32_16x16x32_bf16 v[78:81], v[146:149], v[186:189], v[78:81]
	v_mfma_f32_16x16x32_bf16 v[70:73], v[154:157], v[186:189], v[70:73]
	v_mfma_f32_16x16x32_bf16 v[126:129], v[150:153], v[166:169], v[126:129]
	v_mfma_f32_16x16x32_bf16 v[118:121], v[158:161], v[166:169], v[118:121]
	v_mfma_f32_16x16x32_bf16 v[110:113], v[150:153], v[174:177], v[110:113]
	v_mfma_f32_16x16x32_bf16 v[102:105], v[158:161], v[174:177], v[102:105]
	v_mfma_f32_16x16x32_bf16 v[94:97], v[150:153], v[182:185], v[94:97]
	v_mfma_f32_16x16x32_bf16 v[86:89], v[158:161], v[182:185], v[86:89]
	v_mfma_f32_16x16x32_bf16 v[78:81], v[150:153], v[190:193], v[78:81]
	v_mfma_f32_16x16x32_bf16 v[70:73], v[158:161], v[190:193], v[70:73]
	s_setprio 0
	s_barrier
	s_add_i32 s48, 0, 0x14000
	v_add_u32_e32 v140, s48, v143
	s_add_i32 s46, s46, s37
	ds_read_b128 v[198:201], v140
	ds_read_b128 v[202:205], v140 offset:1024
	ds_read_b128 v[206:209], v140 offset:2048
	ds_read_b128 v[210:213], v140 offset:3072
	v_lshl_add_u64 v[140:141], s[28:29], 0, v[48:49]
	s_mov_b32 m0, s46
	v_lshl_add_u64 v[214:215], s[28:29], 0, v[130:131]
	global_load_lds_dwordx4 v[140:141], off
	s_add_i32 m0, s46, 0x2000
	s_nop 0
	global_load_lds_dwordx4 v[214:215], off
	s_barrier
	s_waitcnt lgkmcnt(0)
	s_setprio 1
	s_waitcnt lgkmcnt(0)
	v_mfma_f32_16x16x32_bf16 v[122:125], v[198:201], v[162:165], v[122:125]
	v_mfma_f32_16x16x32_bf16 v[114:117], v[206:209], v[162:165], v[114:117]
	v_mfma_f32_16x16x32_bf16 v[106:109], v[198:201], v[170:173], v[106:109]
	v_mfma_f32_16x16x32_bf16 v[98:101], v[206:209], v[170:173], v[98:101]
	v_mfma_f32_16x16x32_bf16 v[90:93], v[198:201], v[178:181], v[90:93]
	v_mfma_f32_16x16x32_bf16 v[82:85], v[206:209], v[178:181], v[82:85]
	v_mfma_f32_16x16x32_bf16 v[74:77], v[198:201], v[186:189], v[74:77]
	v_mfma_f32_16x16x32_bf16 v[66:69], v[206:209], v[186:189], v[66:69]
	v_mfma_f32_16x16x32_bf16 v[122:125], v[202:205], v[166:169], v[122:125]
	v_mfma_f32_16x16x32_bf16 v[114:117], v[210:213], v[166:169], v[114:117]
	v_mfma_f32_16x16x32_bf16 v[106:109], v[202:205], v[174:177], v[106:109]
	v_mfma_f32_16x16x32_bf16 v[98:101], v[210:213], v[174:177], v[98:101]
	v_mfma_f32_16x16x32_bf16 v[90:93], v[202:205], v[182:185], v[90:93]
	v_mfma_f32_16x16x32_bf16 v[82:85], v[210:213], v[182:185], v[82:85]
	v_mfma_f32_16x16x32_bf16 v[74:77], v[202:205], v[190:193], v[74:77]
	v_mfma_f32_16x16x32_bf16 v[66:69], v[210:213], v[190:193], v[66:69]
	s_setprio 0
	s_mov_b32 m0, s23
	v_lshl_add_u64 v[216:217], s[30:31], 0, v[134:135]
	s_barrier
	ds_read_b128 v[162:165], v145 offset:16384
	ds_read_b128 v[166:169], v145 offset:17408
	ds_read_b128 v[170:173], v145 offset:18432
	ds_read_b128 v[174:177], v145 offset:19456
	ds_read_b128 v[178:181], v145 offset:20480
	ds_read_b128 v[182:185], v145 offset:21504
	ds_read_b128 v[186:189], v145 offset:22528
	ds_read_b128 v[190:193], v145 offset:23552
	global_load_lds_dwordx4 v[216:217], off
	v_lshl_add_u64 v[218:219], s[30:31], 0, v[132:133]
	s_mov_b32 m0, s25
	s_nop 0
	global_load_lds_dwordx4 v[218:219], off
	s_barrier
	s_waitcnt lgkmcnt(0)
	s_setprio 1
	s_waitcnt lgkmcnt(0)
	v_mfma_f32_16x16x32_bf16 v[62:65], v[146:149], v[162:165], v[62:65]
	v_mfma_f32_16x16x32_bf16 v[54:57], v[154:157], v[162:165], v[54:57]
	v_mfma_f32_16x16x32_bf16 v[44:47], v[146:149], v[170:173], v[44:47]
	v_mfma_f32_16x16x32_bf16 v[36:39], v[154:157], v[170:173], v[36:39]
	v_mfma_f32_16x16x32_bf16 v[28:31], v[146:149], v[178:181], v[28:31]
	v_mfma_f32_16x16x32_bf16 v[20:23], v[154:157], v[178:181], v[20:23]
	v_mfma_f32_16x16x32_bf16 v[12:15], v[146:149], v[186:189], v[12:15]
	v_mfma_f32_16x16x32_bf16 v[4:7], v[154:157], v[186:189], v[4:7]
	v_mfma_f32_16x16x32_bf16 v[62:65], v[150:153], v[166:169], v[62:65]
	v_mfma_f32_16x16x32_bf16 v[54:57], v[158:161], v[166:169], v[54:57]
	v_mfma_f32_16x16x32_bf16 v[44:47], v[150:153], v[174:177], v[44:47]
	v_mfma_f32_16x16x32_bf16 v[36:39], v[158:161], v[174:177], v[36:39]
	v_mfma_f32_16x16x32_bf16 v[28:31], v[150:153], v[182:185], v[28:31]
	v_mfma_f32_16x16x32_bf16 v[20:23], v[158:161], v[182:185], v[20:23]
	v_mfma_f32_16x16x32_bf16 v[12:15], v[150:153], v[190:193], v[12:15]
	v_mfma_f32_16x16x32_bf16 v[4:7], v[158:161], v[190:193], v[4:7]
	s_setprio 0
	s_barrier
	s_add_u32 s46, s28, 0x40000
	s_addc_u32 s47, s29, 0
	s_add_i32 s48, s48, s37
	v_lshl_add_u64 v[146:147], s[46:47], 0, v[48:49]
	s_mov_b32 m0, s48
	s_nop 0
	global_load_lds_dwordx4 v[146:147], off
	v_lshl_add_u64 v[146:147], s[46:47], 0, v[130:131]
	s_add_i32 m0, s48, 0x2000
	s_nop 0
	global_load_lds_dwordx4 v[146:147], off
	s_waitcnt vmcnt(6)
	s_barrier
	s_setprio 1
	v_mfma_f32_16x16x32_bf16 v[58:61], v[198:201], v[162:165], v[58:61]
	v_mfma_f32_16x16x32_bf16 v[50:53], v[206:209], v[162:165], v[50:53]
	v_mfma_f32_16x16x32_bf16 v[40:43], v[198:201], v[170:173], v[40:43]
	v_mfma_f32_16x16x32_bf16 v[32:35], v[206:209], v[170:173], v[32:35]
	v_mfma_f32_16x16x32_bf16 v[24:27], v[198:201], v[178:181], v[24:27]
	v_mfma_f32_16x16x32_bf16 v[16:19], v[206:209], v[178:181], v[16:19]
	v_mfma_f32_16x16x32_bf16 v[8:11], v[198:201], v[186:189], v[8:11]
	v_mfma_f32_16x16x32_bf16 v[0:3], v[206:209], v[186:189], v[0:3]
	v_mfma_f32_16x16x32_bf16 v[58:61], v[202:205], v[166:169], v[58:61]
	v_mfma_f32_16x16x32_bf16 v[50:53], v[210:213], v[166:169], v[50:53]
	v_mfma_f32_16x16x32_bf16 v[40:43], v[202:205], v[174:177], v[40:43]
	v_mfma_f32_16x16x32_bf16 v[32:35], v[210:213], v[174:177], v[32:35]
	v_mfma_f32_16x16x32_bf16 v[24:27], v[202:205], v[182:185], v[24:27]
	v_mfma_f32_16x16x32_bf16 v[16:19], v[210:213], v[182:185], v[16:19]
	v_mfma_f32_16x16x32_bf16 v[8:11], v[202:205], v[190:193], v[8:11]
	v_mfma_f32_16x16x32_bf16 v[0:3], v[210:213], v[190:193], v[0:3]
	s_setprio 0
	s_add_i32 s46, 0, 0x18000
	v_add_u32_e32 v158, s46, v143
	s_barrier
	ds_read_b128 v[146:149], v158
	ds_read_b128 v[150:153], v158 offset:1024
	ds_read_b128 v[154:157], v158 offset:2048
	ds_read_b128 v[158:161], v158 offset:3072
	s_add_u32 s30, s30, 0x40000
	s_addc_u32 s31, s31, 0
	s_mov_b32 m0, s40
	ds_read_b128 v[162:165], v145 offset:32768
	ds_read_b128 v[166:169], v145 offset:33792
	ds_read_b128 v[170:173], v145 offset:34816
	ds_read_b128 v[174:177], v145 offset:35840
	ds_read_b128 v[178:181], v145 offset:36864
	ds_read_b128 v[182:185], v145 offset:37888
	ds_read_b128 v[186:189], v145 offset:38912
	ds_read_b128 v[190:193], v145 offset:39936
	global_load_lds_dwordx4 v134, s[30:31]
	s_mov_b32 m0, s41
	s_nop 0
	global_load_lds_dwordx4 v132, s[30:31]
	s_waitcnt lgkmcnt(8)
	s_barrier
	s_waitcnt lgkmcnt(0)
	s_setprio 1
	s_waitcnt lgkmcnt(0)
	v_mfma_f32_16x16x32_bf16 v[126:129], v[146:149], v[162:165], v[126:129]
	v_mfma_f32_16x16x32_bf16 v[118:121], v[154:157], v[162:165], v[118:121]
	v_mfma_f32_16x16x32_bf16 v[110:113], v[146:149], v[170:173], v[110:113]
	v_mfma_f32_16x16x32_bf16 v[102:105], v[154:157], v[170:173], v[102:105]
	v_mfma_f32_16x16x32_bf16 v[94:97], v[146:149], v[178:181], v[94:97]
	v_mfma_f32_16x16x32_bf16 v[86:89], v[154:157], v[178:181], v[86:89]
	v_mfma_f32_16x16x32_bf16 v[78:81], v[146:149], v[186:189], v[78:81]
	v_mfma_f32_16x16x32_bf16 v[70:73], v[154:157], v[186:189], v[70:73]
	v_mfma_f32_16x16x32_bf16 v[126:129], v[150:153], v[166:169], v[126:129]
	v_mfma_f32_16x16x32_bf16 v[118:121], v[158:161], v[166:169], v[118:121]
	v_mfma_f32_16x16x32_bf16 v[110:113], v[150:153], v[174:177], v[110:113]
	v_mfma_f32_16x16x32_bf16 v[102:105], v[158:161], v[174:177], v[102:105]
	v_mfma_f32_16x16x32_bf16 v[94:97], v[150:153], v[182:185], v[94:97]
	v_mfma_f32_16x16x32_bf16 v[86:89], v[158:161], v[182:185], v[86:89]
	v_mfma_f32_16x16x32_bf16 v[78:81], v[150:153], v[190:193], v[78:81]
	v_mfma_f32_16x16x32_bf16 v[70:73], v[158:161], v[190:193], v[70:73]
	s_setprio 0
	s_barrier
	s_add_i32 s30, 0, 0x1c000
	s_add_i32 s31, s46, s37
	v_add_u32_e32 v210, s30, v143
	v_lshl_add_u64 v[140:141], v[140:141], 0, s[66:67]
	s_mov_b32 m0, s31
	ds_read_b128 v[198:201], v210
	ds_read_b128 v[202:205], v210 offset:1024
	ds_read_b128 v[206:209], v210 offset:2048
	ds_read_b128 v[210:213], v210 offset:3072
	global_load_lds_dwordx4 v[140:141], off
	v_lshl_add_u64 v[140:141], v[214:215], 0, s[66:67]
	s_add_i32 m0, s31, 0x2000
	s_nop 0
	global_load_lds_dwordx4 v[140:141], off
	s_barrier
	s_waitcnt lgkmcnt(0)
	s_setprio 1
	s_waitcnt lgkmcnt(0)
	v_mfma_f32_16x16x32_bf16 v[122:125], v[198:201], v[162:165], v[122:125]
	v_mfma_f32_16x16x32_bf16 v[114:117], v[206:209], v[162:165], v[114:117]
	v_mfma_f32_16x16x32_bf16 v[106:109], v[198:201], v[170:173], v[106:109]
	v_mfma_f32_16x16x32_bf16 v[98:101], v[206:209], v[170:173], v[98:101]
	v_mfma_f32_16x16x32_bf16 v[90:93], v[198:201], v[178:181], v[90:93]
	v_mfma_f32_16x16x32_bf16 v[82:85], v[206:209], v[178:181], v[82:85]
	v_mfma_f32_16x16x32_bf16 v[74:77], v[198:201], v[186:189], v[74:77]
	v_mfma_f32_16x16x32_bf16 v[66:69], v[206:209], v[186:189], v[66:69]
	v_mfma_f32_16x16x32_bf16 v[122:125], v[202:205], v[166:169], v[122:125]
	v_mfma_f32_16x16x32_bf16 v[114:117], v[210:213], v[166:169], v[114:117]
	v_mfma_f32_16x16x32_bf16 v[106:109], v[202:205], v[174:177], v[106:109]
	v_mfma_f32_16x16x32_bf16 v[98:101], v[210:213], v[174:177], v[98:101]
	v_mfma_f32_16x16x32_bf16 v[90:93], v[202:205], v[182:185], v[90:93]
	v_mfma_f32_16x16x32_bf16 v[82:85], v[210:213], v[182:185], v[82:85]
	v_mfma_f32_16x16x32_bf16 v[74:77], v[202:205], v[190:193], v[74:77]
	v_mfma_f32_16x16x32_bf16 v[66:69], v[210:213], v[190:193], v[66:69]
	s_setprio 0
	s_mov_b32 m0, s42
	v_lshl_add_u64 v[140:141], v[216:217], 0, s[66:67]
	s_barrier
	ds_read_b128 v[162:165], v145 offset:49152
	ds_read_b128 v[166:169], v145 offset:50176
	ds_read_b128 v[170:173], v145 offset:51200
	ds_read_b128 v[174:177], v145 offset:52224
	ds_read_b128 v[178:181], v145 offset:53248
	ds_read_b128 v[182:185], v145 offset:54272
	ds_read_b128 v[186:189], v145 offset:55296
	ds_read_b128 v[190:193], v145 offset:56320
	global_load_lds_dwordx4 v[140:141], off
	v_lshl_add_u64 v[140:141], v[218:219], 0, s[66:67]
	s_mov_b32 m0, s43
	s_nop 0
	global_load_lds_dwordx4 v[140:141], off
	s_barrier
	s_waitcnt lgkmcnt(0)
	s_setprio 1
	s_waitcnt lgkmcnt(0)
	v_mfma_f32_16x16x32_bf16 v[62:65], v[146:149], v[162:165], v[62:65]
	v_mfma_f32_16x16x32_bf16 v[54:57], v[154:157], v[162:165], v[54:57]
	v_mfma_f32_16x16x32_bf16 v[44:47], v[146:149], v[170:173], v[44:47]
	v_mfma_f32_16x16x32_bf16 v[36:39], v[154:157], v[170:173], v[36:39]
	v_mfma_f32_16x16x32_bf16 v[28:31], v[146:149], v[178:181], v[28:31]
	v_mfma_f32_16x16x32_bf16 v[20:23], v[154:157], v[178:181], v[20:23]
	v_mfma_f32_16x16x32_bf16 v[12:15], v[146:149], v[186:189], v[12:15]
	v_mfma_f32_16x16x32_bf16 v[4:7], v[154:157], v[186:189], v[4:7]
	v_mfma_f32_16x16x32_bf16 v[62:65], v[150:153], v[166:169], v[62:65]
	v_mfma_f32_16x16x32_bf16 v[54:57], v[158:161], v[166:169], v[54:57]
	v_mfma_f32_16x16x32_bf16 v[44:47], v[150:153], v[174:177], v[44:47]
	v_mfma_f32_16x16x32_bf16 v[36:39], v[158:161], v[174:177], v[36:39]
	v_mfma_f32_16x16x32_bf16 v[28:31], v[150:153], v[182:185], v[28:31]
	v_mfma_f32_16x16x32_bf16 v[20:23], v[158:161], v[182:185], v[20:23]
	v_mfma_f32_16x16x32_bf16 v[12:15], v[150:153], v[190:193], v[12:15]
	v_mfma_f32_16x16x32_bf16 v[4:7], v[158:161], v[190:193], v[4:7]
	s_setprio 0
	s_barrier
	s_add_u32 s28, s28, 0x40080
	s_addc_u32 s29, s29, 0
	s_add_i32 s30, s30, s37
	s_mov_b32 m0, s30
	s_nop 0
	global_load_lds_dwordx4 v48, s[28:29]
	s_add_i32 m0, s30, 0x2000
	s_nop 0
	global_load_lds_dwordx4 v130, s[28:29]
	s_waitcnt vmcnt(6)
	s_barrier
	s_setprio 1
	v_mfma_f32_16x16x32_bf16 v[58:61], v[198:201], v[162:165], v[58:61]
	v_mfma_f32_16x16x32_bf16 v[50:53], v[206:209], v[162:165], v[50:53]
	v_mfma_f32_16x16x32_bf16 v[40:43], v[198:201], v[170:173], v[40:43]
	v_mfma_f32_16x16x32_bf16 v[32:35], v[206:209], v[170:173], v[32:35]
	v_mfma_f32_16x16x32_bf16 v[24:27], v[198:201], v[178:181], v[24:27]
	v_mfma_f32_16x16x32_bf16 v[16:19], v[206:209], v[178:181], v[16:19]
	v_mfma_f32_16x16x32_bf16 v[8:11], v[198:201], v[186:189], v[8:11]
	v_mfma_f32_16x16x32_bf16 v[0:3], v[206:209], v[186:189], v[0:3]
	v_mfma_f32_16x16x32_bf16 v[58:61], v[202:205], v[166:169], v[58:61]
	v_mfma_f32_16x16x32_bf16 v[50:53], v[210:213], v[166:169], v[50:53]
	v_mfma_f32_16x16x32_bf16 v[40:43], v[202:205], v[174:177], v[40:43]
	v_mfma_f32_16x16x32_bf16 v[32:35], v[210:213], v[174:177], v[32:35]
	v_mfma_f32_16x16x32_bf16 v[24:27], v[202:205], v[182:185], v[24:27]
	v_mfma_f32_16x16x32_bf16 v[16:19], v[210:213], v[182:185], v[16:19]
	v_mfma_f32_16x16x32_bf16 v[8:11], v[202:205], v[190:193], v[8:11]
	v_mfma_f32_16x16x32_bf16 v[0:3], v[210:213], v[190:193], v[0:3]
	s_setprio 0
	s_add_i32 s45, s45, 2
	s_add_u32 s26, s26, 0x100
	s_addc_u32 s27, s27, 0
	s_add_u32 s15, s15, 0x100
	s_addc_u32 s17, s17, 0
	s_cmp_gt_u32 s45, 13
	s_barrier
	s_cbranch_scc0 .LBB0_1356
	v_mul_f32_e32 v147, 0xbfb8aa3b, v126
	v_exp_f32_e32 v148, v147
	v_mul_f32_e32 v147, 0xbfb8aa3b, v118
	v_exp_f32_e32 v150, v147
	v_mul_f32_e32 v147, 0xbfb8aa3b, v127
	v_exp_f32_e32 v149, v147
	v_lshl_or_b32 v140, s22, 7, v144
	v_lshl_add_u32 v146, s24, 8, v142
	v_ashrrev_i32_e32 v141, 31, v140
	v_pk_add_f32 v[148:149], v[148:149], 1.0 op_sel_hi:[1,0]
	s_movk_i32 s15, 0x1600
	s_mov_b32 s22, s14
	s_mov_b32 s24, s16
	s_mov_b64 s[28:29], s[20:21]
	v_rcp_f32_e32 v147, v149
	s_nop 0
	v_mul_f32_e32 v127, v127, v147
	s_nop 0
	v_rcp_f32_e32 v147, v148
	s_nop 0
	v_mul_f32_e32 v126, v126, v147
	v_pk_mul_f32 v[122:123], v[122:123], v[126:127]
	v_mul_f32_e32 v126, 0xbfb8aa3b, v119
	v_exp_f32_e32 v151, v126
	s_nop 0
	v_pk_add_f32 v[126:127], v[150:151], 1.0 op_sel_hi:[1,0]
	s_nop 0
	s_nop 0
	v_rcp_f32_e32 v147, v127
	s_nop 0
	v_mul_f32_e32 v119, v119, v147
	s_nop 0
	v_rcp_f32_e32 v127, v126
	s_nop 0
	v_mul_f32_e32 v118, v118, v127
	v_pk_mul_f32 v[114:115], v[114:115], v[118:119]
	v_mul_f32_e32 v119, 0xbfb8aa3b, v120
	v_mul_f32_e32 v118, 0xbfb8aa3b, v128
	v_exp_f32_e32 v126, v119
	v_mul_f32_e32 v119, 0xbfb8aa3b, v129
	v_exp_f32_e32 v118, v118
	v_exp_f32_e32 v119, v119
	s_nop 0
	v_pk_add_f32 v[118:119], v[118:119], 1.0 op_sel_hi:[1,0]
	s_nop 0
	s_nop 0
	v_rcp_f32_e32 v127, v119
	s_nop 0
	v_mul_f32_e32 v119, v129, v127
	s_nop 0
	v_rcp_f32_e32 v127, v118
	s_nop 0
	v_mul_f32_e32 v118, v128, v127
	v_pk_mul_f32 v[124:125], v[124:125], v[118:119]
	v_mul_f32_e32 v118, 0xbfb8aa3b, v121
	v_exp_f32_e32 v127, v118
	s_nop 0
	v_pk_add_f32 v[118:119], v[126:127], 1.0 op_sel_hi:[1,0]
	s_nop 0
	s_nop 0
	v_rcp_f32_e32 v126, v119
	s_nop 0
	v_mul_f32_e32 v119, v121, v126
	s_nop 0
	v_rcp_f32_e32 v121, v118
	s_nop 0
	v_mul_f32_e32 v118, v120, v121
	v_pk_mul_f32 v[116:117], v[116:117], v[118:119]
	v_cvt_pk_bf16_f32 v120, v114, v115
	v_mov_b64_e32 v[114:115], s[12:13]
	v_cvt_pk_bf16_f32 v118, v122, v123
	v_cvt_pk_bf16_f32 v121, v116, v117
	v_mad_i64_i32 v[122:123], s[26:27], v146, s15, v[114:115]
	v_lshlrev_b64 v[116:117], 1, v[140:141]
	v_cvt_pk_bf16_f32 v119, v124, v125
	v_lshl_add_u64 v[122:123], v[122:123], 0, v[116:117]
	global_store_dwordx4 v[122:123], v[118:121], off
	s_nop 1
	v_mul_f32_e32 v119, 0xbfb8aa3b, v102
	v_mul_f32_e32 v118, 0xbfb8aa3b, v110
	v_exp_f32_e32 v120, v119
	v_mul_f32_e32 v119, 0xbfb8aa3b, v111
	v_exp_f32_e32 v118, v118
	v_exp_f32_e32 v119, v119
	s_nop 0
	v_pk_add_f32 v[118:119], v[118:119], 1.0 op_sel_hi:[1,0]
	s_nop 0
	s_nop 0
	v_rcp_f32_e32 v121, v119
	s_nop 0
	v_mul_f32_e32 v111, v111, v121
	s_nop 0
	v_rcp_f32_e32 v119, v118
	s_nop 0
	v_mul_f32_e32 v110, v110, v119
	v_pk_mul_f32 v[106:107], v[106:107], v[110:111]
	v_mul_f32_e32 v110, 0xbfb8aa3b, v103
	v_exp_f32_e32 v121, v110
	s_nop 0
	v_pk_add_f32 v[110:111], v[120:121], 1.0 op_sel_hi:[1,0]
	s_nop 0
	s_nop 0
	v_rcp_f32_e32 v118, v111
	s_nop 0
	v_mul_f32_e32 v103, v103, v118
	s_nop 0
	v_rcp_f32_e32 v111, v110
	s_nop 0
	v_mul_f32_e32 v102, v102, v111
	v_pk_mul_f32 v[102:103], v[98:99], v[102:103]
	v_mul_f32_e32 v99, 0xbfb8aa3b, v104
	v_mul_f32_e32 v98, 0xbfb8aa3b, v112
	v_exp_f32_e32 v110, v99
	v_mul_f32_e32 v99, 0xbfb8aa3b, v113
	v_exp_f32_e32 v98, v98
	v_exp_f32_e32 v99, v99
	s_nop 0
	v_pk_add_f32 v[98:99], v[98:99], 1.0 op_sel_hi:[1,0]
	s_nop 0
	s_nop 0
	v_rcp_f32_e32 v111, v99
	s_nop 0
	v_mul_f32_e32 v99, v113, v111
	s_nop 0
	v_rcp_f32_e32 v111, v98
	s_nop 0
	v_mul_f32_e32 v98, v112, v111
	v_pk_mul_f32 v[108:109], v[108:109], v[98:99]
	v_mul_f32_e32 v98, 0xbfb8aa3b, v105
	v_exp_f32_e32 v111, v98
	s_nop 0
	v_pk_add_f32 v[98:99], v[110:111], 1.0 op_sel_hi:[1,0]
	s_nop 0
	s_nop 0
	v_rcp_f32_e32 v110, v99
	s_nop 0
	v_mul_f32_e32 v99, v105, v110
	s_nop 0
	v_rcp_f32_e32 v105, v98
	s_nop 0
	v_mul_f32_e32 v98, v104, v105
	v_or_b32_e32 v110, 16, v146
	v_pk_mul_f32 v[104:105], v[100:101], v[98:99]
	v_cvt_pk_bf16_f32 v100, v102, v103
	v_mad_i64_i32 v[102:103], s[26:27], v110, s15, v[114:115]
	v_cvt_pk_bf16_f32 v98, v106, v107
	v_cvt_pk_bf16_f32 v99, v108, v109
	v_cvt_pk_bf16_f32 v101, v104, v105
	v_lshl_add_u64 v[102:103], v[102:103], 0, v[116:117]
	global_store_dwordx4 v[102:103], v[98:101], off
	s_nop 1
	v_mul_f32_e32 v99, 0xbfb8aa3b, v86
	v_mul_f32_e32 v98, 0xbfb8aa3b, v94
	v_exp_f32_e32 v100, v99
	v_mul_f32_e32 v99, 0xbfb8aa3b, v95
	v_exp_f32_e32 v98, v98
	v_exp_f32_e32 v99, v99
	s_nop 0
	v_pk_add_f32 v[98:99], v[98:99], 1.0 op_sel_hi:[1,0]
	s_nop 0
	s_nop 0
	v_rcp_f32_e32 v101, v99
	s_nop 0
	v_mul_f32_e32 v95, v95, v101
	s_nop 0
	v_rcp_f32_e32 v99, v98
	s_nop 0
	v_mul_f32_e32 v94, v94, v99
	v_pk_mul_f32 v[90:91], v[90:91], v[94:95]
	v_mul_f32_e32 v94, 0xbfb8aa3b, v87
	v_exp_f32_e32 v101, v94
	s_nop 0
	v_pk_add_f32 v[94:95], v[100:101], 1.0 op_sel_hi:[1,0]
	s_nop 0
	s_nop 0
	v_rcp_f32_e32 v98, v95
	s_nop 0
	v_mul_f32_e32 v87, v87, v98
	s_nop 0
	v_rcp_f32_e32 v95, v94
	s_nop 0
	v_mul_f32_e32 v86, v86, v95
	v_pk_mul_f32 v[86:87], v[82:83], v[86:87]
	v_mul_f32_e32 v83, 0xbfb8aa3b, v88
	v_mul_f32_e32 v82, 0xbfb8aa3b, v96
	v_exp_f32_e32 v94, v83
	v_mul_f32_e32 v83, 0xbfb8aa3b, v97
	v_exp_f32_e32 v82, v82
	v_exp_f32_e32 v83, v83
	s_nop 0
	v_pk_add_f32 v[82:83], v[82:83], 1.0 op_sel_hi:[1,0]
	s_nop 0
	s_nop 0
	v_rcp_f32_e32 v95, v83
	s_nop 0
	v_mul_f32_e32 v83, v97, v95
	s_nop 0
	v_rcp_f32_e32 v95, v82
	s_nop 0
	v_mul_f32_e32 v82, v96, v95
	v_pk_mul_f32 v[92:93], v[92:93], v[82:83]
	v_mul_f32_e32 v82, 0xbfb8aa3b, v89
	v_exp_f32_e32 v95, v82
	s_nop 0
	v_pk_add_f32 v[82:83], v[94:95], 1.0 op_sel_hi:[1,0]
	s_nop 0
	s_nop 0
	v_rcp_f32_e32 v94, v83
	s_nop 0
	v_mul_f32_e32 v83, v89, v94
	s_nop 0
	v_rcp_f32_e32 v89, v82
	s_nop 0
	v_mul_f32_e32 v82, v88, v89
	v_or_b32_e32 v94, 32, v146
	v_pk_mul_f32 v[88:89], v[84:85], v[82:83]
	v_cvt_pk_bf16_f32 v84, v86, v87
	v_mad_i64_i32 v[86:87], s[26:27], v94, s15, v[114:115]
	v_cvt_pk_bf16_f32 v82, v90, v91
	v_cvt_pk_bf16_f32 v83, v92, v93
	v_cvt_pk_bf16_f32 v85, v88, v89
	v_lshl_add_u64 v[86:87], v[86:87], 0, v[116:117]
	global_store_dwordx4 v[86:87], v[82:85], off
	s_nop 1
	v_mul_f32_e32 v83, 0xbfb8aa3b, v70
	v_mul_f32_e32 v82, 0xbfb8aa3b, v78
	v_exp_f32_e32 v84, v83
	v_mul_f32_e32 v83, 0xbfb8aa3b, v79
	v_exp_f32_e32 v82, v82
	v_exp_f32_e32 v83, v83
	s_nop 0
	v_pk_add_f32 v[82:83], v[82:83], 1.0 op_sel_hi:[1,0]
	s_nop 0
	s_nop 0
	v_rcp_f32_e32 v85, v83
	s_nop 0
	v_mul_f32_e32 v79, v79, v85
	s_nop 0
	v_rcp_f32_e32 v83, v82
	s_nop 0
	v_mul_f32_e32 v78, v78, v83
	v_pk_mul_f32 v[74:75], v[74:75], v[78:79]
	v_mul_f32_e32 v78, 0xbfb8aa3b, v71
	v_exp_f32_e32 v85, v78
	s_nop 0
	v_pk_add_f32 v[78:79], v[84:85], 1.0 op_sel_hi:[1,0]
	s_nop 0
	s_nop 0
	v_rcp_f32_e32 v82, v79
	s_nop 0
	v_mul_f32_e32 v71, v71, v82
	s_nop 0
	v_rcp_f32_e32 v79, v78
	s_nop 0
	v_mul_f32_e32 v70, v70, v79
	v_pk_mul_f32 v[70:71], v[66:67], v[70:71]
	v_mul_f32_e32 v67, 0xbfb8aa3b, v72
	v_mul_f32_e32 v66, 0xbfb8aa3b, v80
	v_exp_f32_e32 v78, v67
	v_mul_f32_e32 v67, 0xbfb8aa3b, v81
	v_exp_f32_e32 v66, v66
	v_exp_f32_e32 v67, v67
	s_nop 0
	v_pk_add_f32 v[66:67], v[66:67], 1.0 op_sel_hi:[1,0]
	s_nop 0
	s_nop 0
	v_rcp_f32_e32 v79, v67
	s_nop 0
	v_mul_f32_e32 v67, v81, v79
	s_nop 0
	v_rcp_f32_e32 v79, v66
	s_nop 0
	v_mul_f32_e32 v66, v80, v79
	v_pk_mul_f32 v[76:77], v[76:77], v[66:67]
	v_mul_f32_e32 v66, 0xbfb8aa3b, v73
	v_exp_f32_e32 v79, v66
	s_nop 0
	v_pk_add_f32 v[66:67], v[78:79], 1.0 op_sel_hi:[1,0]
	s_nop 0
	s_nop 0
	v_rcp_f32_e32 v78, v67
	s_nop 0
	v_mul_f32_e32 v67, v73, v78
	s_nop 0
	v_rcp_f32_e32 v73, v66
	s_nop 0
	v_mul_f32_e32 v66, v72, v73
	v_or_b32_e32 v78, 48, v146
	v_pk_mul_f32 v[72:73], v[68:69], v[66:67]
	v_cvt_pk_bf16_f32 v68, v70, v71
	v_mad_i64_i32 v[70:71], s[26:27], v78, s15, v[114:115]
	v_cvt_pk_bf16_f32 v66, v74, v75
	v_cvt_pk_bf16_f32 v67, v76, v77
	v_cvt_pk_bf16_f32 v69, v72, v73
	v_lshl_add_u64 v[70:71], v[70:71], 0, v[116:117]
	global_store_dwordx4 v[70:71], v[66:69], off
	v_add_u32_e32 v70, 0x80, v146
	s_nop 0
	v_mul_f32_e32 v67, 0xbfb8aa3b, v54
	v_mul_f32_e32 v66, 0xbfb8aa3b, v62
	v_exp_f32_e32 v68, v67
	v_mul_f32_e32 v67, 0xbfb8aa3b, v63
	v_exp_f32_e32 v66, v66
	v_exp_f32_e32 v67, v67
	s_nop 0
	v_pk_add_f32 v[66:67], v[66:67], 1.0 op_sel_hi:[1,0]
	s_nop 0
	s_nop 0
	v_rcp_f32_e32 v69, v67
	s_nop 0
	v_mul_f32_e32 v63, v63, v69
	s_nop 0
	v_rcp_f32_e32 v67, v66
	s_nop 0
	v_mul_f32_e32 v62, v62, v67
	v_pk_mul_f32 v[58:59], v[58:59], v[62:63]
	v_mul_f32_e32 v62, 0xbfb8aa3b, v55
	v_exp_f32_e32 v69, v62
	s_nop 0
	v_pk_add_f32 v[62:63], v[68:69], 1.0 op_sel_hi:[1,0]
	s_nop 0
	s_nop 0
	v_rcp_f32_e32 v66, v63
	s_nop 0
	v_mul_f32_e32 v55, v55, v66
	s_nop 0
	v_rcp_f32_e32 v63, v62
	s_nop 0
	v_mul_f32_e32 v54, v54, v63
	v_pk_mul_f32 v[54:55], v[50:51], v[54:55]
	v_mul_f32_e32 v51, 0xbfb8aa3b, v56
	v_mul_f32_e32 v50, 0xbfb8aa3b, v64
	v_exp_f32_e32 v62, v51
	v_mul_f32_e32 v51, 0xbfb8aa3b, v65
	v_exp_f32_e32 v50, v50
	v_exp_f32_e32 v51, v51
	s_nop 0
	v_pk_add_f32 v[50:51], v[50:51], 1.0 op_sel_hi:[1,0]
	s_nop 0
	s_nop 0
	v_rcp_f32_e32 v63, v51
	s_nop 0
	v_mul_f32_e32 v51, v65, v63
	s_nop 0
	v_rcp_f32_e32 v63, v50
	s_nop 0
	v_mul_f32_e32 v50, v64, v63
	v_pk_mul_f32 v[60:61], v[60:61], v[50:51]
	v_mul_f32_e32 v50, 0xbfb8aa3b, v57
	v_exp_f32_e32 v63, v50
	s_nop 0
	v_pk_add_f32 v[50:51], v[62:63], 1.0 op_sel_hi:[1,0]
	s_nop 0
	s_nop 0
	v_rcp_f32_e32 v62, v51
	s_nop 0
	v_mul_f32_e32 v51, v57, v62
	s_nop 0
	v_rcp_f32_e32 v57, v50
	s_nop 0
	v_mul_f32_e32 v50, v56, v57
	v_pk_mul_f32 v[56:57], v[52:53], v[50:51]
	v_cvt_pk_bf16_f32 v52, v54, v55
	v_mad_i64_i32 v[54:55], s[26:27], v70, s15, v[114:115]
	v_cvt_pk_bf16_f32 v50, v58, v59
	v_cvt_pk_bf16_f32 v51, v60, v61
	v_cvt_pk_bf16_f32 v53, v56, v57
	v_lshl_add_u64 v[54:55], v[54:55], 0, v[116:117]
	global_store_dwordx4 v[54:55], v[50:53], off
	s_nop 1
	v_mul_f32_e32 v51, 0xbfb8aa3b, v36
	v_mul_f32_e32 v50, 0xbfb8aa3b, v44
	v_exp_f32_e32 v52, v51
	v_mul_f32_e32 v51, 0xbfb8aa3b, v45
	v_exp_f32_e32 v50, v50
	v_exp_f32_e32 v51, v51
	s_nop 0
	v_pk_add_f32 v[50:51], v[50:51], 1.0 op_sel_hi:[1,0]
	s_nop 0
	s_nop 0
	v_rcp_f32_e32 v53, v51
	s_nop 0
	v_mul_f32_e32 v45, v45, v53
	s_nop 0
	v_rcp_f32_e32 v51, v50
	s_nop 0
	v_mul_f32_e32 v44, v44, v51
	v_pk_mul_f32 v[40:41], v[40:41], v[44:45]
	v_mul_f32_e32 v44, 0xbfb8aa3b, v37
	v_exp_f32_e32 v53, v44
	s_nop 0
	v_pk_add_f32 v[44:45], v[52:53], 1.0 op_sel_hi:[1,0]
	s_nop 0
	s_nop 0
	v_rcp_f32_e32 v50, v45
	s_nop 0
	v_mul_f32_e32 v37, v37, v50
	s_nop 0
	v_rcp_f32_e32 v45, v44
	s_nop 0
	v_mul_f32_e32 v36, v36, v45
	v_pk_mul_f32 v[36:37], v[32:33], v[36:37]
	v_mul_f32_e32 v33, 0xbfb8aa3b, v38
	v_mul_f32_e32 v32, 0xbfb8aa3b, v46
	v_exp_f32_e32 v44, v33
	v_mul_f32_e32 v33, 0xbfb8aa3b, v47
	v_exp_f32_e32 v32, v32
	v_exp_f32_e32 v33, v33
	s_nop 0
	v_pk_add_f32 v[32:33], v[32:33], 1.0 op_sel_hi:[1,0]
	s_nop 0
	s_nop 0
	v_rcp_f32_e32 v45, v33
	s_nop 0
	v_mul_f32_e32 v33, v47, v45
	s_nop 0
	v_rcp_f32_e32 v45, v32
	s_nop 0
	v_mul_f32_e32 v32, v46, v45
	v_pk_mul_f32 v[42:43], v[42:43], v[32:33]
	v_mul_f32_e32 v32, 0xbfb8aa3b, v39
	v_exp_f32_e32 v45, v32
	s_nop 0
	v_pk_add_f32 v[32:33], v[44:45], 1.0 op_sel_hi:[1,0]
	s_nop 0
	s_nop 0
	v_rcp_f32_e32 v44, v33
	s_nop 0
	v_mul_f32_e32 v33, v39, v44
	s_nop 0
	v_rcp_f32_e32 v39, v32
	s_nop 0
	v_mul_f32_e32 v32, v38, v39
	v_add_u32_e32 v44, 0x90, v146
	v_pk_mul_f32 v[38:39], v[34:35], v[32:33]
	v_cvt_pk_bf16_f32 v34, v36, v37
	v_mad_i64_i32 v[36:37], s[26:27], v44, s15, v[114:115]
	v_cvt_pk_bf16_f32 v32, v40, v41
	v_cvt_pk_bf16_f32 v33, v42, v43
	v_cvt_pk_bf16_f32 v35, v38, v39
	v_lshl_add_u64 v[36:37], v[36:37], 0, v[116:117]
	global_store_dwordx4 v[36:37], v[32:35], off
	s_nop 1
	v_mul_f32_e32 v33, 0xbfb8aa3b, v20
	v_mul_f32_e32 v32, 0xbfb8aa3b, v28
	v_exp_f32_e32 v34, v33
	v_mul_f32_e32 v33, 0xbfb8aa3b, v29
	v_exp_f32_e32 v32, v32
	v_exp_f32_e32 v33, v33
	s_nop 0
	v_pk_add_f32 v[32:33], v[32:33], 1.0 op_sel_hi:[1,0]
	s_nop 0
	s_nop 0
	v_rcp_f32_e32 v35, v33
	s_nop 0
	v_mul_f32_e32 v29, v29, v35
	s_nop 0
	v_rcp_f32_e32 v33, v32
	s_nop 0
	v_mul_f32_e32 v28, v28, v33
	v_pk_mul_f32 v[24:25], v[24:25], v[28:29]
	v_mul_f32_e32 v28, 0xbfb8aa3b, v21
	v_exp_f32_e32 v35, v28
	s_nop 0
	v_pk_add_f32 v[28:29], v[34:35], 1.0 op_sel_hi:[1,0]
	s_nop 0
	s_nop 0
	v_rcp_f32_e32 v32, v29
	s_nop 0
	v_mul_f32_e32 v21, v21, v32
	s_nop 0
	v_rcp_f32_e32 v29, v28
	s_nop 0
	v_mul_f32_e32 v20, v20, v29
	v_pk_mul_f32 v[20:21], v[16:17], v[20:21]
	v_mul_f32_e32 v17, 0xbfb8aa3b, v22
	v_mul_f32_e32 v16, 0xbfb8aa3b, v30
	v_exp_f32_e32 v28, v17
	v_mul_f32_e32 v17, 0xbfb8aa3b, v31
	v_exp_f32_e32 v16, v16
	v_exp_f32_e32 v17, v17
	s_nop 0
	v_pk_add_f32 v[16:17], v[16:17], 1.0 op_sel_hi:[1,0]
	s_nop 0
	s_nop 0
	v_rcp_f32_e32 v29, v17
	s_nop 0
	v_mul_f32_e32 v17, v31, v29
	s_nop 0
	v_rcp_f32_e32 v29, v16
	s_nop 0
	v_mul_f32_e32 v16, v30, v29
	v_pk_mul_f32 v[26:27], v[26:27], v[16:17]
	v_mul_f32_e32 v16, 0xbfb8aa3b, v23
	v_exp_f32_e32 v29, v16
	s_nop 0
	v_pk_add_f32 v[16:17], v[28:29], 1.0 op_sel_hi:[1,0]
	s_nop 0
	s_nop 0
	v_rcp_f32_e32 v28, v17
	s_nop 0
	v_mul_f32_e32 v17, v23, v28
	s_nop 0
	v_rcp_f32_e32 v23, v16
	s_nop 0
	v_mul_f32_e32 v16, v22, v23
	v_add_u32_e32 v28, 0xa0, v146
	v_pk_mul_f32 v[22:23], v[18:19], v[16:17]
	v_cvt_pk_bf16_f32 v18, v20, v21
	v_mad_i64_i32 v[20:21], s[26:27], v28, s15, v[114:115]
	v_cvt_pk_bf16_f32 v16, v24, v25
	v_cvt_pk_bf16_f32 v17, v26, v27
	v_cvt_pk_bf16_f32 v19, v22, v23
	v_lshl_add_u64 v[20:21], v[20:21], 0, v[116:117]
	global_store_dwordx4 v[20:21], v[16:19], off
	s_nop 1
	v_mul_f32_e32 v17, 0xbfb8aa3b, v4
	v_mul_f32_e32 v16, 0xbfb8aa3b, v12
	v_exp_f32_e32 v18, v17
	v_mul_f32_e32 v17, 0xbfb8aa3b, v13
	v_exp_f32_e32 v16, v16
	v_exp_f32_e32 v17, v17
	s_nop 0
	v_pk_add_f32 v[16:17], v[16:17], 1.0 op_sel_hi:[1,0]
	s_nop 0
	s_nop 0
	v_rcp_f32_e32 v19, v17
	s_nop 0
	v_mul_f32_e32 v13, v13, v19
	s_nop 0
	v_rcp_f32_e32 v17, v16
	s_nop 0
	v_mul_f32_e32 v12, v12, v17
	v_pk_mul_f32 v[8:9], v[8:9], v[12:13]
	v_mul_f32_e32 v12, 0xbfb8aa3b, v5
	v_exp_f32_e32 v19, v12
	s_nop 0
	v_pk_add_f32 v[12:13], v[18:19], 1.0 op_sel_hi:[1,0]
	s_nop 0
	s_nop 0
	v_rcp_f32_e32 v16, v13
	s_nop 0
	v_mul_f32_e32 v5, v5, v16
	s_nop 0
	v_rcp_f32_e32 v13, v12
	s_nop 0
	v_mul_f32_e32 v4, v4, v13
	v_pk_mul_f32 v[4:5], v[0:1], v[4:5]
	v_mul_f32_e32 v1, 0xbfb8aa3b, v6
	v_mul_f32_e32 v0, 0xbfb8aa3b, v14
	v_exp_f32_e32 v12, v1
	v_mul_f32_e32 v1, 0xbfb8aa3b, v15
	v_exp_f32_e32 v0, v0
	v_exp_f32_e32 v1, v1
	s_nop 0
	v_pk_add_f32 v[0:1], v[0:1], 1.0 op_sel_hi:[1,0]
	s_nop 0
	s_nop 0
	v_rcp_f32_e32 v13, v1
	s_nop 0
	v_mul_f32_e32 v1, v15, v13
	s_nop 0
	v_rcp_f32_e32 v13, v0
	s_nop 0
	v_mul_f32_e32 v0, v14, v13
	v_pk_mul_f32 v[10:11], v[10:11], v[0:1]
	v_mul_f32_e32 v0, 0xbfb8aa3b, v7
	v_exp_f32_e32 v13, v0
	s_nop 0
	v_pk_add_f32 v[0:1], v[12:13], 1.0 op_sel_hi:[1,0]
	s_nop 0
	s_nop 0
	v_rcp_f32_e32 v12, v1
	s_nop 0
	v_mul_f32_e32 v1, v7, v12
	s_nop 0
	v_rcp_f32_e32 v7, v0
	s_nop 0
	v_mul_f32_e32 v0, v6, v7
	v_add_u32_e32 v12, 0xb0, v146
	v_pk_mul_f32 v[6:7], v[2:3], v[0:1]
	v_cvt_pk_bf16_f32 v2, v4, v5
	v_mad_i64_i32 v[4:5], s[26:27], v12, s15, v[114:115]
	v_cvt_pk_bf16_f32 v0, v8, v9
	v_cvt_pk_bf16_f32 v1, v10, v11
	v_cvt_pk_bf16_f32 v3, v6, v7
	v_lshl_add_u64 v[4:5], v[4:5], 0, v[116:117]
	s_and_b64 vcc, exec, s[0:1]
	s_mov_b64 s[26:27], s[18:19]
	global_store_dwordx4 v[4:5], v[0:3], off
	s_cbranch_vccz .LBB0_1353
	s_waitcnt vmcnt(0)
	s_cmpk_gt_u32 s5, 0xff
	s_cbranch_scc1 .LBB0_1360
	s_barrier

.LBB0_1421:
	s_add_u32 s18, s16, 0x100
	s_addc_u32 s19, s17, 0
	s_add_i32 s47, 0, 0x10000
	v_add_u32_e32 v142, s47, v204
	ds_read_b128 v[130:133], v142
	ds_read_b128 v[134:137], v142 offset:1024
	ds_read_b128 v[138:141], v142 offset:2048
	ds_read_b128 v[142:145], v142 offset:3072
	s_cmp_eq_u32 s46, 40
	s_cselect_b32 s23, s11, s19
	s_cselect_b32 s22, s10, s18
	s_cselect_b32 s21, s13, s45
	s_cselect_b32 s20, s12, s44
	v_lshl_add_u64 v[188:189], s[16:17], 0, v[152:153]
	s_add_i32 m0, s31, 0xc000
	ds_read_b128 v[156:159], v206
	ds_read_b128 v[160:163], v206 offset:1024
	ds_read_b128 v[164:167], v206 offset:2048
	ds_read_b128 v[168:171], v206 offset:3072
	ds_read_b128 v[172:175], v206 offset:4096
	ds_read_b128 v[176:179], v206 offset:5120
	ds_read_b128 v[180:183], v206 offset:6144
	ds_read_b128 v[184:187], v206 offset:7168
	global_load_lds_dwordx4 v[188:189], off
	v_lshl_add_u64 v[188:189], s[16:17], 0, v[154:155]
	s_add_i32 m0, s31, 0xe000
	s_nop 0
	global_load_lds_dwordx4 v[188:189], off
	s_waitcnt lgkmcnt(8)
	s_barrier
	s_waitcnt lgkmcnt(0)
	s_setprio 1
	s_waitcnt lgkmcnt(0)
	v_mfma_f32_16x16x32_bf16 v[126:129], v[130:133], v[156:159], v[126:129]
	v_mfma_f32_16x16x32_bf16 v[122:125], v[138:141], v[156:159], v[122:125]
	v_mfma_f32_16x16x32_bf16 v[114:117], v[130:133], v[164:167], v[114:117]
	v_mfma_f32_16x16x32_bf16 v[106:109], v[138:141], v[164:167], v[106:109]
	v_mfma_f32_16x16x32_bf16 v[98:101], v[130:133], v[172:175], v[98:101]
	v_mfma_f32_16x16x32_bf16 v[90:93], v[138:141], v[172:175], v[90:93]
	v_mfma_f32_16x16x32_bf16 v[82:85], v[130:133], v[180:183], v[82:85]
	v_mfma_f32_16x16x32_bf16 v[74:77], v[138:141], v[180:183], v[74:77]
	v_mfma_f32_16x16x32_bf16 v[126:129], v[134:137], v[160:163], v[126:129]
	v_mfma_f32_16x16x32_bf16 v[122:125], v[142:145], v[160:163], v[122:125]
	v_mfma_f32_16x16x32_bf16 v[114:117], v[134:137], v[168:171], v[114:117]
	v_mfma_f32_16x16x32_bf16 v[106:109], v[142:145], v[168:171], v[106:109]
	v_mfma_f32_16x16x32_bf16 v[98:101], v[134:137], v[176:179], v[98:101]
	v_mfma_f32_16x16x32_bf16 v[90:93], v[142:145], v[176:179], v[90:93]
	v_mfma_f32_16x16x32_bf16 v[82:85], v[134:137], v[184:187], v[82:85]
	v_mfma_f32_16x16x32_bf16 v[74:77], v[142:145], v[184:187], v[74:77]
	s_setprio 0
	s_barrier
	s_add_i32 s48, 0, 0x14000
	v_add_u32_e32 v192, s48, v204
	s_add_i32 s16, s47, s25
	ds_read_b128 v[188:191], v192
	ds_read_b128 v[198:201], v192 offset:1024
	ds_read_b128 v[208:211], v192 offset:2048
	ds_read_b128 v[212:215], v192 offset:3072
	v_lshl_add_u64 v[192:193], s[20:21], 0, v[48:49]
	s_mov_b32 m0, s16
	v_lshl_add_u64 v[202:203], s[20:21], 0, v[146:147]
	global_load_lds_dwordx4 v[192:193], off
	s_add_i32 m0, s16, 0x2000
	s_nop 0
	global_load_lds_dwordx4 v[202:203], off
	s_barrier
	s_waitcnt lgkmcnt(0)
	s_setprio 1
	s_waitcnt lgkmcnt(0)
	v_mfma_f32_16x16x32_bf16 v[118:121], v[188:191], v[156:159], v[118:121]
	v_mfma_f32_16x16x32_bf16 v[110:113], v[208:211], v[156:159], v[110:113]
	v_mfma_f32_16x16x32_bf16 v[102:105], v[188:191], v[164:167], v[102:105]
	v_mfma_f32_16x16x32_bf16 v[94:97], v[208:211], v[164:167], v[94:97]
	v_mfma_f32_16x16x32_bf16 v[86:89], v[188:191], v[172:175], v[86:89]
	v_mfma_f32_16x16x32_bf16 v[78:81], v[208:211], v[172:175], v[78:81]
	v_mfma_f32_16x16x32_bf16 v[70:73], v[188:191], v[180:183], v[70:73]
	v_mfma_f32_16x16x32_bf16 v[66:69], v[208:211], v[180:183], v[66:69]
	v_mfma_f32_16x16x32_bf16 v[118:121], v[198:201], v[160:163], v[118:121]
	v_mfma_f32_16x16x32_bf16 v[110:113], v[212:215], v[160:163], v[110:113]
	v_mfma_f32_16x16x32_bf16 v[102:105], v[198:201], v[168:171], v[102:105]
	v_mfma_f32_16x16x32_bf16 v[94:97], v[212:215], v[168:171], v[94:97]
	v_mfma_f32_16x16x32_bf16 v[86:89], v[198:201], v[176:179], v[86:89]
	v_mfma_f32_16x16x32_bf16 v[78:81], v[212:215], v[176:179], v[78:81]
	v_mfma_f32_16x16x32_bf16 v[70:73], v[198:201], v[184:187], v[70:73]
	v_mfma_f32_16x16x32_bf16 v[66:69], v[212:215], v[184:187], v[66:69]
	s_setprio 0
	s_mov_b32 m0, s31
	v_lshl_add_u64 v[216:217], s[22:23], 0, v[48:49]
	s_barrier
	ds_read_b128 v[156:159], v206 offset:16384
	ds_read_b128 v[160:163], v206 offset:17408
	ds_read_b128 v[164:167], v206 offset:18432
	ds_read_b128 v[168:171], v206 offset:19456
	ds_read_b128 v[172:175], v206 offset:20480
	ds_read_b128 v[176:179], v206 offset:21504
	ds_read_b128 v[180:183], v206 offset:22528
	ds_read_b128 v[184:187], v206 offset:23552
	global_load_lds_dwordx4 v[216:217], off
	v_lshl_add_u64 v[218:219], s[22:23], 0, v[146:147]
	s_mov_b32 m0, s34
	s_nop 0
	global_load_lds_dwordx4 v[218:219], off
	s_barrier
	s_waitcnt lgkmcnt(0)
	s_setprio 1
	s_waitcnt lgkmcnt(0)
	v_mfma_f32_16x16x32_bf16 v[62:65], v[130:133], v[156:159], v[62:65]
	v_mfma_f32_16x16x32_bf16 v[58:61], v[138:141], v[156:159], v[58:61]
	v_mfma_f32_16x16x32_bf16 v[50:53], v[130:133], v[164:167], v[50:53]
	v_mfma_f32_16x16x32_bf16 v[40:43], v[138:141], v[164:167], v[40:43]
	v_mfma_f32_16x16x32_bf16 v[32:35], v[130:133], v[172:175], v[32:35]
	v_mfma_f32_16x16x32_bf16 v[24:27], v[138:141], v[172:175], v[24:27]
	v_mfma_f32_16x16x32_bf16 v[16:19], v[130:133], v[180:183], v[16:19]
	v_mfma_f32_16x16x32_bf16 v[8:11], v[138:141], v[180:183], v[8:11]
	v_mfma_f32_16x16x32_bf16 v[62:65], v[134:137], v[160:163], v[62:65]
	v_mfma_f32_16x16x32_bf16 v[58:61], v[142:145], v[160:163], v[58:61]
	v_mfma_f32_16x16x32_bf16 v[50:53], v[134:137], v[168:171], v[50:53]
	v_mfma_f32_16x16x32_bf16 v[40:43], v[142:145], v[168:171], v[40:43]
	v_mfma_f32_16x16x32_bf16 v[32:35], v[134:137], v[176:179], v[32:35]
	v_mfma_f32_16x16x32_bf16 v[24:27], v[142:145], v[176:179], v[24:27]
	v_mfma_f32_16x16x32_bf16 v[16:19], v[134:137], v[184:187], v[16:19]
	v_mfma_f32_16x16x32_bf16 v[8:11], v[142:145], v[184:187], v[8:11]
	s_setprio 0
	s_barrier
	s_add_u32 s16, s20, 0xb0000
	s_addc_u32 s17, s21, 0
	s_add_i32 s47, s48, s25
	s_mov_b32 m0, s47
	s_nop 0
	global_load_lds_dwordx4 v48, s[16:17]
	s_add_i32 m0, s47, 0x2000
	s_nop 0
	global_load_lds_dwordx4 v146, s[16:17]
	s_waitcnt vmcnt(6)
	s_barrier
	s_setprio 1
	v_mfma_f32_16x16x32_bf16 v[54:57], v[188:191], v[156:159], v[54:57]
	v_mfma_f32_16x16x32_bf16 v[44:47], v[208:211], v[156:159], v[44:47]
	v_mfma_f32_16x16x32_bf16 v[36:39], v[188:191], v[164:167], v[36:39]
	v_mfma_f32_16x16x32_bf16 v[28:31], v[208:211], v[164:167], v[28:31]
	v_mfma_f32_16x16x32_bf16 v[20:23], v[188:191], v[172:175], v[20:23]
	v_mfma_f32_16x16x32_bf16 v[12:15], v[208:211], v[172:175], v[12:15]
	v_mfma_f32_16x16x32_bf16 v[4:7], v[188:191], v[180:183], v[4:7]
	v_mfma_f32_16x16x32_bf16 v[0:3], v[208:211], v[180:183], v[0:3]
	v_mfma_f32_16x16x32_bf16 v[54:57], v[198:201], v[160:163], v[54:57]
	v_mfma_f32_16x16x32_bf16 v[44:47], v[212:215], v[160:163], v[44:47]
	v_mfma_f32_16x16x32_bf16 v[36:39], v[198:201], v[168:171], v[36:39]
	v_mfma_f32_16x16x32_bf16 v[28:31], v[212:215], v[168:171], v[28:31]
	v_mfma_f32_16x16x32_bf16 v[20:23], v[198:201], v[176:179], v[20:23]
	v_mfma_f32_16x16x32_bf16 v[12:15], v[212:215], v[176:179], v[12:15]
	v_mfma_f32_16x16x32_bf16 v[4:7], v[198:201], v[184:187], v[4:7]
	v_mfma_f32_16x16x32_bf16 v[0:3], v[212:215], v[184:187], v[0:3]
	s_setprio 0
	s_add_i32 s47, 0, 0x18000
	v_add_u32_e32 v142, s47, v204
	s_barrier
	ds_read_b128 v[130:133], v142
	ds_read_b128 v[134:137], v142 offset:1024
	ds_read_b128 v[138:141], v142 offset:2048
	ds_read_b128 v[142:145], v142 offset:3072
	s_add_u32 s16, s22, 0xb0000
	s_addc_u32 s17, s23, 0
	s_mov_b32 m0, s35
	ds_read_b128 v[156:159], v206 offset:32768
	ds_read_b128 v[160:163], v206 offset:33792
	ds_read_b128 v[164:167], v206 offset:34816
	ds_read_b128 v[168:171], v206 offset:35840
	ds_read_b128 v[172:175], v206 offset:36864
	ds_read_b128 v[176:179], v206 offset:37888
	ds_read_b128 v[180:183], v206 offset:38912
	ds_read_b128 v[184:187], v206 offset:39936
	global_load_lds_dwordx4 v48, s[16:17]
	s_mov_b32 m0, s36
	s_nop 0
	global_load_lds_dwordx4 v146, s[16:17]
	s_waitcnt lgkmcnt(8)
	s_barrier
	s_waitcnt lgkmcnt(0)
	s_setprio 1
	s_waitcnt lgkmcnt(0)
	v_mfma_f32_16x16x32_bf16 v[126:129], v[130:133], v[156:159], v[126:129]
	v_mfma_f32_16x16x32_bf16 v[122:125], v[138:141], v[156:159], v[122:125]
	v_mfma_f32_16x16x32_bf16 v[114:117], v[130:133], v[164:167], v[114:117]
	v_mfma_f32_16x16x32_bf16 v[106:109], v[138:141], v[164:167], v[106:109]
	v_mfma_f32_16x16x32_bf16 v[98:101], v[130:133], v[172:175], v[98:101]
	v_mfma_f32_16x16x32_bf16 v[90:93], v[138:141], v[172:175], v[90:93]
	v_mfma_f32_16x16x32_bf16 v[82:85], v[130:133], v[180:183], v[82:85]
	v_mfma_f32_16x16x32_bf16 v[74:77], v[138:141], v[180:183], v[74:77]
	v_mfma_f32_16x16x32_bf16 v[126:129], v[134:137], v[160:163], v[126:129]
	v_mfma_f32_16x16x32_bf16 v[122:125], v[142:145], v[160:163], v[122:125]
	v_mfma_f32_16x16x32_bf16 v[114:117], v[134:137], v[168:171], v[114:117]
	v_mfma_f32_16x16x32_bf16 v[106:109], v[142:145], v[168:171], v[106:109]
	v_mfma_f32_16x16x32_bf16 v[98:101], v[134:137], v[176:179], v[98:101]
	v_mfma_f32_16x16x32_bf16 v[90:93], v[142:145], v[176:179], v[90:93]
	v_mfma_f32_16x16x32_bf16 v[82:85], v[134:137], v[184:187], v[82:85]
	v_mfma_f32_16x16x32_bf16 v[74:77], v[142:145], v[184:187], v[74:77]
	s_setprio 0
	s_barrier
	s_add_i32 s22, 0, 0x1c000
	s_add_i32 s16, s47, s25
	v_add_u32_e32 v207, s22, v204
	v_lshl_add_u64 v[192:193], v[192:193], 0, s[66:67]
	s_mov_b32 m0, s16
	ds_read_b128 v[188:191], v207
	ds_read_b128 v[198:201], v207 offset:1024
	ds_read_b128 v[208:211], v207 offset:2048
	ds_read_b128 v[212:215], v207 offset:3072
	global_load_lds_dwordx4 v[192:193], off
	v_lshl_add_u64 v[192:193], v[202:203], 0, s[66:67]
	s_add_i32 m0, s16, 0x2000
	s_nop 0
	global_load_lds_dwordx4 v[192:193], off
	s_barrier
	s_waitcnt lgkmcnt(0)
	s_setprio 1
	s_waitcnt lgkmcnt(0)
	v_mfma_f32_16x16x32_bf16 v[118:121], v[188:191], v[156:159], v[118:121]
	v_mfma_f32_16x16x32_bf16 v[110:113], v[208:211], v[156:159], v[110:113]
	v_mfma_f32_16x16x32_bf16 v[102:105], v[188:191], v[164:167], v[102:105]
	v_mfma_f32_16x16x32_bf16 v[94:97], v[208:211], v[164:167], v[94:97]
	v_mfma_f32_16x16x32_bf16 v[86:89], v[188:191], v[172:175], v[86:89]
	v_mfma_f32_16x16x32_bf16 v[78:81], v[208:211], v[172:175], v[78:81]
	v_mfma_f32_16x16x32_bf16 v[70:73], v[188:191], v[180:183], v[70:73]
	v_mfma_f32_16x16x32_bf16 v[66:69], v[208:211], v[180:183], v[66:69]
	v_mfma_f32_16x16x32_bf16 v[118:121], v[198:201], v[160:163], v[118:121]
	v_mfma_f32_16x16x32_bf16 v[110:113], v[212:215], v[160:163], v[110:113]
	v_mfma_f32_16x16x32_bf16 v[102:105], v[198:201], v[168:171], v[102:105]
	v_mfma_f32_16x16x32_bf16 v[94:97], v[212:215], v[168:171], v[94:97]
	v_mfma_f32_16x16x32_bf16 v[86:89], v[198:201], v[176:179], v[86:89]
	v_mfma_f32_16x16x32_bf16 v[78:81], v[212:215], v[176:179], v[78:81]
	v_mfma_f32_16x16x32_bf16 v[70:73], v[198:201], v[184:187], v[70:73]
	v_mfma_f32_16x16x32_bf16 v[66:69], v[212:215], v[184:187], v[66:69]
	s_setprio 0
	s_mov_b32 m0, s39
	v_lshl_add_u64 v[192:193], v[216:217], 0, s[66:67]
	s_barrier
	ds_read_b128 v[156:159], v206 offset:49152
	ds_read_b128 v[160:163], v206 offset:50176
	ds_read_b128 v[164:167], v206 offset:51200
	ds_read_b128 v[168:171], v206 offset:52224
	ds_read_b128 v[172:175], v206 offset:53248
	ds_read_b128 v[176:179], v206 offset:54272
	ds_read_b128 v[180:183], v206 offset:55296
	ds_read_b128 v[184:187], v206 offset:56320
	global_load_lds_dwordx4 v[192:193], off
	v_lshl_add_u64 v[192:193], v[218:219], 0, s[66:67]
	s_mov_b32 m0, s40
	s_nop 0
	global_load_lds_dwordx4 v[192:193], off
	s_barrier
	s_waitcnt lgkmcnt(0)
	s_setprio 1
	s_waitcnt lgkmcnt(0)
	v_mfma_f32_16x16x32_bf16 v[62:65], v[130:133], v[156:159], v[62:65]
	v_mfma_f32_16x16x32_bf16 v[58:61], v[138:141], v[156:159], v[58:61]
	v_mfma_f32_16x16x32_bf16 v[50:53], v[130:133], v[164:167], v[50:53]
	v_mfma_f32_16x16x32_bf16 v[40:43], v[138:141], v[164:167], v[40:43]
	v_mfma_f32_16x16x32_bf16 v[32:35], v[130:133], v[172:175], v[32:35]
	v_mfma_f32_16x16x32_bf16 v[24:27], v[138:141], v[172:175], v[24:27]
	v_mfma_f32_16x16x32_bf16 v[16:19], v[130:133], v[180:183], v[16:19]
	v_mfma_f32_16x16x32_bf16 v[8:11], v[138:141], v[180:183], v[8:11]
	v_mfma_f32_16x16x32_bf16 v[62:65], v[134:137], v[160:163], v[62:65]
	v_mfma_f32_16x16x32_bf16 v[58:61], v[142:145], v[160:163], v[58:61]
	v_mfma_f32_16x16x32_bf16 v[50:53], v[134:137], v[168:171], v[50:53]
	v_mfma_f32_16x16x32_bf16 v[40:43], v[142:145], v[168:171], v[40:43]
	v_mfma_f32_16x16x32_bf16 v[32:35], v[134:137], v[176:179], v[32:35]
	v_mfma_f32_16x16x32_bf16 v[24:27], v[142:145], v[176:179], v[24:27]
	v_mfma_f32_16x16x32_bf16 v[16:19], v[134:137], v[184:187], v[16:19]
	v_mfma_f32_16x16x32_bf16 v[8:11], v[142:145], v[184:187], v[8:11]
	s_setprio 0
	s_barrier
	s_add_u32 s16, s20, 0xb0080
	s_addc_u32 s17, s21, 0
	s_add_i32 s20, s22, s25
	s_mov_b32 m0, s20
	s_nop 0
	global_load_lds_dwordx4 v48, s[16:17]
	s_add_i32 m0, s20, 0x2000
	s_nop 0
	global_load_lds_dwordx4 v146, s[16:17]
	s_waitcnt vmcnt(6)
	s_barrier
	s_setprio 1
	v_mfma_f32_16x16x32_bf16 v[54:57], v[188:191], v[156:159], v[54:57]
	v_mfma_f32_16x16x32_bf16 v[44:47], v[208:211], v[156:159], v[44:47]
	v_mfma_f32_16x16x32_bf16 v[36:39], v[188:191], v[164:167], v[36:39]
	v_mfma_f32_16x16x32_bf16 v[28:31], v[208:211], v[164:167], v[28:31]
	v_mfma_f32_16x16x32_bf16 v[20:23], v[188:191], v[172:175], v[20:23]
	v_mfma_f32_16x16x32_bf16 v[12:15], v[208:211], v[172:175], v[12:15]
	v_mfma_f32_16x16x32_bf16 v[4:7], v[188:191], v[180:183], v[4:7]
	v_mfma_f32_16x16x32_bf16 v[0:3], v[208:211], v[180:183], v[0:3]
	v_mfma_f32_16x16x32_bf16 v[54:57], v[198:201], v[160:163], v[54:57]
	v_mfma_f32_16x16x32_bf16 v[44:47], v[212:215], v[160:163], v[44:47]
	v_mfma_f32_16x16x32_bf16 v[36:39], v[198:201], v[168:171], v[36:39]
	v_mfma_f32_16x16x32_bf16 v[28:31], v[212:215], v[168:171], v[28:31]
	v_mfma_f32_16x16x32_bf16 v[20:23], v[198:201], v[176:179], v[20:23]
	v_mfma_f32_16x16x32_bf16 v[12:15], v[212:215], v[176:179], v[12:15]
	v_mfma_f32_16x16x32_bf16 v[4:7], v[198:201], v[184:187], v[4:7]
	v_mfma_f32_16x16x32_bf16 v[0:3], v[212:215], v[184:187], v[0:3]
	s_setprio 0
	s_add_i32 s46, s46, 2
	s_add_u32 s44, s44, 0x100
	s_addc_u32 s45, s45, 0
	s_cmp_gt_u32 s46, 41
	s_mov_b64 s[16:17], s[18:19]
	s_barrier
	s_cbranch_scc0 .LBB0_1421
	s_mul_hi_i32 s16, s14, 0x38e38e39
	s_lshr_b32 s17, s16, 31
	s_ashr_i32 s16, s16, 1
	s_add_i32 s16, s16, s17
	s_mul_i32 s17, s16, -9
	v_lshl_or_b32 v156, s15, 8, v205
	s_ashr_i32 s15, s14, 31
	s_add_i32 s18, s17, s14
	s_lshl_b64 s[14:15], s[14:15], 19
	s_ashr_i32 s17, s16, 31
	v_lshl_add_u64 v[158:159], v[150:151], 0, s[14:15]
	v_sub_co_u32_e64 v130, s[14:15], s18, 1
	s_lshl_b64 s[18:19], s[16:17], 23
	s_and_b64 s[14:15], s[14:15], exec
	v_ashrrev_i32_e32 v131, 31, v130
	s_cselect_b32 s14, 32, s16
	v_lshlrev_b64 v[130:131], 20, v[130:131]
	s_mul_hi_i32 s15, s14, 0x6000
	s_mulk_i32 s14, 0x6000
	v_ashrrev_i32_e32 v157, 31, v156
	v_lshl_add_u64 v[130:131], s[6:7], 0, v[130:131]
	s_add_u32 s14, s37, s14
	v_lshl_add_u64 v[130:131], v[130:131], 0, s[18:19]
	s_addc_u32 s15, s38, s15
	v_lshlrev_b64 v[208:209], 2, v[156:157]
	v_lshl_add_u64 v[162:163], v[130:131], 0, v[148:149]
	v_lshl_add_u64 v[130:131], s[14:15], 0, v[208:209]
	v_lshl_add_u64 v[156:157], v[156:157], 1, v[158:159]
	global_load_dwordx4 v[142:145], v[130:131], off
	global_load_dwordx4 v[138:141], v[130:131], off offset:64
	global_load_dwordx4 v[134:137], v[130:131], off offset:512
	s_nop 0
	global_load_dwordx4 v[130:133], v[130:131], off offset:576
	s_nop 0
	s_mov_b32 s14, 0x40000
	s_nop 0
	v_lshl_add_u64 v[162:163], v[162:163], 0, v[208:209]
	s_nop 0
	s_mov_b32 s15, s42
	s_nop 0
	s_mov_b32 s14, 0x48000
	s_nop 0
	s_mov_b32 s14, 0x50000
	s_nop 0
	s_mov_b32 s14, 0x58000
	s_nop 0
	s_mov_b32 s14, 0x20000
	s_nop 0
	s_nop 0
	s_mov_b64 s[18:19], s[12:13]
	s_mov_b64 s[16:17], s[10:11]
	v_and_b32_e32 v202, 16, v224
	v_lshrrev_b32_e32 v203, 1, v202
	v_add_u32_e32 v202, v202, v203
	v_mov_b32_e32 v203, 0
	v_mov_b32_e32 v223, 0
	v_lshl_add_u64 v[246:247], v[156:157], 0, v[202:203]
	v_mov_b32_e32 v222, 0x0
	v_lshl_add_u64 v[190:191], v[246:247], 0, v[222:223]
	global_load_dwordx4 v[198:201], v[190:191], off
	global_load_dwordx4 v[218:221], v[190:191], off offset:256
	v_mov_b32_e32 v222, 0x8000
	v_lshl_add_u64 v[190:191], v[246:247], 0, v[222:223]
	global_load_dwordx4 v[242:245], v[190:191], off
	global_load_dwordx4 v[164:167], v[190:191], off offset:256
	v_mov_b32_e32 v222, 0x10000
	v_lshl_add_u64 v[190:191], v[246:247], 0, v[222:223]
	global_load_dwordx4 v[168:171], v[190:191], off
	global_load_dwordx4 v[172:175], v[190:191], off offset:256
	v_mov_b32_e32 v222, 0x18000
	v_lshl_add_u64 v[190:191], v[246:247], 0, v[222:223]
	global_load_dwordx4 v[176:179], v[190:191], off
	global_load_dwordx4 v[180:183], v[190:191], off offset:256
	v_mov_b32_e32 v222, 0x40000
	v_lshl_add_u64 v[190:191], v[246:247], 0, v[222:223]
	global_load_dwordx4 v[184:187], v[190:191], off
	s_waitcnt vmcnt(8)
	v_permlane16_swap_b32 v198, v200
	v_permlane16_swap_b32 v199, v201
	s_nop 1
	v_lshlrev_b32_e32 v210, 16, v198
	v_and_b32_e32 v211, 0xffff0000, v198
	v_lshlrev_b32_e32 v212, 16, v199
	v_and_b32_e32 v213, 0xffff0000, v199
	v_pk_fma_f32 v[126:127], v[126:127], v[142:143], v[210:211]
	v_pk_fma_f32 v[128:129], v[128:129], v[144:145], v[212:213]
	v_lshlrev_b32_e32 v214, 16, v200
	v_and_b32_e32 v215, 0xffff0000, v200
	v_lshlrev_b32_e32 v216, 16, v201
	v_and_b32_e32 v217, 0xffff0000, v201
	v_pk_fma_f32 v[122:123], v[122:123], v[138:139], v[214:215]
	v_pk_fma_f32 v[124:125], v[124:125], v[140:141], v[216:217]
	v_mov_b32_e32 v222, 0x0
	v_lshl_add_u64 v[192:193], v[162:163], 0, v[222:223]
	global_store_dwordx4 v[192:193], v[126:129], off
	global_store_dwordx4 v[192:193], v[122:125], off offset:64
	global_load_dwordx4 v[198:201], v[190:191], off offset:256
	s_waitcnt vmcnt(10)
	v_permlane16_swap_b32 v218, v220
	v_permlane16_swap_b32 v219, v221
	s_nop 1
	v_lshlrev_b32_e32 v210, 16, v218
	v_and_b32_e32 v211, 0xffff0000, v218
	v_lshlrev_b32_e32 v212, 16, v219
	v_and_b32_e32 v213, 0xffff0000, v219
	v_pk_fma_f32 v[118:119], v[118:119], v[134:135], v[210:211]
	v_pk_fma_f32 v[120:121], v[120:121], v[136:137], v[212:213]
	v_lshlrev_b32_e32 v214, 16, v220
	v_and_b32_e32 v215, 0xffff0000, v220
	v_lshlrev_b32_e32 v216, 16, v221
	v_and_b32_e32 v217, 0xffff0000, v221
	v_pk_fma_f32 v[110:111], v[110:111], v[130:131], v[214:215]
	v_pk_fma_f32 v[112:113], v[112:113], v[132:133], v[216:217]
	v_mov_b32_e32 v222, 0x0
	v_lshl_add_u64 v[192:193], v[162:163], 0, v[222:223]
	global_store_dwordx4 v[192:193], v[118:121], off offset:512
	global_store_dwordx4 v[192:193], v[110:113], off offset:576
	v_mov_b32_e32 v222, 0x48000
	v_lshl_add_u64 v[190:191], v[246:247], 0, v[222:223]
	global_load_dwordx4 v[218:221], v[190:191], off
	s_waitcnt vmcnt(12)
	v_permlane16_swap_b32 v242, v244
	v_permlane16_swap_b32 v243, v245
	s_nop 1
	v_lshlrev_b32_e32 v210, 16, v242
	v_and_b32_e32 v211, 0xffff0000, v242
	v_lshlrev_b32_e32 v212, 16, v243
	v_and_b32_e32 v213, 0xffff0000, v243
	v_pk_fma_f32 v[114:115], v[114:115], v[142:143], v[210:211]
	v_pk_fma_f32 v[116:117], v[116:117], v[144:145], v[212:213]
	v_lshlrev_b32_e32 v214, 16, v244
	v_and_b32_e32 v215, 0xffff0000, v244
	v_lshlrev_b32_e32 v216, 16, v245
	v_and_b32_e32 v217, 0xffff0000, v245
	v_pk_fma_f32 v[106:107], v[106:107], v[138:139], v[214:215]
	v_pk_fma_f32 v[108:109], v[108:109], v[140:141], v[216:217]
	v_mov_b32_e32 v222, 0x10000
	v_lshl_add_u64 v[192:193], v[162:163], 0, v[222:223]
	global_store_dwordx4 v[192:193], v[114:117], off
	global_store_dwordx4 v[192:193], v[106:109], off offset:64
	global_load_dwordx4 v[242:245], v[190:191], off offset:256
	s_waitcnt vmcnt(14)
	v_permlane16_swap_b32 v164, v166
	v_permlane16_swap_b32 v165, v167
	s_nop 1
	v_lshlrev_b32_e32 v210, 16, v164
	v_and_b32_e32 v211, 0xffff0000, v164
	v_lshlrev_b32_e32 v212, 16, v165
	v_and_b32_e32 v213, 0xffff0000, v165
	v_pk_fma_f32 v[102:103], v[102:103], v[134:135], v[210:211]
	v_pk_fma_f32 v[104:105], v[104:105], v[136:137], v[212:213]
	v_lshlrev_b32_e32 v214, 16, v166
	v_and_b32_e32 v215, 0xffff0000, v166
	v_lshlrev_b32_e32 v216, 16, v167
	v_and_b32_e32 v217, 0xffff0000, v167
	v_pk_fma_f32 v[94:95], v[94:95], v[130:131], v[214:215]
	v_pk_fma_f32 v[96:97], v[96:97], v[132:133], v[216:217]
	v_mov_b32_e32 v222, 0x10000
	v_lshl_add_u64 v[192:193], v[162:163], 0, v[222:223]
	global_store_dwordx4 v[192:193], v[102:105], off offset:512
	global_store_dwordx4 v[192:193], v[94:97], off offset:576
	v_mov_b32_e32 v222, 0x50000
	v_lshl_add_u64 v[190:191], v[246:247], 0, v[222:223]
	global_load_dwordx4 v[164:167], v[190:191], off
	s_waitcnt vmcnt(16)
	v_permlane16_swap_b32 v168, v170
	v_permlane16_swap_b32 v169, v171
	s_nop 1
	v_lshlrev_b32_e32 v210, 16, v168
	v_and_b32_e32 v211, 0xffff0000, v168
	v_lshlrev_b32_e32 v212, 16, v169
	v_and_b32_e32 v213, 0xffff0000, v169
	v_pk_fma_f32 v[98:99], v[98:99], v[142:143], v[210:211]
	v_pk_fma_f32 v[100:101], v[100:101], v[144:145], v[212:213]
	v_lshlrev_b32_e32 v214, 16, v170
	v_and_b32_e32 v215, 0xffff0000, v170
	v_lshlrev_b32_e32 v216, 16, v171
	v_and_b32_e32 v217, 0xffff0000, v171
	v_pk_fma_f32 v[90:91], v[90:91], v[138:139], v[214:215]
	v_pk_fma_f32 v[92:93], v[92:93], v[140:141], v[216:217]
	v_mov_b32_e32 v222, 0x20000
	v_lshl_add_u64 v[192:193], v[162:163], 0, v[222:223]
	global_store_dwordx4 v[192:193], v[98:101], off
	global_store_dwordx4 v[192:193], v[90:93], off offset:64
	global_load_dwordx4 v[168:171], v[190:191], off offset:256
	s_waitcnt vmcnt(18)
	v_permlane16_swap_b32 v172, v174
	v_permlane16_swap_b32 v173, v175
	s_nop 1
	v_lshlrev_b32_e32 v210, 16, v172
	v_and_b32_e32 v211, 0xffff0000, v172
	v_lshlrev_b32_e32 v212, 16, v173
	v_and_b32_e32 v213, 0xffff0000, v173
	v_pk_fma_f32 v[86:87], v[86:87], v[134:135], v[210:211]
	v_pk_fma_f32 v[88:89], v[88:89], v[136:137], v[212:213]
	v_lshlrev_b32_e32 v214, 16, v174
	v_and_b32_e32 v215, 0xffff0000, v174
	v_lshlrev_b32_e32 v216, 16, v175
	v_and_b32_e32 v217, 0xffff0000, v175
	v_pk_fma_f32 v[78:79], v[78:79], v[130:131], v[214:215]
	v_pk_fma_f32 v[80:81], v[80:81], v[132:133], v[216:217]
	v_mov_b32_e32 v222, 0x20000
	v_lshl_add_u64 v[192:193], v[162:163], 0, v[222:223]
	global_store_dwordx4 v[192:193], v[86:89], off offset:512
	global_store_dwordx4 v[192:193], v[78:81], off offset:576
	v_mov_b32_e32 v222, 0x58000
	v_lshl_add_u64 v[190:191], v[246:247], 0, v[222:223]
	global_load_dwordx4 v[172:175], v[190:191], off
	s_waitcnt vmcnt(20)
	v_permlane16_swap_b32 v176, v178
	v_permlane16_swap_b32 v177, v179
	s_nop 1
	v_lshlrev_b32_e32 v210, 16, v176
	v_and_b32_e32 v211, 0xffff0000, v176
	v_lshlrev_b32_e32 v212, 16, v177
	v_and_b32_e32 v213, 0xffff0000, v177
	v_pk_fma_f32 v[82:83], v[82:83], v[142:143], v[210:211]
	v_pk_fma_f32 v[84:85], v[84:85], v[144:145], v[212:213]
	v_lshlrev_b32_e32 v214, 16, v178
	v_and_b32_e32 v215, 0xffff0000, v178
	v_lshlrev_b32_e32 v216, 16, v179
	v_and_b32_e32 v217, 0xffff0000, v179
	v_pk_fma_f32 v[74:75], v[74:75], v[138:139], v[214:215]
	v_pk_fma_f32 v[76:77], v[76:77], v[140:141], v[216:217]
	v_mov_b32_e32 v222, 0x30000
	v_lshl_add_u64 v[192:193], v[162:163], 0, v[222:223]
	global_store_dwordx4 v[192:193], v[82:85], off
	global_store_dwordx4 v[192:193], v[74:77], off offset:64
	global_load_dwordx4 v[176:179], v[190:191], off offset:256
	s_waitcnt vmcnt(22)
	v_permlane16_swap_b32 v180, v182
	v_permlane16_swap_b32 v181, v183
	s_nop 1
	v_lshlrev_b32_e32 v210, 16, v180
	v_and_b32_e32 v211, 0xffff0000, v180
	v_lshlrev_b32_e32 v212, 16, v181
	v_and_b32_e32 v213, 0xffff0000, v181
	v_pk_fma_f32 v[70:71], v[70:71], v[134:135], v[210:211]
	v_pk_fma_f32 v[72:73], v[72:73], v[136:137], v[212:213]
	v_lshlrev_b32_e32 v214, 16, v182
	v_and_b32_e32 v215, 0xffff0000, v182
	v_lshlrev_b32_e32 v216, 16, v183
	v_and_b32_e32 v217, 0xffff0000, v183
	v_pk_fma_f32 v[66:67], v[66:67], v[130:131], v[214:215]
	v_pk_fma_f32 v[68:69], v[68:69], v[132:133], v[216:217]
	v_mov_b32_e32 v222, 0x30000
	v_lshl_add_u64 v[192:193], v[162:163], 0, v[222:223]
	global_store_dwordx4 v[192:193], v[70:73], off offset:512
	global_store_dwordx4 v[192:193], v[66:69], off offset:576
	s_waitcnt vmcnt(23)
	v_permlane16_swap_b32 v184, v186
	v_permlane16_swap_b32 v185, v187
	s_nop 1
	v_lshlrev_b32_e32 v210, 16, v184
	v_and_b32_e32 v211, 0xffff0000, v184
	v_lshlrev_b32_e32 v212, 16, v185
	v_and_b32_e32 v213, 0xffff0000, v185
	v_pk_fma_f32 v[62:63], v[62:63], v[142:143], v[210:211]
	v_pk_fma_f32 v[64:65], v[64:65], v[144:145], v[212:213]
	v_lshlrev_b32_e32 v214, 16, v186
	v_and_b32_e32 v215, 0xffff0000, v186
	v_lshlrev_b32_e32 v216, 16, v187
	v_and_b32_e32 v217, 0xffff0000, v187
	v_pk_fma_f32 v[58:59], v[58:59], v[138:139], v[214:215]
	v_pk_fma_f32 v[60:61], v[60:61], v[140:141], v[216:217]
	v_mov_b32_e32 v222, 0x80000
	v_lshl_add_u64 v[192:193], v[162:163], 0, v[222:223]
	global_store_dwordx4 v[192:193], v[62:65], off
	global_store_dwordx4 v[192:193], v[58:61], off offset:64
	s_waitcnt vmcnt(22)
	v_permlane16_swap_b32 v198, v200
	v_permlane16_swap_b32 v199, v201
	s_nop 1
	v_lshlrev_b32_e32 v210, 16, v198
	v_and_b32_e32 v211, 0xffff0000, v198
	v_lshlrev_b32_e32 v212, 16, v199
	v_and_b32_e32 v213, 0xffff0000, v199
	v_pk_fma_f32 v[54:55], v[54:55], v[134:135], v[210:211]
	v_pk_fma_f32 v[56:57], v[56:57], v[136:137], v[212:213]
	v_lshlrev_b32_e32 v214, 16, v200
	v_and_b32_e32 v215, 0xffff0000, v200
	v_lshlrev_b32_e32 v216, 16, v201
	v_and_b32_e32 v217, 0xffff0000, v201
	v_pk_fma_f32 v[44:45], v[44:45], v[130:131], v[214:215]
	v_pk_fma_f32 v[46:47], v[46:47], v[132:133], v[216:217]
	v_mov_b32_e32 v222, 0x80000
	v_lshl_add_u64 v[192:193], v[162:163], 0, v[222:223]
	global_store_dwordx4 v[192:193], v[54:57], off offset:512
	global_store_dwordx4 v[192:193], v[44:47], off offset:576
	s_waitcnt vmcnt(21)
	v_permlane16_swap_b32 v218, v220
	v_permlane16_swap_b32 v219, v221
	s_nop 1
	v_lshlrev_b32_e32 v210, 16, v218
	v_and_b32_e32 v211, 0xffff0000, v218
	v_lshlrev_b32_e32 v212, 16, v219
	v_and_b32_e32 v213, 0xffff0000, v219
	v_pk_fma_f32 v[50:51], v[50:51], v[142:143], v[210:211]
	v_pk_fma_f32 v[52:53], v[52:53], v[144:145], v[212:213]
	v_lshlrev_b32_e32 v214, 16, v220
	v_and_b32_e32 v215, 0xffff0000, v220
	v_lshlrev_b32_e32 v216, 16, v221
	v_and_b32_e32 v217, 0xffff0000, v221
	v_pk_fma_f32 v[40:41], v[40:41], v[138:139], v[214:215]
	v_pk_fma_f32 v[42:43], v[42:43], v[140:141], v[216:217]
	v_mov_b32_e32 v222, 0x90000
	v_lshl_add_u64 v[192:193], v[162:163], 0, v[222:223]
	global_store_dwordx4 v[192:193], v[50:53], off
	global_store_dwordx4 v[192:193], v[40:43], off offset:64
	s_waitcnt vmcnt(20)
	v_permlane16_swap_b32 v242, v244
	v_permlane16_swap_b32 v243, v245
	s_nop 1
	v_lshlrev_b32_e32 v210, 16, v242
	v_and_b32_e32 v211, 0xffff0000, v242
	v_lshlrev_b32_e32 v212, 16, v243
	v_and_b32_e32 v213, 0xffff0000, v243
	v_pk_fma_f32 v[36:37], v[36:37], v[134:135], v[210:211]
	v_pk_fma_f32 v[38:39], v[38:39], v[136:137], v[212:213]
	v_lshlrev_b32_e32 v214, 16, v244
	v_and_b32_e32 v215, 0xffff0000, v244
	v_lshlrev_b32_e32 v216, 16, v245
	v_and_b32_e32 v217, 0xffff0000, v245
	v_pk_fma_f32 v[28:29], v[28:29], v[130:131], v[214:215]
	v_pk_fma_f32 v[30:31], v[30:31], v[132:133], v[216:217]
	v_mov_b32_e32 v222, 0x90000
	v_lshl_add_u64 v[192:193], v[162:163], 0, v[222:223]
	global_store_dwordx4 v[192:193], v[36:39], off offset:512
	global_store_dwordx4 v[192:193], v[28:31], off offset:576
	s_waitcnt vmcnt(19)
	v_permlane16_swap_b32 v164, v166
	v_permlane16_swap_b32 v165, v167
	s_nop 1
	v_lshlrev_b32_e32 v210, 16, v164
	v_and_b32_e32 v211, 0xffff0000, v164
	v_lshlrev_b32_e32 v212, 16, v165
	v_and_b32_e32 v213, 0xffff0000, v165
	v_pk_fma_f32 v[32:33], v[32:33], v[142:143], v[210:211]
	v_pk_fma_f32 v[34:35], v[34:35], v[144:145], v[212:213]
	v_lshlrev_b32_e32 v214, 16, v166
	v_and_b32_e32 v215, 0xffff0000, v166
	v_lshlrev_b32_e32 v216, 16, v167
	v_and_b32_e32 v217, 0xffff0000, v167
	v_pk_fma_f32 v[24:25], v[24:25], v[138:139], v[214:215]
	v_pk_fma_f32 v[26:27], v[26:27], v[140:141], v[216:217]
	v_mov_b32_e32 v222, 0xa0000
	v_lshl_add_u64 v[192:193], v[162:163], 0, v[222:223]
	global_store_dwordx4 v[192:193], v[32:35], off
	global_store_dwordx4 v[192:193], v[24:27], off offset:64
	s_waitcnt vmcnt(18)
	v_permlane16_swap_b32 v168, v170
	v_permlane16_swap_b32 v169, v171
	s_nop 1
	v_lshlrev_b32_e32 v210, 16, v168
	v_and_b32_e32 v211, 0xffff0000, v168
	v_lshlrev_b32_e32 v212, 16, v169
	v_and_b32_e32 v213, 0xffff0000, v169
	v_pk_fma_f32 v[20:21], v[20:21], v[134:135], v[210:211]
	v_pk_fma_f32 v[22:23], v[22:23], v[136:137], v[212:213]
	v_lshlrev_b32_e32 v214, 16, v170
	v_and_b32_e32 v215, 0xffff0000, v170
	v_lshlrev_b32_e32 v216, 16, v171
	v_and_b32_e32 v217, 0xffff0000, v171
	v_pk_fma_f32 v[12:13], v[12:13], v[130:131], v[214:215]
	v_pk_fma_f32 v[14:15], v[14:15], v[132:133], v[216:217]
	v_mov_b32_e32 v222, 0xa0000
	v_lshl_add_u64 v[192:193], v[162:163], 0, v[222:223]
	global_store_dwordx4 v[192:193], v[20:23], off offset:512
	global_store_dwordx4 v[192:193], v[12:15], off offset:576
	s_waitcnt vmcnt(17)
	v_permlane16_swap_b32 v172, v174
	v_permlane16_swap_b32 v173, v175
	s_nop 1
	v_lshlrev_b32_e32 v210, 16, v172
	v_and_b32_e32 v211, 0xffff0000, v172
	v_lshlrev_b32_e32 v212, 16, v173
	v_and_b32_e32 v213, 0xffff0000, v173
	v_pk_fma_f32 v[16:17], v[16:17], v[142:143], v[210:211]
	v_pk_fma_f32 v[18:19], v[18:19], v[144:145], v[212:213]
	v_lshlrev_b32_e32 v214, 16, v174
	v_and_b32_e32 v215, 0xffff0000, v174
	v_lshlrev_b32_e32 v216, 16, v175
	v_and_b32_e32 v217, 0xffff0000, v175
	v_pk_fma_f32 v[8:9], v[8:9], v[138:139], v[214:215]
	v_pk_fma_f32 v[10:11], v[10:11], v[140:141], v[216:217]
	v_mov_b32_e32 v222, 0xb0000
	v_lshl_add_u64 v[192:193], v[162:163], 0, v[222:223]
	global_store_dwordx4 v[192:193], v[16:19], off
	global_store_dwordx4 v[192:193], v[8:11], off offset:64
	s_waitcnt vmcnt(16)
	v_permlane16_swap_b32 v176, v178
	v_permlane16_swap_b32 v177, v179
	s_nop 1
	v_lshlrev_b32_e32 v210, 16, v176
	v_and_b32_e32 v211, 0xffff0000, v176
	v_lshlrev_b32_e32 v212, 16, v177
	v_and_b32_e32 v213, 0xffff0000, v177
	v_pk_fma_f32 v[4:5], v[4:5], v[134:135], v[210:211]
	v_pk_fma_f32 v[6:7], v[6:7], v[136:137], v[212:213]
	v_lshlrev_b32_e32 v214, 16, v178
	v_and_b32_e32 v215, 0xffff0000, v178
	v_lshlrev_b32_e32 v216, 16, v179
	v_and_b32_e32 v217, 0xffff0000, v179
	v_pk_fma_f32 v[0:1], v[0:1], v[130:131], v[214:215]
	v_pk_fma_f32 v[2:3], v[2:3], v[132:133], v[216:217]
	v_mov_b32_e32 v222, 0xb0000
	v_lshl_add_u64 v[192:193], v[162:163], 0, v[222:223]
	global_store_dwordx4 v[192:193], v[4:7], off offset:512
	global_store_dwordx4 v[192:193], v[0:3], off offset:576
	s_mov_b32 s14, 0x30000
	s_mov_b32 s14, 0x80000
	s_mov_b32 s14, 0x90000
	s_mov_b32 s14, 0xa0000
	s_mov_b32 s14, 0xb0000
	s_and_b64 vcc, exec, s[0:1]
	s_mov_b32 s14, s43
	s_cbranch_vccz .LBB0_1418
	s_waitcnt vmcnt(0)
	s_cmpk_gt_u32 s24, 0xff
	s_cbranch_scc1 .LBB0_1425
	s_barrier

.LBB0_1435:
	s_add_u32 s20, s18, 0x100
	s_addc_u32 s21, s19, 0
	s_add_i32 s47, 0, 0x10000
	v_add_u32_e32 v142, s47, v242
	ds_read_b128 v[130:133], v142
	ds_read_b128 v[134:137], v142 offset:1024
	ds_read_b128 v[138:141], v142 offset:2048
	ds_read_b128 v[142:145], v142 offset:3072
	s_cmp_eq_u32 s46, 40
	s_cselect_b32 s25, s13, s21
	s_cselect_b32 s24, s12, s20
	s_cselect_b32 s23, s15, s45
	s_cselect_b32 s22, s14, s44
	v_lshl_add_u64 v[186:187], s[18:19], 0, v[150:151]
	s_add_i32 m0, s31, 0xc000
	ds_read_b128 v[154:157], v244
	ds_read_b128 v[158:161], v244 offset:1024
	ds_read_b128 v[162:165], v244 offset:2048
	ds_read_b128 v[166:169], v244 offset:3072
	ds_read_b128 v[170:173], v244 offset:4096
	ds_read_b128 v[174:177], v244 offset:5120
	ds_read_b128 v[178:181], v244 offset:6144
	ds_read_b128 v[182:185], v244 offset:7168
	global_load_lds_dwordx4 v[186:187], off
	v_lshl_add_u64 v[186:187], s[18:19], 0, v[152:153]
	s_add_i32 m0, s31, 0xe000
	s_nop 0
	global_load_lds_dwordx4 v[186:187], off
	s_waitcnt lgkmcnt(8)
	s_barrier
	s_waitcnt lgkmcnt(0)
	s_setprio 1
	s_waitcnt lgkmcnt(0)
	v_mfma_f32_16x16x32_bf16 v[126:129], v[130:133], v[154:157], v[126:129]
	v_mfma_f32_16x16x32_bf16 v[122:125], v[138:141], v[154:157], v[122:125]
	v_mfma_f32_16x16x32_bf16 v[114:117], v[130:133], v[162:165], v[114:117]
	v_mfma_f32_16x16x32_bf16 v[106:109], v[138:141], v[162:165], v[106:109]
	v_mfma_f32_16x16x32_bf16 v[98:101], v[130:133], v[170:173], v[98:101]
	v_mfma_f32_16x16x32_bf16 v[90:93], v[138:141], v[170:173], v[90:93]
	v_mfma_f32_16x16x32_bf16 v[82:85], v[130:133], v[178:181], v[82:85]
	v_mfma_f32_16x16x32_bf16 v[74:77], v[138:141], v[178:181], v[74:77]
	v_mfma_f32_16x16x32_bf16 v[126:129], v[134:137], v[158:161], v[126:129]
	v_mfma_f32_16x16x32_bf16 v[122:125], v[142:145], v[158:161], v[122:125]
	v_mfma_f32_16x16x32_bf16 v[114:117], v[134:137], v[166:169], v[114:117]
	v_mfma_f32_16x16x32_bf16 v[106:109], v[142:145], v[166:169], v[106:109]
	v_mfma_f32_16x16x32_bf16 v[98:101], v[134:137], v[174:177], v[98:101]
	v_mfma_f32_16x16x32_bf16 v[90:93], v[142:145], v[174:177], v[90:93]
	v_mfma_f32_16x16x32_bf16 v[82:85], v[134:137], v[182:185], v[82:85]
	v_mfma_f32_16x16x32_bf16 v[74:77], v[142:145], v[182:185], v[74:77]
	s_setprio 0
	s_barrier
	s_add_i32 s48, 0, 0x14000
	s_add_i32 s18, s47, s30
	v_add_u32_e32 v202, s48, v242
	v_lshl_add_u64 v[206:207], s[22:23], 0, v[48:49]
	s_mov_b32 m0, s18
	ds_read_b128 v[186:189], v202
	ds_read_b128 v[190:193], v202 offset:1024
	ds_read_b128 v[198:201], v202 offset:2048
	ds_read_b128 v[202:205], v202 offset:3072
	global_load_lds_dwordx4 v[206:207], off
	v_lshl_add_u64 v[208:209], s[22:23], 0, v[146:147]
	s_add_i32 m0, s18, 0x2000
	s_nop 0
	global_load_lds_dwordx4 v[208:209], off
	s_barrier
	s_waitcnt lgkmcnt(0)
	s_setprio 1
	s_waitcnt lgkmcnt(0)
	v_mfma_f32_16x16x32_bf16 v[118:121], v[186:189], v[154:157], v[118:121]
	v_mfma_f32_16x16x32_bf16 v[110:113], v[198:201], v[154:157], v[110:113]
	v_mfma_f32_16x16x32_bf16 v[102:105], v[186:189], v[162:165], v[102:105]
	v_mfma_f32_16x16x32_bf16 v[94:97], v[198:201], v[162:165], v[94:97]
	v_mfma_f32_16x16x32_bf16 v[86:89], v[186:189], v[170:173], v[86:89]
	v_mfma_f32_16x16x32_bf16 v[78:81], v[198:201], v[170:173], v[78:81]
	v_mfma_f32_16x16x32_bf16 v[70:73], v[186:189], v[178:181], v[70:73]
	v_mfma_f32_16x16x32_bf16 v[66:69], v[198:201], v[178:181], v[66:69]
	v_mfma_f32_16x16x32_bf16 v[118:121], v[190:193], v[158:161], v[118:121]
	v_mfma_f32_16x16x32_bf16 v[110:113], v[202:205], v[158:161], v[110:113]
	v_mfma_f32_16x16x32_bf16 v[102:105], v[190:193], v[166:169], v[102:105]
	v_mfma_f32_16x16x32_bf16 v[94:97], v[202:205], v[166:169], v[94:97]
	v_mfma_f32_16x16x32_bf16 v[86:89], v[190:193], v[174:177], v[86:89]
	v_mfma_f32_16x16x32_bf16 v[78:81], v[202:205], v[174:177], v[78:81]
	v_mfma_f32_16x16x32_bf16 v[70:73], v[190:193], v[182:185], v[70:73]
	v_mfma_f32_16x16x32_bf16 v[66:69], v[202:205], v[182:185], v[66:69]
	s_setprio 0
	s_mov_b32 m0, s31
	v_lshl_add_u64 v[210:211], s[24:25], 0, v[48:49]
	s_barrier
	ds_read_b128 v[154:157], v244 offset:16384
	ds_read_b128 v[158:161], v244 offset:17408
	ds_read_b128 v[162:165], v244 offset:18432
	ds_read_b128 v[166:169], v244 offset:19456
	ds_read_b128 v[170:173], v244 offset:20480
	ds_read_b128 v[174:177], v244 offset:21504
	ds_read_b128 v[178:181], v244 offset:22528
	ds_read_b128 v[182:185], v244 offset:23552
	global_load_lds_dwordx4 v[210:211], off
	v_lshl_add_u64 v[212:213], s[24:25], 0, v[146:147]
	s_mov_b32 m0, s34
	s_nop 0
	global_load_lds_dwordx4 v[212:213], off
	s_barrier
	s_waitcnt lgkmcnt(0)
	s_setprio 1
	s_waitcnt lgkmcnt(0)
	v_mfma_f32_16x16x32_bf16 v[62:65], v[130:133], v[154:157], v[62:65]
	v_mfma_f32_16x16x32_bf16 v[58:61], v[138:141], v[154:157], v[58:61]
	v_mfma_f32_16x16x32_bf16 v[50:53], v[130:133], v[162:165], v[50:53]
	v_mfma_f32_16x16x32_bf16 v[40:43], v[138:141], v[162:165], v[40:43]
	v_mfma_f32_16x16x32_bf16 v[32:35], v[130:133], v[170:173], v[32:35]
	v_mfma_f32_16x16x32_bf16 v[24:27], v[138:141], v[170:173], v[24:27]
	v_mfma_f32_16x16x32_bf16 v[16:19], v[130:133], v[178:181], v[16:19]
	v_mfma_f32_16x16x32_bf16 v[8:11], v[138:141], v[178:181], v[8:11]
	v_mfma_f32_16x16x32_bf16 v[62:65], v[134:137], v[158:161], v[62:65]
	v_mfma_f32_16x16x32_bf16 v[58:61], v[142:145], v[158:161], v[58:61]
	v_mfma_f32_16x16x32_bf16 v[50:53], v[134:137], v[166:169], v[50:53]
	v_mfma_f32_16x16x32_bf16 v[40:43], v[142:145], v[166:169], v[40:43]
	v_mfma_f32_16x16x32_bf16 v[32:35], v[134:137], v[174:177], v[32:35]
	v_mfma_f32_16x16x32_bf16 v[24:27], v[142:145], v[174:177], v[24:27]
	v_mfma_f32_16x16x32_bf16 v[16:19], v[134:137], v[182:185], v[16:19]
	v_mfma_f32_16x16x32_bf16 v[8:11], v[142:145], v[182:185], v[8:11]
	s_setprio 0
	s_barrier
	s_add_u32 s18, s22, 0xb0000
	s_addc_u32 s19, s23, 0
	s_add_i32 s47, s48, s30
	s_mov_b32 m0, s47
	s_nop 0
	global_load_lds_dwordx4 v48, s[18:19]
	s_add_i32 m0, s47, 0x2000
	s_nop 0
	global_load_lds_dwordx4 v146, s[18:19]
	s_waitcnt vmcnt(6)
	s_barrier
	s_setprio 1
	v_mfma_f32_16x16x32_bf16 v[54:57], v[186:189], v[154:157], v[54:57]
	v_mfma_f32_16x16x32_bf16 v[44:47], v[198:201], v[154:157], v[44:47]
	v_mfma_f32_16x16x32_bf16 v[36:39], v[186:189], v[162:165], v[36:39]
	v_mfma_f32_16x16x32_bf16 v[28:31], v[198:201], v[162:165], v[28:31]
	v_mfma_f32_16x16x32_bf16 v[20:23], v[186:189], v[170:173], v[20:23]
	v_mfma_f32_16x16x32_bf16 v[12:15], v[198:201], v[170:173], v[12:15]
	v_mfma_f32_16x16x32_bf16 v[4:7], v[186:189], v[178:181], v[4:7]
	v_mfma_f32_16x16x32_bf16 v[0:3], v[198:201], v[178:181], v[0:3]
	v_mfma_f32_16x16x32_bf16 v[54:57], v[190:193], v[158:161], v[54:57]
	v_mfma_f32_16x16x32_bf16 v[44:47], v[202:205], v[158:161], v[44:47]
	v_mfma_f32_16x16x32_bf16 v[36:39], v[190:193], v[166:169], v[36:39]
	v_mfma_f32_16x16x32_bf16 v[28:31], v[202:205], v[166:169], v[28:31]
	v_mfma_f32_16x16x32_bf16 v[20:23], v[190:193], v[174:177], v[20:23]
	v_mfma_f32_16x16x32_bf16 v[12:15], v[202:205], v[174:177], v[12:15]
	v_mfma_f32_16x16x32_bf16 v[4:7], v[190:193], v[182:185], v[4:7]
	v_mfma_f32_16x16x32_bf16 v[0:3], v[202:205], v[182:185], v[0:3]
	s_setprio 0
	s_add_i32 s47, 0, 0x18000
	v_add_u32_e32 v142, s47, v242
	s_barrier
	ds_read_b128 v[130:133], v142
	ds_read_b128 v[134:137], v142 offset:1024
	ds_read_b128 v[138:141], v142 offset:2048
	ds_read_b128 v[142:145], v142 offset:3072
	s_add_u32 s18, s24, 0xb0000
	s_addc_u32 s19, s25, 0
	s_mov_b32 m0, s35
	ds_read_b128 v[154:157], v244 offset:32768
	ds_read_b128 v[158:161], v244 offset:33792
	ds_read_b128 v[162:165], v244 offset:34816
	ds_read_b128 v[166:169], v244 offset:35840
	ds_read_b128 v[170:173], v244 offset:36864
	ds_read_b128 v[174:177], v244 offset:37888
	ds_read_b128 v[178:181], v244 offset:38912
	ds_read_b128 v[182:185], v244 offset:39936
	global_load_lds_dwordx4 v48, s[18:19]
	s_mov_b32 m0, s36
	s_nop 0
	global_load_lds_dwordx4 v146, s[18:19]
	s_waitcnt lgkmcnt(8)
	s_barrier
	s_waitcnt lgkmcnt(0)
	s_setprio 1
	s_waitcnt lgkmcnt(0)
	v_mfma_f32_16x16x32_bf16 v[126:129], v[130:133], v[154:157], v[126:129]
	v_mfma_f32_16x16x32_bf16 v[122:125], v[138:141], v[154:157], v[122:125]
	v_mfma_f32_16x16x32_bf16 v[114:117], v[130:133], v[162:165], v[114:117]
	v_mfma_f32_16x16x32_bf16 v[106:109], v[138:141], v[162:165], v[106:109]
	v_mfma_f32_16x16x32_bf16 v[98:101], v[130:133], v[170:173], v[98:101]
	v_mfma_f32_16x16x32_bf16 v[90:93], v[138:141], v[170:173], v[90:93]
	v_mfma_f32_16x16x32_bf16 v[82:85], v[130:133], v[178:181], v[82:85]
	v_mfma_f32_16x16x32_bf16 v[74:77], v[138:141], v[178:181], v[74:77]
	v_mfma_f32_16x16x32_bf16 v[126:129], v[134:137], v[158:161], v[126:129]
	v_mfma_f32_16x16x32_bf16 v[122:125], v[142:145], v[158:161], v[122:125]
	v_mfma_f32_16x16x32_bf16 v[114:117], v[134:137], v[166:169], v[114:117]
	v_mfma_f32_16x16x32_bf16 v[106:109], v[142:145], v[166:169], v[106:109]
	v_mfma_f32_16x16x32_bf16 v[98:101], v[134:137], v[174:177], v[98:101]
	v_mfma_f32_16x16x32_bf16 v[90:93], v[142:145], v[174:177], v[90:93]
	v_mfma_f32_16x16x32_bf16 v[82:85], v[134:137], v[182:185], v[82:85]
	v_mfma_f32_16x16x32_bf16 v[74:77], v[142:145], v[182:185], v[74:77]
	s_setprio 0
	s_barrier
	s_add_i32 s24, 0, 0x1c000
	s_add_i32 s18, s47, s30
	v_add_u32_e32 v202, s24, v242
	v_lshl_add_u64 v[206:207], v[206:207], 0, s[66:67]
	s_mov_b32 m0, s18
	ds_read_b128 v[186:189], v202
	ds_read_b128 v[190:193], v202 offset:1024
	ds_read_b128 v[198:201], v202 offset:2048
	ds_read_b128 v[202:205], v202 offset:3072
	global_load_lds_dwordx4 v[206:207], off
	v_lshl_add_u64 v[206:207], v[208:209], 0, s[66:67]
	s_add_i32 m0, s18, 0x2000
	s_nop 0
	global_load_lds_dwordx4 v[206:207], off
	s_barrier
	s_waitcnt lgkmcnt(0)
	s_setprio 1
	s_waitcnt lgkmcnt(0)
	v_mfma_f32_16x16x32_bf16 v[118:121], v[186:189], v[154:157], v[118:121]
	v_mfma_f32_16x16x32_bf16 v[110:113], v[198:201], v[154:157], v[110:113]
	v_mfma_f32_16x16x32_bf16 v[102:105], v[186:189], v[162:165], v[102:105]
	v_mfma_f32_16x16x32_bf16 v[94:97], v[198:201], v[162:165], v[94:97]
	v_mfma_f32_16x16x32_bf16 v[86:89], v[186:189], v[170:173], v[86:89]
	v_mfma_f32_16x16x32_bf16 v[78:81], v[198:201], v[170:173], v[78:81]
	v_mfma_f32_16x16x32_bf16 v[70:73], v[186:189], v[178:181], v[70:73]
	v_mfma_f32_16x16x32_bf16 v[66:69], v[198:201], v[178:181], v[66:69]
	v_mfma_f32_16x16x32_bf16 v[118:121], v[190:193], v[158:161], v[118:121]
	v_mfma_f32_16x16x32_bf16 v[110:113], v[202:205], v[158:161], v[110:113]
	v_mfma_f32_16x16x32_bf16 v[102:105], v[190:193], v[166:169], v[102:105]
	v_mfma_f32_16x16x32_bf16 v[94:97], v[202:205], v[166:169], v[94:97]
	v_mfma_f32_16x16x32_bf16 v[86:89], v[190:193], v[174:177], v[86:89]
	v_mfma_f32_16x16x32_bf16 v[78:81], v[202:205], v[174:177], v[78:81]
	v_mfma_f32_16x16x32_bf16 v[70:73], v[190:193], v[182:185], v[70:73]
	v_mfma_f32_16x16x32_bf16 v[66:69], v[202:205], v[182:185], v[66:69]
	s_setprio 0
	s_mov_b32 m0, s39
	v_lshl_add_u64 v[206:207], v[210:211], 0, s[66:67]
	s_barrier
	ds_read_b128 v[154:157], v244 offset:49152
	ds_read_b128 v[158:161], v244 offset:50176
	ds_read_b128 v[162:165], v244 offset:51200
	ds_read_b128 v[166:169], v244 offset:52224
	ds_read_b128 v[170:173], v244 offset:53248
	ds_read_b128 v[174:177], v244 offset:54272
	ds_read_b128 v[178:181], v244 offset:55296
	ds_read_b128 v[182:185], v244 offset:56320
	global_load_lds_dwordx4 v[206:207], off
	v_lshl_add_u64 v[206:207], v[212:213], 0, s[66:67]
	s_mov_b32 m0, s40
	s_nop 0
	global_load_lds_dwordx4 v[206:207], off
	s_barrier
	s_waitcnt lgkmcnt(0)
	s_setprio 1
	s_waitcnt lgkmcnt(0)
	v_mfma_f32_16x16x32_bf16 v[62:65], v[130:133], v[154:157], v[62:65]
	v_mfma_f32_16x16x32_bf16 v[58:61], v[138:141], v[154:157], v[58:61]
	v_mfma_f32_16x16x32_bf16 v[50:53], v[130:133], v[162:165], v[50:53]
	v_mfma_f32_16x16x32_bf16 v[40:43], v[138:141], v[162:165], v[40:43]
	v_mfma_f32_16x16x32_bf16 v[32:35], v[130:133], v[170:173], v[32:35]
	v_mfma_f32_16x16x32_bf16 v[24:27], v[138:141], v[170:173], v[24:27]
	v_mfma_f32_16x16x32_bf16 v[16:19], v[130:133], v[178:181], v[16:19]
	v_mfma_f32_16x16x32_bf16 v[8:11], v[138:141], v[178:181], v[8:11]
	v_mfma_f32_16x16x32_bf16 v[62:65], v[134:137], v[158:161], v[62:65]
	v_mfma_f32_16x16x32_bf16 v[58:61], v[142:145], v[158:161], v[58:61]
	v_mfma_f32_16x16x32_bf16 v[50:53], v[134:137], v[166:169], v[50:53]
	v_mfma_f32_16x16x32_bf16 v[40:43], v[142:145], v[166:169], v[40:43]
	v_mfma_f32_16x16x32_bf16 v[32:35], v[134:137], v[174:177], v[32:35]
	v_mfma_f32_16x16x32_bf16 v[24:27], v[142:145], v[174:177], v[24:27]
	v_mfma_f32_16x16x32_bf16 v[16:19], v[134:137], v[182:185], v[16:19]
	v_mfma_f32_16x16x32_bf16 v[8:11], v[142:145], v[182:185], v[8:11]
	s_setprio 0
	s_barrier
	s_add_u32 s18, s22, 0xb0080
	s_addc_u32 s19, s23, 0
	s_add_i32 s22, s24, s30
	s_mov_b32 m0, s22
	s_nop 0
	global_load_lds_dwordx4 v48, s[18:19]
	s_add_i32 m0, s22, 0x2000
	s_nop 0
	global_load_lds_dwordx4 v146, s[18:19]
	s_waitcnt vmcnt(6)
	s_barrier
	s_setprio 1
	v_mfma_f32_16x16x32_bf16 v[54:57], v[186:189], v[154:157], v[54:57]
	v_mfma_f32_16x16x32_bf16 v[44:47], v[198:201], v[154:157], v[44:47]
	v_mfma_f32_16x16x32_bf16 v[36:39], v[186:189], v[162:165], v[36:39]
	v_mfma_f32_16x16x32_bf16 v[28:31], v[198:201], v[162:165], v[28:31]
	v_mfma_f32_16x16x32_bf16 v[20:23], v[186:189], v[170:173], v[20:23]
	v_mfma_f32_16x16x32_bf16 v[12:15], v[198:201], v[170:173], v[12:15]
	v_mfma_f32_16x16x32_bf16 v[4:7], v[186:189], v[178:181], v[4:7]
	v_mfma_f32_16x16x32_bf16 v[0:3], v[198:201], v[178:181], v[0:3]
	v_mfma_f32_16x16x32_bf16 v[54:57], v[190:193], v[158:161], v[54:57]
	v_mfma_f32_16x16x32_bf16 v[44:47], v[202:205], v[158:161], v[44:47]
	v_mfma_f32_16x16x32_bf16 v[36:39], v[190:193], v[166:169], v[36:39]
	v_mfma_f32_16x16x32_bf16 v[28:31], v[202:205], v[166:169], v[28:31]
	v_mfma_f32_16x16x32_bf16 v[20:23], v[190:193], v[174:177], v[20:23]
	v_mfma_f32_16x16x32_bf16 v[12:15], v[202:205], v[174:177], v[12:15]
	v_mfma_f32_16x16x32_bf16 v[4:7], v[190:193], v[182:185], v[4:7]
	v_mfma_f32_16x16x32_bf16 v[0:3], v[202:205], v[182:185], v[0:3]
	s_setprio 0
	s_add_i32 s46, s46, 2
	s_add_u32 s44, s44, 0x100
	s_addc_u32 s45, s45, 0
	s_cmp_gt_u32 s46, 41
	s_mov_b64 s[18:19], s[20:21]
	s_barrier
	s_cbranch_scc0 .LBB0_1435
	s_mul_hi_i32 s18, s16, 0x38e38e39
	s_lshr_b32 s19, s18, 31
	s_ashr_i32 s18, s18, 1
	s_add_i32 s18, s18, s19
	s_mul_i32 s19, s18, -9
	v_lshl_or_b32 v154, s17, 8, v243
	s_sub_i32 s17, 0, s16
	s_cmp_lg_u32 s19, s17
	s_cselect_b32 s17, s18, 32
	s_mul_hi_i32 s19, s17, 0x6000
	s_mulk_i32 s17, 0x6000
	s_add_u32 s18, s37, s17
	s_addc_u32 s19, s38, s19
	s_ashr_i32 s17, s16, 31
	s_lshl_b64 s[16:17], s[16:17], 18
	v_ashrrev_i32_e32 v155, 31, v154
	v_lshl_add_u64 v[156:157], s[16:17], 0, v[148:149]
	v_lshl_add_u64 v[130:131], v[154:155], 2, s[18:19]
	v_lshl_add_u64 v[154:155], v[156:157], 0, v[154:155]
	v_lshlrev_b64 v[184:185], 1, v[154:155]
	v_lshl_add_u64 v[154:155], s[10:11], 0, v[184:185]
	global_load_dwordx4 v[142:145], v[130:131], off
	global_load_dwordx4 v[138:141], v[130:131], off offset:64
	global_load_dwordx4 v[134:137], v[130:131], off offset:512
	s_nop 0
	global_load_dwordx4 v[130:133], v[130:131], off offset:576
	s_nop 0
	s_mov_b32 s16, 0x40000
	s_nop 0
	s_mov_b32 s17, 0x48000
	s_nop 0
	s_mov_b32 s18, 0x50000
	s_nop 0
	s_mov_b32 s19, 0x58000
	s_nop 0
	v_lshl_add_u64 v[184:185], s[6:7], 0, v[184:185]
	s_nop 0
	s_mov_b64 s[20:21], s[14:15]
	s_nop 0
	v_and_b32_e32 v210, 16, v224
	v_lshrrev_b32_e32 v211, 1, v210
	v_add_u32_e32 v210, v210, v211
	v_mov_b32_e32 v211, 0
	v_mov_b32_e32 v213, 0
	v_lshl_add_u64 v[214:215], v[154:155], 0, v[210:211]
	v_lshl_add_u64 v[216:217], v[184:185], 0, v[210:211]
	v_mov_b32_e32 v212, 0x0
	v_lshl_add_u64 v[218:219], v[214:215], 0, v[212:213]
	global_load_dwordx4 v[164:167], v[218:219], off
	global_load_dwordx4 v[168:171], v[218:219], off offset:256
	v_mov_b32_e32 v212, 0x8000
	v_lshl_add_u64 v[218:219], v[214:215], 0, v[212:213]
	global_load_dwordx4 v[172:175], v[218:219], off
	global_load_dwordx4 v[176:179], v[218:219], off offset:256
	v_mov_b32_e32 v212, 0x10000
	v_lshl_add_u64 v[218:219], v[214:215], 0, v[212:213]
	global_load_dwordx4 v[180:183], v[218:219], off
	global_load_dwordx4 v[198:201], v[218:219], off offset:256
	v_mov_b32_e32 v212, 0x18000
	v_lshl_add_u64 v[218:219], v[214:215], 0, v[212:213]
	global_load_dwordx4 v[202:205], v[218:219], off
	global_load_dwordx4 v[206:209], v[218:219], off offset:256
	s_waitcnt vmcnt(7)
	v_permlane16_swap_b32 v164, v166
	v_permlane16_swap_b32 v165, v167
	s_nop 1
	v_lshlrev_b32_e32 v186, 16, v164
	v_and_b32_e32 v187, 0xffff0000, v164
	v_lshlrev_b32_e32 v188, 16, v165
	v_and_b32_e32 v189, 0xffff0000, v165
	v_pk_fma_f32 v[126:127], v[126:127], v[142:143], v[186:187]
	v_pk_fma_f32 v[128:129], v[128:129], v[144:145], v[188:189]
	v_lshlrev_b32_e32 v190, 16, v166
	v_and_b32_e32 v191, 0xffff0000, v166
	v_lshlrev_b32_e32 v192, 16, v167
	v_and_b32_e32 v193, 0xffff0000, v167
	v_pk_fma_f32 v[122:123], v[122:123], v[138:139], v[190:191]
	v_pk_fma_f32 v[124:125], v[124:125], v[140:141], v[192:193]
	v_cvt_pk_bf16_f32 v126, v126, v127
	v_cvt_pk_bf16_f32 v127, v128, v129
	v_cvt_pk_bf16_f32 v128, v122, v123
	v_cvt_pk_bf16_f32 v129, v124, v125
	s_nop 1
	v_permlane16_swap_b32 v126, v128
	v_permlane16_swap_b32 v127, v129
	v_mov_b32_e32 v212, 0x0
	v_lshl_add_u64 v[220:221], v[216:217], 0, v[212:213]
	global_store_dwordx4 v[220:221], v[126:129], off
	v_mov_b32_e32 v212, 0x40000
	v_lshl_add_u64 v[218:219], v[214:215], 0, v[212:213]
	global_load_dwordx4 v[164:167], v[218:219], off
	s_waitcnt vmcnt(8)
	v_permlane16_swap_b32 v168, v170
	v_permlane16_swap_b32 v169, v171
	s_nop 1
	v_lshlrev_b32_e32 v186, 16, v168
	v_and_b32_e32 v187, 0xffff0000, v168
	v_lshlrev_b32_e32 v188, 16, v169
	v_and_b32_e32 v189, 0xffff0000, v169
	v_pk_fma_f32 v[118:119], v[118:119], v[134:135], v[186:187]
	v_pk_fma_f32 v[120:121], v[120:121], v[136:137], v[188:189]
	v_lshlrev_b32_e32 v190, 16, v170
	v_and_b32_e32 v191, 0xffff0000, v170
	v_lshlrev_b32_e32 v192, 16, v171
	v_and_b32_e32 v193, 0xffff0000, v171
	v_pk_fma_f32 v[110:111], v[110:111], v[130:131], v[190:191]
	v_pk_fma_f32 v[112:113], v[112:113], v[132:133], v[192:193]
	v_cvt_pk_bf16_f32 v118, v118, v119
	v_cvt_pk_bf16_f32 v119, v120, v121
	v_cvt_pk_bf16_f32 v120, v110, v111
	v_cvt_pk_bf16_f32 v121, v112, v113
	s_nop 1
	v_permlane16_swap_b32 v118, v120
	v_permlane16_swap_b32 v119, v121
	v_mov_b32_e32 v212, 0x0
	v_lshl_add_u64 v[220:221], v[216:217], 0, v[212:213]
	global_store_dwordx4 v[220:221], v[118:121], off offset:256
	global_load_dwordx4 v[168:171], v[218:219], off offset:256
	s_waitcnt vmcnt(9)
	v_permlane16_swap_b32 v172, v174
	v_permlane16_swap_b32 v173, v175
	s_nop 1
	v_lshlrev_b32_e32 v186, 16, v172
	v_and_b32_e32 v187, 0xffff0000, v172
	v_lshlrev_b32_e32 v188, 16, v173
	v_and_b32_e32 v189, 0xffff0000, v173
	v_pk_fma_f32 v[114:115], v[114:115], v[142:143], v[186:187]
	v_pk_fma_f32 v[116:117], v[116:117], v[144:145], v[188:189]
	v_lshlrev_b32_e32 v190, 16, v174
	v_and_b32_e32 v191, 0xffff0000, v174
	v_lshlrev_b32_e32 v192, 16, v175
	v_and_b32_e32 v193, 0xffff0000, v175
	v_pk_fma_f32 v[106:107], v[106:107], v[138:139], v[190:191]
	v_pk_fma_f32 v[108:109], v[108:109], v[140:141], v[192:193]
	v_cvt_pk_bf16_f32 v114, v114, v115
	v_cvt_pk_bf16_f32 v115, v116, v117
	v_cvt_pk_bf16_f32 v116, v106, v107
	v_cvt_pk_bf16_f32 v117, v108, v109
	s_nop 1
	v_permlane16_swap_b32 v114, v116
	v_permlane16_swap_b32 v115, v117
	v_mov_b32_e32 v212, 0x8000
	v_lshl_add_u64 v[220:221], v[216:217], 0, v[212:213]
	global_store_dwordx4 v[220:221], v[114:117], off
	v_mov_b32_e32 v212, 0x48000
	v_lshl_add_u64 v[218:219], v[214:215], 0, v[212:213]
	global_load_dwordx4 v[172:175], v[218:219], off
	s_waitcnt vmcnt(10)
	v_permlane16_swap_b32 v176, v178
	v_permlane16_swap_b32 v177, v179
	s_nop 1
	v_lshlrev_b32_e32 v186, 16, v176
	v_and_b32_e32 v187, 0xffff0000, v176
	v_lshlrev_b32_e32 v188, 16, v177
	v_and_b32_e32 v189, 0xffff0000, v177
	v_pk_fma_f32 v[102:103], v[102:103], v[134:135], v[186:187]
	v_pk_fma_f32 v[104:105], v[104:105], v[136:137], v[188:189]
	v_lshlrev_b32_e32 v190, 16, v178
	v_and_b32_e32 v191, 0xffff0000, v178
	v_lshlrev_b32_e32 v192, 16, v179
	v_and_b32_e32 v193, 0xffff0000, v179
	v_pk_fma_f32 v[94:95], v[94:95], v[130:131], v[190:191]
	v_pk_fma_f32 v[96:97], v[96:97], v[132:133], v[192:193]
	v_cvt_pk_bf16_f32 v102, v102, v103
	v_cvt_pk_bf16_f32 v103, v104, v105
	v_cvt_pk_bf16_f32 v104, v94, v95
	v_cvt_pk_bf16_f32 v105, v96, v97
	s_nop 1
	v_permlane16_swap_b32 v102, v104
	v_permlane16_swap_b32 v103, v105
	v_mov_b32_e32 v212, 0x8000
	v_lshl_add_u64 v[220:221], v[216:217], 0, v[212:213]
	global_store_dwordx4 v[220:221], v[102:105], off offset:256
	global_load_dwordx4 v[176:179], v[218:219], off offset:256
	s_waitcnt vmcnt(11)
	v_permlane16_swap_b32 v180, v182
	v_permlane16_swap_b32 v181, v183
	s_nop 1
	v_lshlrev_b32_e32 v186, 16, v180
	v_and_b32_e32 v187, 0xffff0000, v180
	v_lshlrev_b32_e32 v188, 16, v181
	v_and_b32_e32 v189, 0xffff0000, v181
	v_pk_fma_f32 v[98:99], v[98:99], v[142:143], v[186:187]
	v_pk_fma_f32 v[100:101], v[100:101], v[144:145], v[188:189]
	v_lshlrev_b32_e32 v190, 16, v182
	v_and_b32_e32 v191, 0xffff0000, v182
	v_lshlrev_b32_e32 v192, 16, v183
	v_and_b32_e32 v193, 0xffff0000, v183
	v_pk_fma_f32 v[90:91], v[90:91], v[138:139], v[190:191]
	v_pk_fma_f32 v[92:93], v[92:93], v[140:141], v[192:193]
	v_cvt_pk_bf16_f32 v98, v98, v99
	v_cvt_pk_bf16_f32 v99, v100, v101
	v_cvt_pk_bf16_f32 v100, v90, v91
	v_cvt_pk_bf16_f32 v101, v92, v93
	s_nop 1
	v_permlane16_swap_b32 v98, v100
	v_permlane16_swap_b32 v99, v101
	v_mov_b32_e32 v212, 0x10000
	v_lshl_add_u64 v[220:221], v[216:217], 0, v[212:213]
	global_store_dwordx4 v[220:221], v[98:101], off
	v_mov_b32_e32 v212, 0x50000
	v_lshl_add_u64 v[218:219], v[214:215], 0, v[212:213]
	global_load_dwordx4 v[180:183], v[218:219], off
	s_waitcnt vmcnt(12)
	v_permlane16_swap_b32 v198, v200
	v_permlane16_swap_b32 v199, v201
	s_nop 1
	v_lshlrev_b32_e32 v186, 16, v198
	v_and_b32_e32 v187, 0xffff0000, v198
	v_lshlrev_b32_e32 v188, 16, v199
	v_and_b32_e32 v189, 0xffff0000, v199
	v_pk_fma_f32 v[86:87], v[86:87], v[134:135], v[186:187]
	v_pk_fma_f32 v[88:89], v[88:89], v[136:137], v[188:189]
	v_lshlrev_b32_e32 v190, 16, v200
	v_and_b32_e32 v191, 0xffff0000, v200
	v_lshlrev_b32_e32 v192, 16, v201
	v_and_b32_e32 v193, 0xffff0000, v201
	v_pk_fma_f32 v[78:79], v[78:79], v[130:131], v[190:191]
	v_pk_fma_f32 v[80:81], v[80:81], v[132:133], v[192:193]
	v_cvt_pk_bf16_f32 v86, v86, v87
	v_cvt_pk_bf16_f32 v87, v88, v89
	v_cvt_pk_bf16_f32 v88, v78, v79
	v_cvt_pk_bf16_f32 v89, v80, v81
	s_nop 1
	v_permlane16_swap_b32 v86, v88
	v_permlane16_swap_b32 v87, v89
	v_mov_b32_e32 v212, 0x10000
	v_lshl_add_u64 v[220:221], v[216:217], 0, v[212:213]
	global_store_dwordx4 v[220:221], v[86:89], off offset:256
	global_load_dwordx4 v[198:201], v[218:219], off offset:256
	s_waitcnt vmcnt(13)
	v_permlane16_swap_b32 v202, v204
	v_permlane16_swap_b32 v203, v205
	s_nop 1
	v_lshlrev_b32_e32 v186, 16, v202
	v_and_b32_e32 v187, 0xffff0000, v202
	v_lshlrev_b32_e32 v188, 16, v203
	v_and_b32_e32 v189, 0xffff0000, v203
	v_pk_fma_f32 v[82:83], v[82:83], v[142:143], v[186:187]
	v_pk_fma_f32 v[84:85], v[84:85], v[144:145], v[188:189]
	v_lshlrev_b32_e32 v190, 16, v204
	v_and_b32_e32 v191, 0xffff0000, v204
	v_lshlrev_b32_e32 v192, 16, v205
	v_and_b32_e32 v193, 0xffff0000, v205
	v_pk_fma_f32 v[74:75], v[74:75], v[138:139], v[190:191]
	v_pk_fma_f32 v[76:77], v[76:77], v[140:141], v[192:193]
	v_cvt_pk_bf16_f32 v82, v82, v83
	v_cvt_pk_bf16_f32 v83, v84, v85
	v_cvt_pk_bf16_f32 v84, v74, v75
	v_cvt_pk_bf16_f32 v85, v76, v77
	s_nop 1
	v_permlane16_swap_b32 v82, v84
	v_permlane16_swap_b32 v83, v85
	v_mov_b32_e32 v212, 0x18000
	v_lshl_add_u64 v[220:221], v[216:217], 0, v[212:213]
	global_store_dwordx4 v[220:221], v[82:85], off
	v_mov_b32_e32 v212, 0x58000
	v_lshl_add_u64 v[218:219], v[214:215], 0, v[212:213]
	global_load_dwordx4 v[202:205], v[218:219], off
	s_waitcnt vmcnt(14)
	v_permlane16_swap_b32 v206, v208
	v_permlane16_swap_b32 v207, v209
	s_nop 1
	v_lshlrev_b32_e32 v186, 16, v206
	v_and_b32_e32 v187, 0xffff0000, v206
	v_lshlrev_b32_e32 v188, 16, v207
	v_and_b32_e32 v189, 0xffff0000, v207
	v_pk_fma_f32 v[70:71], v[70:71], v[134:135], v[186:187]
	v_pk_fma_f32 v[72:73], v[72:73], v[136:137], v[188:189]
	v_lshlrev_b32_e32 v190, 16, v208
	v_and_b32_e32 v191, 0xffff0000, v208
	v_lshlrev_b32_e32 v192, 16, v209
	v_and_b32_e32 v193, 0xffff0000, v209
	v_pk_fma_f32 v[66:67], v[66:67], v[130:131], v[190:191]
	v_pk_fma_f32 v[68:69], v[68:69], v[132:133], v[192:193]
	v_cvt_pk_bf16_f32 v70, v70, v71
	v_cvt_pk_bf16_f32 v71, v72, v73
	v_cvt_pk_bf16_f32 v72, v66, v67
	v_cvt_pk_bf16_f32 v73, v68, v69
	s_nop 1
	v_permlane16_swap_b32 v70, v72
	v_permlane16_swap_b32 v71, v73
	v_mov_b32_e32 v212, 0x18000
	v_lshl_add_u64 v[220:221], v[216:217], 0, v[212:213]
	global_store_dwordx4 v[220:221], v[70:73], off offset:256
	global_load_dwordx4 v[206:209], v[218:219], off offset:256
	s_waitcnt vmcnt(14)
	v_permlane16_swap_b32 v164, v166
	v_permlane16_swap_b32 v165, v167
	s_nop 1
	v_lshlrev_b32_e32 v186, 16, v164
	v_and_b32_e32 v187, 0xffff0000, v164
	v_lshlrev_b32_e32 v188, 16, v165
	v_and_b32_e32 v189, 0xffff0000, v165
	v_pk_fma_f32 v[62:63], v[62:63], v[142:143], v[186:187]
	v_pk_fma_f32 v[64:65], v[64:65], v[144:145], v[188:189]
	v_lshlrev_b32_e32 v190, 16, v166
	v_and_b32_e32 v191, 0xffff0000, v166
	v_lshlrev_b32_e32 v192, 16, v167
	v_and_b32_e32 v193, 0xffff0000, v167
	v_pk_fma_f32 v[58:59], v[58:59], v[138:139], v[190:191]
	v_pk_fma_f32 v[60:61], v[60:61], v[140:141], v[192:193]
	v_cvt_pk_bf16_f32 v62, v62, v63
	v_cvt_pk_bf16_f32 v63, v64, v65
	v_cvt_pk_bf16_f32 v64, v58, v59
	v_cvt_pk_bf16_f32 v65, v60, v61
	s_nop 1
	v_permlane16_swap_b32 v62, v64
	v_permlane16_swap_b32 v63, v65
	v_mov_b32_e32 v212, 0x40000
	v_lshl_add_u64 v[220:221], v[216:217], 0, v[212:213]
	global_store_dwordx4 v[220:221], v[62:65], off
	s_waitcnt vmcnt(13)
	v_permlane16_swap_b32 v168, v170
	v_permlane16_swap_b32 v169, v171
	s_nop 1
	v_lshlrev_b32_e32 v186, 16, v168
	v_and_b32_e32 v187, 0xffff0000, v168
	v_lshlrev_b32_e32 v188, 16, v169
	v_and_b32_e32 v189, 0xffff0000, v169
	v_pk_fma_f32 v[54:55], v[54:55], v[134:135], v[186:187]
	v_pk_fma_f32 v[56:57], v[56:57], v[136:137], v[188:189]
	v_lshlrev_b32_e32 v190, 16, v170
	v_and_b32_e32 v191, 0xffff0000, v170
	v_lshlrev_b32_e32 v192, 16, v171
	v_and_b32_e32 v193, 0xffff0000, v171
	v_pk_fma_f32 v[44:45], v[44:45], v[130:131], v[190:191]
	v_pk_fma_f32 v[46:47], v[46:47], v[132:133], v[192:193]
	v_cvt_pk_bf16_f32 v54, v54, v55
	v_cvt_pk_bf16_f32 v55, v56, v57
	v_cvt_pk_bf16_f32 v56, v44, v45
	v_cvt_pk_bf16_f32 v57, v46, v47
	s_nop 1
	v_permlane16_swap_b32 v54, v56
	v_permlane16_swap_b32 v55, v57
	v_mov_b32_e32 v212, 0x40000
	v_lshl_add_u64 v[220:221], v[216:217], 0, v[212:213]
	global_store_dwordx4 v[220:221], v[54:57], off offset:256
	s_waitcnt vmcnt(12)
	v_permlane16_swap_b32 v172, v174
	v_permlane16_swap_b32 v173, v175
	s_nop 1
	v_lshlrev_b32_e32 v186, 16, v172
	v_and_b32_e32 v187, 0xffff0000, v172
	v_lshlrev_b32_e32 v188, 16, v173
	v_and_b32_e32 v189, 0xffff0000, v173
	v_pk_fma_f32 v[50:51], v[50:51], v[142:143], v[186:187]
	v_pk_fma_f32 v[52:53], v[52:53], v[144:145], v[188:189]
	v_lshlrev_b32_e32 v190, 16, v174
	v_and_b32_e32 v191, 0xffff0000, v174
	v_lshlrev_b32_e32 v192, 16, v175
	v_and_b32_e32 v193, 0xffff0000, v175
	v_pk_fma_f32 v[40:41], v[40:41], v[138:139], v[190:191]
	v_pk_fma_f32 v[42:43], v[42:43], v[140:141], v[192:193]
	v_cvt_pk_bf16_f32 v50, v50, v51
	v_cvt_pk_bf16_f32 v51, v52, v53
	v_cvt_pk_bf16_f32 v52, v40, v41
	v_cvt_pk_bf16_f32 v53, v42, v43
	s_nop 1
	v_permlane16_swap_b32 v50, v52
	v_permlane16_swap_b32 v51, v53
	v_mov_b32_e32 v212, 0x48000
	v_lshl_add_u64 v[220:221], v[216:217], 0, v[212:213]
	global_store_dwordx4 v[220:221], v[50:53], off
	s_waitcnt vmcnt(11)
	v_permlane16_swap_b32 v176, v178
	v_permlane16_swap_b32 v177, v179
	s_nop 1
	v_lshlrev_b32_e32 v186, 16, v176
	v_and_b32_e32 v187, 0xffff0000, v176
	v_lshlrev_b32_e32 v188, 16, v177
	v_and_b32_e32 v189, 0xffff0000, v177
	v_pk_fma_f32 v[36:37], v[36:37], v[134:135], v[186:187]
	v_pk_fma_f32 v[38:39], v[38:39], v[136:137], v[188:189]
	v_lshlrev_b32_e32 v190, 16, v178
	v_and_b32_e32 v191, 0xffff0000, v178
	v_lshlrev_b32_e32 v192, 16, v179
	v_and_b32_e32 v193, 0xffff0000, v179
	v_pk_fma_f32 v[28:29], v[28:29], v[130:131], v[190:191]
	v_pk_fma_f32 v[30:31], v[30:31], v[132:133], v[192:193]
	v_cvt_pk_bf16_f32 v36, v36, v37
	v_cvt_pk_bf16_f32 v37, v38, v39
	v_cvt_pk_bf16_f32 v38, v28, v29
	v_cvt_pk_bf16_f32 v39, v30, v31
	s_nop 1
	v_permlane16_swap_b32 v36, v38
	v_permlane16_swap_b32 v37, v39
	v_mov_b32_e32 v212, 0x48000
	v_lshl_add_u64 v[220:221], v[216:217], 0, v[212:213]
	global_store_dwordx4 v[220:221], v[36:39], off offset:256
	s_waitcnt vmcnt(10)
	v_permlane16_swap_b32 v180, v182
	v_permlane16_swap_b32 v181, v183
	s_nop 1
	v_lshlrev_b32_e32 v186, 16, v180
	v_and_b32_e32 v187, 0xffff0000, v180
	v_lshlrev_b32_e32 v188, 16, v181
	v_and_b32_e32 v189, 0xffff0000, v181
	v_pk_fma_f32 v[32:33], v[32:33], v[142:143], v[186:187]
	v_pk_fma_f32 v[34:35], v[34:35], v[144:145], v[188:189]
	v_lshlrev_b32_e32 v190, 16, v182
	v_and_b32_e32 v191, 0xffff0000, v182
	v_lshlrev_b32_e32 v192, 16, v183
	v_and_b32_e32 v193, 0xffff0000, v183
	v_pk_fma_f32 v[24:25], v[24:25], v[138:139], v[190:191]
	v_pk_fma_f32 v[26:27], v[26:27], v[140:141], v[192:193]
	v_cvt_pk_bf16_f32 v32, v32, v33
	v_cvt_pk_bf16_f32 v33, v34, v35
	v_cvt_pk_bf16_f32 v34, v24, v25
	v_cvt_pk_bf16_f32 v35, v26, v27
	s_nop 1
	v_permlane16_swap_b32 v32, v34
	v_permlane16_swap_b32 v33, v35
	v_mov_b32_e32 v212, 0x50000
	v_lshl_add_u64 v[220:221], v[216:217], 0, v[212:213]
	global_store_dwordx4 v[220:221], v[32:35], off
	s_waitcnt vmcnt(9)
	v_permlane16_swap_b32 v198, v200
	v_permlane16_swap_b32 v199, v201
	s_nop 1
	v_lshlrev_b32_e32 v186, 16, v198
	v_and_b32_e32 v187, 0xffff0000, v198
	v_lshlrev_b32_e32 v188, 16, v199
	v_and_b32_e32 v189, 0xffff0000, v199
	v_pk_fma_f32 v[20:21], v[20:21], v[134:135], v[186:187]
	v_pk_fma_f32 v[22:23], v[22:23], v[136:137], v[188:189]
	v_lshlrev_b32_e32 v190, 16, v200
	v_and_b32_e32 v191, 0xffff0000, v200
	v_lshlrev_b32_e32 v192, 16, v201
	v_and_b32_e32 v193, 0xffff0000, v201
	v_pk_fma_f32 v[12:13], v[12:13], v[130:131], v[190:191]
	v_pk_fma_f32 v[14:15], v[14:15], v[132:133], v[192:193]
	v_cvt_pk_bf16_f32 v20, v20, v21
	v_cvt_pk_bf16_f32 v21, v22, v23
	v_cvt_pk_bf16_f32 v22, v12, v13
	v_cvt_pk_bf16_f32 v23, v14, v15
	s_nop 1
	v_permlane16_swap_b32 v20, v22
	v_permlane16_swap_b32 v21, v23
	v_mov_b32_e32 v212, 0x50000
	v_lshl_add_u64 v[220:221], v[216:217], 0, v[212:213]
	global_store_dwordx4 v[220:221], v[20:23], off offset:256
	s_waitcnt vmcnt(8)
	v_permlane16_swap_b32 v202, v204
	v_permlane16_swap_b32 v203, v205
	s_nop 1
	v_lshlrev_b32_e32 v186, 16, v202
	v_and_b32_e32 v187, 0xffff0000, v202
	v_lshlrev_b32_e32 v188, 16, v203
	v_and_b32_e32 v189, 0xffff0000, v203
	v_pk_fma_f32 v[16:17], v[16:17], v[142:143], v[186:187]
	v_pk_fma_f32 v[18:19], v[18:19], v[144:145], v[188:189]
	v_lshlrev_b32_e32 v190, 16, v204
	v_and_b32_e32 v191, 0xffff0000, v204
	v_lshlrev_b32_e32 v192, 16, v205
	v_and_b32_e32 v193, 0xffff0000, v205
	v_pk_fma_f32 v[8:9], v[8:9], v[138:139], v[190:191]
	v_pk_fma_f32 v[10:11], v[10:11], v[140:141], v[192:193]
	v_cvt_pk_bf16_f32 v16, v16, v17
	v_cvt_pk_bf16_f32 v17, v18, v19
	v_cvt_pk_bf16_f32 v18, v8, v9
	v_cvt_pk_bf16_f32 v19, v10, v11
	s_nop 1
	v_permlane16_swap_b32 v16, v18
	v_permlane16_swap_b32 v17, v19
	v_mov_b32_e32 v212, 0x58000
	v_lshl_add_u64 v[220:221], v[216:217], 0, v[212:213]
	global_store_dwordx4 v[220:221], v[16:19], off
	s_waitcnt vmcnt(7)
	v_permlane16_swap_b32 v206, v208
	v_permlane16_swap_b32 v207, v209
	s_nop 1
	v_lshlrev_b32_e32 v186, 16, v206
	v_and_b32_e32 v187, 0xffff0000, v206
	v_lshlrev_b32_e32 v188, 16, v207
	v_and_b32_e32 v189, 0xffff0000, v207
	v_pk_fma_f32 v[4:5], v[4:5], v[134:135], v[186:187]
	v_pk_fma_f32 v[6:7], v[6:7], v[136:137], v[188:189]
	v_lshlrev_b32_e32 v190, 16, v208
	v_and_b32_e32 v191, 0xffff0000, v208
	v_lshlrev_b32_e32 v192, 16, v209
	v_and_b32_e32 v193, 0xffff0000, v209
	v_pk_fma_f32 v[0:1], v[0:1], v[130:131], v[190:191]
	v_pk_fma_f32 v[2:3], v[2:3], v[132:133], v[192:193]
	v_cvt_pk_bf16_f32 v4, v4, v5
	v_cvt_pk_bf16_f32 v5, v6, v7
	v_cvt_pk_bf16_f32 v6, v0, v1
	v_cvt_pk_bf16_f32 v7, v2, v3
	s_nop 1
	v_permlane16_swap_b32 v4, v6
	v_permlane16_swap_b32 v5, v7
	v_mov_b32_e32 v212, 0x58000
	v_lshl_add_u64 v[220:221], v[216:217], 0, v[212:213]
	global_store_dwordx4 v[220:221], v[4:7], off offset:256
	s_mov_b32 s16, s43
	s_mov_b32 s17, s42
	s_and_b64 vcc, exec, s[0:1]
	s_mov_b64 s[18:19], s[12:13]
	s_cbranch_vccz .LBB0_1432
	s_waitcnt vmcnt(0)
	s_cmpk_gt_u32 s29, 0xff
	s_cbranch_scc1 .LBB0_1439
	s_barrier
